# hoist 8 ss row-scale loads to top of GEMM epilogues (P1,P6,P8,P12), drop per-block vmcnt(0)
# speedup vs baseline: 1.0150x; 1.0150x over previous
; __device__ __forceinline__ unsigned pk(float lo, float hi) { return pg8::cvt_pk_bf16(lo, hi); }
;     __device__ __forceinline__ void operator()(const pg8::f32x4 (&acc)[2][2][4][2], const pg8::Unit& u, int wr, int wc, int fr, int fq) const {
;         const int row0 = u.pm * 256 + wr * 64 + fr;
; #pragma unroll
;         for (int ai = 0; ai < 2; ++ai)
; #pragma unroll
;             for (int m = 0; m < 4; ++m) {
;                 const int row = row0 + ai * 128 + m * 16; const float rs = rsqrtf(ss[row] * (1.f / DM) + EPS);
;                 if (u.pn < 12) {
; #pragma unroll
;                     for (int bj = 0; bj < 2; ++bj) { const f32x4 v0 = acc[ai][bj][m][0] * rs, v1 = acc[ai][bj][m][1] * rs;
;                         u32x4 w; w.x = pk(v0[0], v0[1]); w.y = pk(v0[2], v0[3]); w.z = pk(v1[0], v1[1]); w.w = pk(v1[2], v1[3]);
;                         *(u32x4*)(proj + (size_t)row * NPJ + u.pn * 256 + bj * 128 + wc * 32 + 8 * fq) = w; }
;                 } else if (wc == 0 && fq < 2) {
; #pragma unroll
;                     for (int n = 0; n < 2; ++n) *(f32x4*)(gl + (size_t)row * 16 + 8 * fq + 4 * n) = acc[ai][0][m][n] * rs;
.LBB0_269:
	v_lshl_add_u32 v152, s4, 8, v141
	v_ashrrev_i32_e32 v153, 31, v152
	v_lshl_add_u64 v[154:155], v[152:153], 2, s[8:9]
	global_load_dword v172, v[154:155], off
	global_load_dword v173, v[154:155], off offset:64
	global_load_dword v174, v[154:155], off offset:128
	global_load_dword v175, v[154:155], off offset:192
	global_load_dword v176, v[154:155], off offset:512
	global_load_dword v177, v[154:155], off offset:576
	global_load_dword v178, v[154:155], off offset:640
	global_load_dword v179, v[154:155], off offset:704
	s_cmp_gt_i32 s42, 11
	s_cselect_b64 s[84:85], -1, 0
	s_and_b64 s[4:5], exec, s[84:85]
	s_mov_b64 s[6:7], -1
	s_waitcnt vmcnt(0)
	v_mov_b32_e32 v138, v172
	v_fmamk_f32 v138, v138, 0x3a800000, v161
	v_mul_f32_e32 v156, 0x4b800000, v138
	v_cmp_gt_f32_e32 vcc, s63, v138
	s_nop 1
	v_cndmask_b32_e32 v138, v138, v156, vcc
	v_rsq_f32_e32 v138, v138
	s_nop 0
	v_mul_f32_e32 v156, 0x45800000, v138
	v_cndmask_b32_e32 v156, v138, v156, vcc
	s_mov_b64 vcc, s[4:5]
	s_cbranch_vccz .LBB0_273
	s_and_saveexec_b64 s[4:5], s[74:75]
	s_cbranch_execz .LBB0_272
	v_lshlrev_b64 v[162:163], 6, v[152:153]
	v_lshl_add_u64 v[170:171], v[142:143], 0, v[162:163]
	v_pk_mul_f32 v[168:169], v[128:129], v[156:157] op_sel_hi:[1,0]
	v_pk_mul_f32 v[166:167], v[126:127], v[156:157] op_sel_hi:[1,0]
	v_pk_mul_f32 v[164:165], v[124:125], v[156:157] op_sel_hi:[1,0]
	v_pk_mul_f32 v[162:163], v[122:123], v[156:157] op_sel_hi:[1,0]
	global_store_dwordx4 v[170:171], v[166:169], off
	global_store_dwordx4 v[170:171], v[162:165], off offset:16

; __device__ __forceinline__ unsigned pk(float lo, float hi) { return pg8::cvt_pk_bf16(lo, hi); }
;     __device__ __forceinline__ void operator()(const pg8::f32x4 (&acc)[2][2][4][2], const pg8::Unit& u, int wr, int wc, int fr, int fq) const {
;     ...
;                 const int row = row0 + ai * 128 + m * 16; const float rs = rsqrtf(ss[row] * (1.f / DM) + EPS);
;                 if (u.pn < 12) {
; #pragma unroll
;                     for (int bj = 0; bj < 2; ++bj) { const f32x4 v0 = acc[ai][bj][m][0] * rs, v1 = acc[ai][bj][m][1] * rs;
;                         u32x4 w; w.x = pk(v0[0], v0[1]); w.y = pk(v0[2], v0[3]); w.z = pk(v1[0], v1[1]); w.w = pk(v1[2], v1[3]);
;                         *(u32x4*)(proj + (size_t)row * NPJ + u.pn * 256 + bj * 128 + wc * 32 + 8 * fq) = w; }
;                 } else if (wc == 0 && fq < 2) {
; #pragma unroll
;                     for (int n = 0; n < 2; ++n) *(f32x4*)(gl + (size_t)row * 16 + 8 * fq + 4 * n) = acc[ai][0][m][n] * rs;
.LBB0_275:
	s_nop 1
	v_or_b32_e32 v116, 16, v152
	v_ashrrev_i32_e32 v117, 31, v116
	v_lshl_add_u64 v[114:115], v[116:117], 2, s[8:9]
	s_nop 0
	s_andn2_b64 vcc, exec, s[84:85]
	v_mov_b32_e32 v114, v173
	v_fmamk_f32 v114, v114, 0x3a800000, v161
	v_mul_f32_e32 v115, 0x4b800000, v114
	v_cmp_gt_f32_e64 s[6:7], s63, v114
	s_nop 1
	v_cndmask_b32_e64 v114, v114, v115, s[6:7]
	v_rsq_f32_e32 v114, v114
	v_cndmask_b32_e64 v115, 0, 1, s[84:85]
	v_cmp_ne_u32_e64 s[4:5], 1, v115
	v_mul_f32_e32 v115, 0x45800000, v114
	v_cndmask_b32_e64 v114, v114, v115, s[6:7]
	s_mov_b64 s[6:7], -1
	s_cbranch_vccnz .LBB0_279
	s_and_saveexec_b64 s[6:7], s[74:75]
	s_cbranch_execz .LBB0_278
	v_lshlrev_b64 v[118:119], 6, v[116:117]
	v_lshl_add_u64 v[126:127], v[142:143], 0, v[118:119]
	v_pk_mul_f32 v[124:125], v[112:113], v[114:115] op_sel_hi:[1,0]
	v_pk_mul_f32 v[122:123], v[110:111], v[114:115] op_sel_hi:[1,0]
	v_pk_mul_f32 v[120:121], v[108:109], v[114:115] op_sel_hi:[1,0]
	v_pk_mul_f32 v[118:119], v[106:107], v[114:115] op_sel_hi:[1,0]
	global_store_dwordx4 v[126:127], v[122:125], off
	global_store_dwordx4 v[126:127], v[118:121], off offset:16

; __device__ __forceinline__ unsigned pk(float lo, float hi) { return pg8::cvt_pk_bf16(lo, hi); }
;     __device__ __forceinline__ void operator()(const pg8::f32x4 (&acc)[2][2][4][2], const pg8::Unit& u, int wr, int wc, int fr, int fq) const {
;     ...
;                 const int row = row0 + ai * 128 + m * 16; const float rs = rsqrtf(ss[row] * (1.f / DM) + EPS);
;                 if (u.pn < 12) {
; #pragma unroll
;                     for (int bj = 0; bj < 2; ++bj) { const f32x4 v0 = acc[ai][bj][m][0] * rs, v1 = acc[ai][bj][m][1] * rs;
;                         u32x4 w; w.x = pk(v0[0], v0[1]); w.y = pk(v0[2], v0[3]); w.z = pk(v1[0], v1[1]); w.w = pk(v1[2], v1[3]);
;                         *(u32x4*)(proj + (size_t)row * NPJ + u.pn * 256 + bj * 128 + wc * 32 + 8 * fq) = w; }
;                 } else if (wc == 0 && fq < 2) {
; #pragma unroll
;                     for (int n = 0; n < 2; ++n) *(f32x4*)(gl + (size_t)row * 16 + 8 * fq + 4 * n) = acc[ai][0][m][n] * rs;
.LBB0_281:
	s_nop 1
	v_or_b32_e32 v100, 32, v152
	v_ashrrev_i32_e32 v101, 31, v100
	v_lshl_add_u64 v[98:99], v[100:101], 2, s[8:9]
	s_nop 0
	s_and_b64 vcc, exec, s[4:5]
	v_mov_b32_e32 v98, v174
	v_fmamk_f32 v98, v98, 0x3a800000, v161
	v_mul_f32_e32 v99, 0x4b800000, v98
	v_cmp_gt_f32_e64 s[6:7], s63, v98
	s_nop 1
	v_cndmask_b32_e64 v98, v98, v99, s[6:7]
	v_rsq_f32_e32 v98, v98
	s_nop 0
	v_mul_f32_e32 v99, 0x45800000, v98
	v_cndmask_b32_e64 v98, v98, v99, s[6:7]
	s_mov_b64 s[6:7], -1
	s_cbranch_vccnz .LBB0_285
	s_and_saveexec_b64 s[6:7], s[74:75]
	s_cbranch_execz .LBB0_284
	v_lshlrev_b64 v[102:103], 6, v[100:101]
	v_lshl_add_u64 v[110:111], v[142:143], 0, v[102:103]
	v_pk_mul_f32 v[108:109], v[96:97], v[98:99] op_sel_hi:[1,0]
	v_pk_mul_f32 v[106:107], v[94:95], v[98:99] op_sel_hi:[1,0]
	v_pk_mul_f32 v[104:105], v[92:93], v[98:99] op_sel_hi:[1,0]
	v_pk_mul_f32 v[102:103], v[90:91], v[98:99] op_sel_hi:[1,0]
	global_store_dwordx4 v[110:111], v[106:109], off
	global_store_dwordx4 v[110:111], v[102:105], off offset:16

; __device__ __forceinline__ unsigned pk(float lo, float hi) { return pg8::cvt_pk_bf16(lo, hi); }
;     __device__ __forceinline__ void operator()(const pg8::f32x4 (&acc)[2][2][4][2], const pg8::Unit& u, int wr, int wc, int fr, int fq) const {
;     ...
;                 const int row = row0 + ai * 128 + m * 16; const float rs = rsqrtf(ss[row] * (1.f / DM) + EPS);
;                 if (u.pn < 12) {
; #pragma unroll
;                     for (int bj = 0; bj < 2; ++bj) { const f32x4 v0 = acc[ai][bj][m][0] * rs, v1 = acc[ai][bj][m][1] * rs;
;                         u32x4 w; w.x = pk(v0[0], v0[1]); w.y = pk(v0[2], v0[3]); w.z = pk(v1[0], v1[1]); w.w = pk(v1[2], v1[3]);
;                         *(u32x4*)(proj + (size_t)row * NPJ + u.pn * 256 + bj * 128 + wc * 32 + 8 * fq) = w; }
;                 } else if (wc == 0 && fq < 2) {
; #pragma unroll
;                     for (int n = 0; n < 2; ++n) *(f32x4*)(gl + (size_t)row * 16 + 8 * fq + 4 * n) = acc[ai][0][m][n] * rs;
.LBB0_287:
	s_nop 1
	v_or_b32_e32 v84, 48, v152
	v_ashrrev_i32_e32 v85, 31, v84
	v_lshl_add_u64 v[82:83], v[84:85], 2, s[8:9]
	s_nop 0
	s_and_b64 vcc, exec, s[4:5]
	v_mov_b32_e32 v82, v175
	v_fmamk_f32 v82, v82, 0x3a800000, v161
	v_mul_f32_e32 v83, 0x4b800000, v82
	v_cmp_gt_f32_e64 s[6:7], s63, v82
	s_nop 1
	v_cndmask_b32_e64 v82, v82, v83, s[6:7]
	v_rsq_f32_e32 v82, v82
	s_nop 0
	v_mul_f32_e32 v83, 0x45800000, v82
	v_cndmask_b32_e64 v82, v82, v83, s[6:7]
	s_mov_b64 s[6:7], -1
	s_cbranch_vccnz .LBB0_291
	s_and_saveexec_b64 s[6:7], s[74:75]
	s_cbranch_execz .LBB0_290
	v_lshlrev_b64 v[86:87], 6, v[84:85]
	v_lshl_add_u64 v[94:95], v[142:143], 0, v[86:87]
	v_pk_mul_f32 v[92:93], v[80:81], v[82:83] op_sel_hi:[1,0]
	v_pk_mul_f32 v[90:91], v[78:79], v[82:83] op_sel_hi:[1,0]
	v_pk_mul_f32 v[88:89], v[76:77], v[82:83] op_sel_hi:[1,0]
	v_pk_mul_f32 v[86:87], v[74:75], v[82:83] op_sel_hi:[1,0]
	global_store_dwordx4 v[94:95], v[90:93], off
	global_store_dwordx4 v[94:95], v[86:89], off offset:16

; __device__ __forceinline__ unsigned pk(float lo, float hi) { return pg8::cvt_pk_bf16(lo, hi); }
;     __device__ __forceinline__ void operator()(const pg8::f32x4 (&acc)[2][2][4][2], const pg8::Unit& u, int wr, int wc, int fr, int fq) const {
;     ...
;                 const int row = row0 + ai * 128 + m * 16; const float rs = rsqrtf(ss[row] * (1.f / DM) + EPS);
;                 if (u.pn < 12) {
; #pragma unroll
;                     for (int bj = 0; bj < 2; ++bj) { const f32x4 v0 = acc[ai][bj][m][0] * rs, v1 = acc[ai][bj][m][1] * rs;
;                         u32x4 w; w.x = pk(v0[0], v0[1]); w.y = pk(v0[2], v0[3]); w.z = pk(v1[0], v1[1]); w.w = pk(v1[2], v1[3]);
;                         *(u32x4*)(proj + (size_t)row * NPJ + u.pn * 256 + bj * 128 + wc * 32 + 8 * fq) = w; }
;                 } else if (wc == 0 && fq < 2) {
; #pragma unroll
;                     for (int n = 0; n < 2; ++n) *(f32x4*)(gl + (size_t)row * 16 + 8 * fq + 4 * n) = acc[ai][0][m][n] * rs;
.LBB0_293:
	s_nop 0
	s_nop 0
	v_add_u32_e32 v68, 0x80, v152
	s_and_b64 vcc, exec, s[4:5]
	v_ashrrev_i32_e32 v69, 31, v68
	v_mov_b32_e32 v66, v176
	v_fmamk_f32 v66, v66, 0x3a800000, v161
	v_mul_f32_e32 v67, 0x4b800000, v66
	v_cmp_gt_f32_e64 s[6:7], s63, v66
	s_nop 1
	v_cndmask_b32_e64 v66, v66, v67, s[6:7]
	v_rsq_f32_e32 v66, v66
	s_nop 0
	v_mul_f32_e32 v67, 0x45800000, v66
	v_cndmask_b32_e64 v66, v66, v67, s[6:7]
	s_mov_b64 s[6:7], -1
	s_cbranch_vccnz .LBB0_297
	s_and_saveexec_b64 s[6:7], s[74:75]
	s_cbranch_execz .LBB0_296
	v_lshlrev_b64 v[70:71], 6, v[68:69]
	v_lshl_add_u64 v[78:79], v[142:143], 0, v[70:71]
	v_pk_mul_f32 v[76:77], v[64:65], v[66:67] op_sel_hi:[1,0]
	v_pk_mul_f32 v[74:75], v[62:63], v[66:67] op_sel_hi:[1,0]
	v_pk_mul_f32 v[72:73], v[60:61], v[66:67] op_sel_hi:[1,0]
	v_pk_mul_f32 v[70:71], v[58:59], v[66:67] op_sel_hi:[1,0]
	global_store_dwordx4 v[78:79], v[74:77], off
	global_store_dwordx4 v[78:79], v[70:73], off offset:16

; __device__ __forceinline__ unsigned pk(float lo, float hi) { return pg8::cvt_pk_bf16(lo, hi); }
;     __device__ __forceinline__ void operator()(const pg8::f32x4 (&acc)[2][2][4][2], const pg8::Unit& u, int wr, int wc, int fr, int fq) const {
;     ...
;                 const int row = row0 + ai * 128 + m * 16; const float rs = rsqrtf(ss[row] * (1.f / DM) + EPS);
;                 if (u.pn < 12) {
; #pragma unroll
;                     for (int bj = 0; bj < 2; ++bj) { const f32x4 v0 = acc[ai][bj][m][0] * rs, v1 = acc[ai][bj][m][1] * rs;
;                         u32x4 w; w.x = pk(v0[0], v0[1]); w.y = pk(v0[2], v0[3]); w.z = pk(v1[0], v1[1]); w.w = pk(v1[2], v1[3]);
;                         *(u32x4*)(proj + (size_t)row * NPJ + u.pn * 256 + bj * 128 + wc * 32 + 8 * fq) = w; }
;                 } else if (wc == 0 && fq < 2) {
; #pragma unroll
;                     for (int n = 0; n < 2; ++n) *(f32x4*)(gl + (size_t)row * 16 + 8 * fq + 4 * n) = acc[ai][0][m][n] * rs;
.LBB0_299:
	s_nop 0
	s_nop 0
	v_add_u32_e32 v52, 0x90, v152
	s_and_b64 vcc, exec, s[4:5]
	v_ashrrev_i32_e32 v53, 31, v52
	v_mov_b32_e32 v50, v177
	v_fmamk_f32 v50, v50, 0x3a800000, v161
	v_mul_f32_e32 v51, 0x4b800000, v50
	v_cmp_gt_f32_e64 s[6:7], s63, v50
	s_nop 1
	v_cndmask_b32_e64 v50, v50, v51, s[6:7]
	v_rsq_f32_e32 v50, v50
	s_nop 0
	v_mul_f32_e32 v51, 0x45800000, v50
	v_cndmask_b32_e64 v50, v50, v51, s[6:7]
	s_mov_b64 s[6:7], -1
	s_cbranch_vccnz .LBB0_303
	s_and_saveexec_b64 s[6:7], s[74:75]
	s_cbranch_execz .LBB0_302
	v_lshlrev_b64 v[54:55], 6, v[52:53]
	v_lshl_add_u64 v[62:63], v[142:143], 0, v[54:55]
	v_pk_mul_f32 v[60:61], v[48:49], v[50:51] op_sel_hi:[1,0]
	v_pk_mul_f32 v[58:59], v[46:47], v[50:51] op_sel_hi:[1,0]
	v_pk_mul_f32 v[56:57], v[44:45], v[50:51] op_sel_hi:[1,0]
	v_pk_mul_f32 v[54:55], v[42:43], v[50:51] op_sel_hi:[1,0]
	global_store_dwordx4 v[62:63], v[58:61], off
	global_store_dwordx4 v[62:63], v[54:57], off offset:16

; __device__ __forceinline__ unsigned pk(float lo, float hi) { return pg8::cvt_pk_bf16(lo, hi); }
;     __device__ __forceinline__ void operator()(const pg8::f32x4 (&acc)[2][2][4][2], const pg8::Unit& u, int wr, int wc, int fr, int fq) const {
;     ...
;                 const int row = row0 + ai * 128 + m * 16; const float rs = rsqrtf(ss[row] * (1.f / DM) + EPS);
;                 if (u.pn < 12) {
; #pragma unroll
;                     for (int bj = 0; bj < 2; ++bj) { const f32x4 v0 = acc[ai][bj][m][0] * rs, v1 = acc[ai][bj][m][1] * rs;
;                         u32x4 w; w.x = pk(v0[0], v0[1]); w.y = pk(v0[2], v0[3]); w.z = pk(v1[0], v1[1]); w.w = pk(v1[2], v1[3]);
;                         *(u32x4*)(proj + (size_t)row * NPJ + u.pn * 256 + bj * 128 + wc * 32 + 8 * fq) = w; }
;                 } else if (wc == 0 && fq < 2) {
; #pragma unroll
;                     for (int n = 0; n < 2; ++n) *(f32x4*)(gl + (size_t)row * 16 + 8 * fq + 4 * n) = acc[ai][0][m][n] * rs;
.LBB0_305:
	s_nop 0
	s_nop 0
	v_add_u32_e32 v36, 0xa0, v152
	s_and_b64 vcc, exec, s[4:5]
	v_ashrrev_i32_e32 v37, 31, v36
	v_mov_b32_e32 v34, v178
	v_fmamk_f32 v34, v34, 0x3a800000, v161
	v_mul_f32_e32 v35, 0x4b800000, v34
	v_cmp_gt_f32_e64 s[6:7], s63, v34
	s_nop 1
	v_cndmask_b32_e64 v34, v34, v35, s[6:7]
	v_rsq_f32_e32 v34, v34
	s_nop 0
	v_mul_f32_e32 v35, 0x45800000, v34
	v_cndmask_b32_e64 v34, v34, v35, s[6:7]
	s_mov_b64 s[6:7], -1
	s_cbranch_vccnz .LBB0_309
	s_and_saveexec_b64 s[6:7], s[74:75]
	s_cbranch_execz .LBB0_308
	v_lshlrev_b64 v[38:39], 6, v[36:37]
	v_lshl_add_u64 v[46:47], v[142:143], 0, v[38:39]
	v_pk_mul_f32 v[44:45], v[32:33], v[34:35] op_sel_hi:[1,0]
	v_pk_mul_f32 v[42:43], v[30:31], v[34:35] op_sel_hi:[1,0]
	v_pk_mul_f32 v[40:41], v[28:29], v[34:35] op_sel_hi:[1,0]
	v_pk_mul_f32 v[38:39], v[26:27], v[34:35] op_sel_hi:[1,0]
	global_store_dwordx4 v[46:47], v[42:45], off
	global_store_dwordx4 v[46:47], v[38:41], off offset:16

; __device__ __forceinline__ unsigned pk(float lo, float hi) { return pg8::cvt_pk_bf16(lo, hi); }
;     __device__ __forceinline__ void operator()(const pg8::f32x4 (&acc)[2][2][4][2], const pg8::Unit& u, int wr, int wc, int fr, int fq) const {
;     ...
;                 const int row = row0 + ai * 128 + m * 16; const float rs = rsqrtf(ss[row] * (1.f / DM) + EPS);
;                 if (u.pn < 12) {
; #pragma unroll
;                     for (int bj = 0; bj < 2; ++bj) { const f32x4 v0 = acc[ai][bj][m][0] * rs, v1 = acc[ai][bj][m][1] * rs;
;                         u32x4 w; w.x = pk(v0[0], v0[1]); w.y = pk(v0[2], v0[3]); w.z = pk(v1[0], v1[1]); w.w = pk(v1[2], v1[3]);
;                         *(u32x4*)(proj + (size_t)row * NPJ + u.pn * 256 + bj * 128 + wc * 32 + 8 * fq) = w; }
;                 } else if (wc == 0 && fq < 2) {
; #pragma unroll
;                     for (int n = 0; n < 2; ++n) *(f32x4*)(gl + (size_t)row * 16 + 8 * fq + 4 * n) = acc[ai][0][m][n] * rs;
.LBB0_311:
	s_nop 0
	s_nop 0
	v_add_u32_e32 v20, 0xb0, v152
	s_and_b64 vcc, exec, s[4:5]
	v_ashrrev_i32_e32 v21, 31, v20
	s_mov_b64 s[4:5], -1
	v_mov_b32_e32 v18, v179
	v_fmamk_f32 v18, v18, 0x3a800000, v161
	v_mul_f32_e32 v19, 0x4b800000, v18
	v_cmp_gt_f32_e64 s[6:7], s63, v18
	s_nop 1
	v_cndmask_b32_e64 v18, v18, v19, s[6:7]
	v_rsq_f32_e32 v18, v18
	s_nop 0
	v_mul_f32_e32 v19, 0x45800000, v18
	v_cndmask_b32_e64 v18, v18, v19, s[6:7]
	s_cbranch_vccnz .LBB0_316
	s_and_saveexec_b64 s[4:5], s[74:75]
	s_cbranch_execz .LBB0_314
	v_lshlrev_b64 v[22:23], 6, v[20:21]
	v_lshl_add_u64 v[30:31], v[142:143], 0, v[22:23]
	v_pk_mul_f32 v[28:29], v[16:17], v[18:19] op_sel_hi:[1,0]
	v_pk_mul_f32 v[26:27], v[14:15], v[18:19] op_sel_hi:[1,0]
	v_pk_mul_f32 v[24:25], v[12:13], v[18:19] op_sel_hi:[1,0]
	v_pk_mul_f32 v[22:23], v[10:11], v[18:19] op_sel_hi:[1,0]
	global_store_dwordx4 v[30:31], v[26:29], off
	global_store_dwordx4 v[30:31], v[22:25], off offset:16

; __device__ __forceinline__ unsigned pk(float lo, float hi) { return pg8::cvt_pk_bf16(lo, hi); }
;     __device__ __forceinline__ void operator()(const pg8::f32x4 (&acc)[2][2][4][2], const pg8::Unit& u, int wr, int wc, int fr, int fq) const {
;         const int row0 = u.pm * 256 + wr * 64 + fr;
; #pragma unroll
;         for (int ai = 0; ai < 2; ++ai)
; #pragma unroll
;             for (int m = 0; m < 4; ++m) {
;                 const int row = row0 + ai * 128 + m * 16; const float rs = rsqrtf(ss[row] * (1.f / DM) + EPS);
;                 float y[8];
; #pragma unroll
;                 for (int n = 0; n < 2; ++n)
; #pragma unroll
;                     for (int i = 0; i < 4; ++i) { const float g = acc[ai][0][m][n][i] * rs, up = acc[ai][1][m][n][i] * rs; y[4 * n + i] = g * up * __builtin_amdgcn_rcpf(1.f + __expf(-g)); }
;                 u32x4 w; w.x = pk(y[0], y[1]); w.y = pk(y[2], y[3]); w.z = pk(y[4], y[5]); w.w = pk(y[6], y[7]);
;                 *(u32x4*)(act + (size_t)row * DFF + u.pn * 128 + wc * 32 + 8 * fq) = w;
.LBB0_901:
	v_lshl_add_u32 v148, s68, 8, v152
	v_ashrrev_i32_e32 v149, 31, v148
	v_lshl_add_u64 v[150:151], v[148:149], 2, s[8:9]
	global_load_dword v170, v[150:151], off
	global_load_dword v171, v[150:151], off offset:64
	global_load_dword v172, v[150:151], off offset:128
	global_load_dword v173, v[150:151], off offset:192
	global_load_dword v174, v[150:151], off offset:512
	global_load_dword v175, v[150:151], off offset:576
	global_load_dword v176, v[150:151], off offset:640
	global_load_dword v177, v[150:151], off offset:704
	v_or_b32_e32 v162, 16, v148
	v_ashrrev_i32_e32 v163, 31, v162
	v_mov_b32_e32 v161, v116
	v_mov_b32_e32 v116, v125
	v_mov_b32_e32 v158, v126
	v_mov_b32_e32 v159, v118
	v_mov_b32_e32 v118, v127
	v_mov_b32_e32 v126, v128
	v_mov_b32_e32 v127, v120
	v_mov_b32_e32 v120, v129
	v_mov_b32_e32 v128, v122
	v_mov_b32_e32 v129, v114
	v_mov_b32_e32 v114, v123
	v_mov_b32_e32 v160, v124
	s_lshl_b32 s68, s69, 7
	v_mov_b64_e32 v[122:123], s[12:13]
	s_ashr_i32 s69, s68, 31
	v_mad_i64_i32 v[124:125], s[70:71], v148, s77, v[122:123]
	s_lshl_b64 s[68:69], s[68:69], 1
	v_lshl_add_u64 v[124:125], v[124:125], 0, s[68:69]
	v_lshl_add_u64 v[124:125], v[124:125], 0, s[4:5]
	v_lshl_add_u64 v[124:125], v[124:125], 0, v[138:139]
	s_waitcnt vmcnt(0)
	v_mov_b32_e32 v149, v170
	v_fmamk_f32 v149, v149, 0x3a800000, v157
	v_mul_f32_e32 v164, 0x4b800000, v149
	v_cmp_gt_f32_e32 vcc, s76, v149
	s_nop 1
	v_cndmask_b32_e32 v149, v149, v164, vcc
	v_rsq_f32_e32 v149, v149
	v_lshl_add_u64 v[164:165], v[162:163], 2, s[8:9]
	v_mul_f32_e32 v163, 0x45800000, v149
	v_cndmask_b32_e32 v166, v149, v163, vcc
	v_pk_mul_f32 v[116:117], v[116:117], v[166:167] op_sel_hi:[1,0]
	v_pk_mul_f32 v[158:159], v[158:159], v[166:167] op_sel_hi:[1,0]
	v_pk_mul_f32 v[118:119], v[118:119], v[166:167] op_sel_hi:[1,0]
	v_pk_mul_f32 v[126:127], v[126:127], v[166:167] op_sel_hi:[1,0]
	v_pk_mul_f32 v[120:121], v[120:121], v[166:167] op_sel_hi:[1,0]
	v_pk_mul_f32 v[128:129], v[128:129], v[166:167] op_sel_hi:[1,0]
	v_pk_mul_f32 v[114:115], v[114:115], v[166:167] op_sel_hi:[1,0]
	v_pk_mul_f32 v[160:161], v[160:161], v[166:167] op_sel_hi:[1,0]
	v_mul_f32_e32 v117, v116, v117
	v_mul_f32_e32 v116, 0xbfb8aa3b, v116
	v_mul_f32_e32 v149, v158, v159
	v_mul_f32_e32 v158, 0xbfb8aa3b, v158
	v_mul_f32_e32 v119, v118, v119
	v_mul_f32_e32 v118, 0xbfb8aa3b, v118
	v_mul_f32_e32 v127, v126, v127
	v_mul_f32_e32 v126, 0xbfb8aa3b, v126
	v_mul_f32_e32 v121, v120, v121
	v_mul_f32_e32 v120, 0xbfb8aa3b, v120
	v_mul_f32_e32 v129, v128, v129
	v_mul_f32_e32 v128, 0xbfb8aa3b, v128
	v_mul_f32_e32 v115, v114, v115
	v_mul_f32_e32 v114, 0xbfb8aa3b, v114
	v_mul_f32_e32 v159, v160, v161
	v_mul_f32_e32 v160, 0xbfb8aa3b, v160
	v_exp_f32_e32 v116, v116
	v_exp_f32_e32 v158, v158
	v_exp_f32_e32 v118, v118
	v_exp_f32_e32 v126, v126
	v_exp_f32_e32 v120, v120
	v_exp_f32_e32 v128, v128
	v_exp_f32_e32 v114, v114
	v_exp_f32_e32 v160, v160
	v_add_f32_e32 v116, 1.0, v116
	v_add_f32_e32 v158, 1.0, v158
	v_add_f32_e32 v118, 1.0, v118
	v_add_f32_e32 v126, 1.0, v126
	v_add_f32_e32 v120, 1.0, v120
	v_add_f32_e32 v128, 1.0, v128
	v_add_f32_e32 v114, 1.0, v114
	v_add_f32_e32 v160, 1.0, v160
	v_rcp_f32_e32 v116, v116
	v_rcp_f32_e32 v158, v158
	v_rcp_f32_e32 v118, v118
	v_rcp_f32_e32 v126, v126
	v_rcp_f32_e32 v120, v120
	v_rcp_f32_e32 v128, v128
	v_rcp_f32_e32 v114, v114
	v_rcp_f32_e32 v160, v160
	v_mul_f32_e32 v117, v117, v116
	v_mul_f32_e32 v149, v149, v158
	v_mul_f32_e32 v118, v119, v118
	v_mul_f32_e32 v119, v127, v126
	v_mul_f32_e32 v120, v121, v120
	v_mul_f32_e32 v121, v129, v128
	v_mul_f32_e32 v126, v115, v114
	v_mul_f32_e32 v127, v159, v160
	v_cvt_pk_bf16_f32 v114, v149, v118
	v_cvt_pk_bf16_f32 v115, v119, v120
	v_cvt_pk_bf16_f32 v116, v121, v126
	v_cvt_pk_bf16_f32 v117, v127, v117
	global_store_dwordx4 v[124:125], v[114:117], off
	s_nop 0
	v_mov_b32_e32 v118, v171
	v_fmamk_f32 v118, v118, 0x3a800000, v157
	v_mul_f32_e32 v119, 0x4b800000, v118
	v_cmp_gt_f32_e32 vcc, s76, v118
	v_mov_b32_e32 v114, v110
	v_mov_b32_e32 v110, v112
	v_cndmask_b32_e32 v118, v118, v119, vcc
	v_rsq_f32_e32 v120, v118
	v_mov_b32_e32 v112, v106
	v_mov_b32_e32 v106, v108
	v_or_b32_e32 v108, 32, v148
	v_mov_b32_e32 v115, v102
	v_mov_b32_e32 v102, v111
	v_mov_b32_e32 v111, v104
	v_mov_b32_e32 v104, v113
	v_mov_b32_e32 v113, v98
	v_mov_b32_e32 v98, v107
	v_mov_b32_e32 v107, v100
	v_mov_b32_e32 v100, v109
	v_ashrrev_i32_e32 v109, 31, v108
	v_lshl_add_u64 v[118:119], v[108:109], 2, s[8:9]
	v_mul_f32_e32 v109, 0x45800000, v120
	v_cndmask_b32_e32 v120, v120, v109, vcc
	v_pk_mul_f32 v[100:101], v[100:101], v[120:121] op_sel_hi:[1,0]
	v_pk_mul_f32 v[114:115], v[114:115], v[120:121] op_sel_hi:[1,0]
	v_pk_mul_f32 v[102:103], v[102:103], v[120:121] op_sel_hi:[1,0]
	v_pk_mul_f32 v[110:111], v[110:111], v[120:121] op_sel_hi:[1,0]
	v_pk_mul_f32 v[104:105], v[104:105], v[120:121] op_sel_hi:[1,0]
	v_pk_mul_f32 v[112:113], v[112:113], v[120:121] op_sel_hi:[1,0]
	v_pk_mul_f32 v[98:99], v[98:99], v[120:121] op_sel_hi:[1,0]
	v_pk_mul_f32 v[106:107], v[106:107], v[120:121] op_sel_hi:[1,0]
	v_mul_f32_e32 v101, v100, v101
	v_mul_f32_e32 v100, 0xbfb8aa3b, v100
	v_mul_f32_e32 v109, v114, v115
	v_mul_f32_e32 v114, 0xbfb8aa3b, v114
	v_mul_f32_e32 v103, v102, v103
	v_mul_f32_e32 v102, 0xbfb8aa3b, v102
	v_mul_f32_e32 v111, v110, v111
	v_mul_f32_e32 v110, 0xbfb8aa3b, v110
	v_mul_f32_e32 v105, v104, v105
	v_mul_f32_e32 v104, 0xbfb8aa3b, v104
	v_mul_f32_e32 v113, v112, v113
	v_mul_f32_e32 v112, 0xbfb8aa3b, v112
	v_mul_f32_e32 v99, v98, v99
	v_mul_f32_e32 v98, 0xbfb8aa3b, v98
	v_mul_f32_e32 v107, v106, v107
	v_mul_f32_e32 v106, 0xbfb8aa3b, v106
	v_exp_f32_e32 v100, v100
	v_exp_f32_e32 v114, v114
; __device__ __forceinline__ unsigned pk(float lo, float hi) { return pg8::cvt_pk_bf16(lo, hi); }
;     __device__ __forceinline__ void operator()(const pg8::f32x4 (&acc)[2][2][4][2], const pg8::Unit& u, int wr, int wc, int fr, int fq) const {
;     ...
;                 const int row = row0 + ai * 128 + m * 16; const float rs = rsqrtf(ss[row] * (1.f / DM) + EPS);
;                 float y[8];
; #pragma unroll
;                 for (int n = 0; n < 2; ++n)
; #pragma unroll
;                     for (int i = 0; i < 4; ++i) { const float g = acc[ai][0][m][n][i] * rs, up = acc[ai][1][m][n][i] * rs; y[4 * n + i] = g * up * __builtin_amdgcn_rcpf(1.f + __expf(-g)); }
;                 u32x4 w; w.x = pk(y[0], y[1]); w.y = pk(y[2], y[3]); w.z = pk(y[4], y[5]); w.w = pk(y[6], y[7]);
;                 *(u32x4*)(act + (size_t)row * DFF + u.pn * 128 + wc * 32 + 8 * fq) = w;
	v_exp_f32_e32 v102, v102
	v_exp_f32_e32 v110, v110
	v_exp_f32_e32 v104, v104
	v_exp_f32_e32 v112, v112
	v_exp_f32_e32 v98, v98
	v_exp_f32_e32 v106, v106
	v_add_f32_e32 v100, 1.0, v100
	v_add_f32_e32 v114, 1.0, v114
	v_add_f32_e32 v102, 1.0, v102
	v_add_f32_e32 v110, 1.0, v110
	v_add_f32_e32 v104, 1.0, v104
	v_add_f32_e32 v112, 1.0, v112
	v_add_f32_e32 v98, 1.0, v98
	v_add_f32_e32 v106, 1.0, v106
	v_rcp_f32_e32 v100, v100
	v_mad_i64_i32 v[116:117], s[70:71], v162, s77, v[122:123]
	v_rcp_f32_e32 v114, v114
	v_rcp_f32_e32 v102, v102
	v_rcp_f32_e32 v110, v110
	v_rcp_f32_e32 v104, v104
	v_rcp_f32_e32 v112, v112
	v_rcp_f32_e32 v98, v98
	v_rcp_f32_e32 v106, v106
	v_lshl_add_u64 v[116:117], v[116:117], 0, s[68:69]
	v_lshl_add_u64 v[116:117], v[116:117], 0, s[4:5]
	v_lshl_add_u64 v[116:117], v[116:117], 0, v[138:139]
	v_mul_f32_e32 v101, v101, v100
	v_mul_f32_e32 v109, v109, v114
	v_mul_f32_e32 v102, v103, v102
	v_mul_f32_e32 v103, v111, v110
	v_mul_f32_e32 v104, v105, v104
	v_mul_f32_e32 v105, v113, v112
	v_mul_f32_e32 v110, v99, v98
	v_mul_f32_e32 v106, v107, v106
	v_cvt_pk_bf16_f32 v98, v109, v102
	v_cvt_pk_bf16_f32 v99, v103, v104
	v_cvt_pk_bf16_f32 v100, v105, v110
	v_cvt_pk_bf16_f32 v101, v106, v101
	global_store_dwordx4 v[116:117], v[98:101], off
	s_nop 0
	v_mov_b32_e32 v102, v172
	v_fmamk_f32 v102, v102, 0x3a800000, v157
	v_mul_f32_e32 v103, 0x4b800000, v102
	v_cmp_gt_f32_e32 vcc, s76, v102
	v_mov_b32_e32 v98, v94
	v_mov_b32_e32 v94, v96
	v_cndmask_b32_e32 v102, v102, v103, vcc
	v_rsq_f32_e32 v104, v102
	v_mov_b32_e32 v96, v90
	v_mov_b32_e32 v90, v92
	v_or_b32_e32 v92, 48, v148
	v_mov_b32_e32 v99, v86
	v_mov_b32_e32 v86, v95
	v_mov_b32_e32 v95, v88
	v_mov_b32_e32 v88, v97
	v_mov_b32_e32 v97, v82
	v_mov_b32_e32 v82, v91
	v_mov_b32_e32 v91, v84
	v_mov_b32_e32 v84, v93
	v_ashrrev_i32_e32 v93, 31, v92
	v_lshl_add_u64 v[102:103], v[92:93], 2, s[8:9]
	v_mul_f32_e32 v93, 0x45800000, v104
	v_cndmask_b32_e32 v104, v104, v93, vcc
	v_pk_mul_f32 v[84:85], v[84:85], v[104:105] op_sel_hi:[1,0]
	v_pk_mul_f32 v[98:99], v[98:99], v[104:105] op_sel_hi:[1,0]
	v_pk_mul_f32 v[86:87], v[86:87], v[104:105] op_sel_hi:[1,0]
	v_pk_mul_f32 v[94:95], v[94:95], v[104:105] op_sel_hi:[1,0]
	v_pk_mul_f32 v[88:89], v[88:89], v[104:105] op_sel_hi:[1,0]
	v_pk_mul_f32 v[96:97], v[96:97], v[104:105] op_sel_hi:[1,0]
	v_pk_mul_f32 v[82:83], v[82:83], v[104:105] op_sel_hi:[1,0]
	v_pk_mul_f32 v[90:91], v[90:91], v[104:105] op_sel_hi:[1,0]
	v_mul_f32_e32 v85, v84, v85
	v_mul_f32_e32 v84, 0xbfb8aa3b, v84
	v_mul_f32_e32 v93, v98, v99
	v_mul_f32_e32 v98, 0xbfb8aa3b, v98
	v_mul_f32_e32 v87, v86, v87
	v_mul_f32_e32 v86, 0xbfb8aa3b, v86
	v_mul_f32_e32 v95, v94, v95
	v_mul_f32_e32 v94, 0xbfb8aa3b, v94
	v_mul_f32_e32 v89, v88, v89
	v_mul_f32_e32 v88, 0xbfb8aa3b, v88
	v_mul_f32_e32 v97, v96, v97
	v_mul_f32_e32 v96, 0xbfb8aa3b, v96
	v_mul_f32_e32 v83, v82, v83
	v_mul_f32_e32 v82, 0xbfb8aa3b, v82
	v_mul_f32_e32 v91, v90, v91
	v_mul_f32_e32 v90, 0xbfb8aa3b, v90
	v_exp_f32_e32 v84, v84
	v_exp_f32_e32 v98, v98
	v_exp_f32_e32 v86, v86
	v_exp_f32_e32 v94, v94
	v_exp_f32_e32 v88, v88
	v_exp_f32_e32 v96, v96
	v_exp_f32_e32 v82, v82
	v_exp_f32_e32 v90, v90
	v_add_f32_e32 v84, 1.0, v84
	v_add_f32_e32 v98, 1.0, v98
	v_add_f32_e32 v86, 1.0, v86
	v_add_f32_e32 v94, 1.0, v94
	v_add_f32_e32 v88, 1.0, v88
	v_add_f32_e32 v96, 1.0, v96
	v_add_f32_e32 v82, 1.0, v82
	v_add_f32_e32 v90, 1.0, v90
	v_rcp_f32_e32 v84, v84
	v_mad_i64_i32 v[100:101], s[70:71], v108, s77, v[122:123]
	v_rcp_f32_e32 v98, v98
	v_rcp_f32_e32 v86, v86
	v_rcp_f32_e32 v94, v94
	v_rcp_f32_e32 v88, v88
	v_rcp_f32_e32 v96, v96
	v_rcp_f32_e32 v82, v82
	v_rcp_f32_e32 v90, v90
	v_lshl_add_u64 v[100:101], v[100:101], 0, s[68:69]
	v_lshl_add_u64 v[100:101], v[100:101], 0, s[4:5]
	v_lshl_add_u64 v[100:101], v[100:101], 0, v[138:139]
	v_mul_f32_e32 v85, v85, v84
	v_mul_f32_e32 v93, v93, v98
	v_mul_f32_e32 v86, v87, v86
	v_mul_f32_e32 v87, v95, v94
	v_mul_f32_e32 v88, v89, v88
	v_mul_f32_e32 v89, v97, v96
	v_mul_f32_e32 v94, v83, v82
	v_mul_f32_e32 v90, v91, v90
	v_cvt_pk_bf16_f32 v82, v93, v86
	v_cvt_pk_bf16_f32 v83, v87, v88
	v_cvt_pk_bf16_f32 v84, v89, v94
	v_cvt_pk_bf16_f32 v85, v90, v85
	global_store_dwordx4 v[100:101], v[82:85], off
	s_nop 0
	s_nop 0
	v_mov_b32_e32 v83, v70
	v_mov_b32_e32 v70, v79
	v_mov_b32_e32 v79, v72
	v_mov_b32_e32 v72, v81
	v_mov_b32_e32 v81, v66
	v_mov_b32_e32 v66, v75
	v_mov_b32_e32 v75, v68
	v_mov_b32_e32 v68, v77
	v_mov_b32_e32 v82, v78
	v_mov_b32_e32 v78, v80
	v_mov_b32_e32 v80, v74
	v_mov_b32_e32 v74, v76
	v_mad_i64_i32 v[76:77], s[70:71], v92, s77, v[122:123]
	v_lshl_add_u64 v[76:77], v[76:77], 0, s[68:69]
	v_lshl_add_u64 v[76:77], v[76:77], 0, s[4:5]
	v_lshl_add_u64 v[76:77], v[76:77], 0, v[138:139]
	v_mov_b32_e32 v84, v173
	v_fmamk_f32 v84, v84, 0x3a800000, v157
	v_mul_f32_e32 v85, 0x4b800000, v84
	v_cmp_gt_f32_e32 vcc, s76, v84
	s_nop 1
	v_cndmask_b32_e32 v84, v84, v85, vcc
	v_rsq_f32_e32 v84, v84
	s_nop 0
	v_mul_f32_e32 v85, 0x45800000, v84
	v_cndmask_b32_e32 v84, v84, v85, vcc
	v_pk_mul_f32 v[68:69], v[68:69], v[84:85] op_sel_hi:[1,0]
	v_pk_mul_f32 v[82:83], v[82:83], v[84:85] op_sel_hi:[1,0]
	v_pk_mul_f32 v[70:71], v[70:71], v[84:85] op_sel_hi:[1,0]
	v_pk_mul_f32 v[78:79], v[78:79], v[84:85] op_sel_hi:[1,0]
	v_pk_mul_f32 v[72:73], v[72:73], v[84:85] op_sel_hi:[1,0]
	v_pk_mul_f32 v[80:81], v[80:81], v[84:85] op_sel_hi:[1,0]
	v_pk_mul_f32 v[66:67], v[66:67], v[84:85] op_sel_hi:[1,0]
	v_pk_mul_f32 v[74:75], v[74:75], v[84:85] op_sel_hi:[1,0]
	v_mul_f32_e32 v69, v68, v69
	v_mul_f32_e32 v68, 0xbfb8aa3b, v68
	v_mul_f32_e32 v83, v82, v83
	v_mul_f32_e32 v82, 0xbfb8aa3b, v82
	v_mul_f32_e32 v71, v70, v71
; __device__ __forceinline__ unsigned pk(float lo, float hi) { return pg8::cvt_pk_bf16(lo, hi); }
;     __device__ __forceinline__ void operator()(const pg8::f32x4 (&acc)[2][2][4][2], const pg8::Unit& u, int wr, int wc, int fr, int fq) const {
;     ...
;                 const int row = row0 + ai * 128 + m * 16; const float rs = rsqrtf(ss[row] * (1.f / DM) + EPS);
;                 float y[8];
; #pragma unroll
;                 for (int n = 0; n < 2; ++n)
; #pragma unroll
;                     for (int i = 0; i < 4; ++i) { const float g = acc[ai][0][m][n][i] * rs, up = acc[ai][1][m][n][i] * rs; y[4 * n + i] = g * up * __builtin_amdgcn_rcpf(1.f + __expf(-g)); }
;                 u32x4 w; w.x = pk(y[0], y[1]); w.y = pk(y[2], y[3]); w.z = pk(y[4], y[5]); w.w = pk(y[6], y[7]);
;                 *(u32x4*)(act + (size_t)row * DFF + u.pn * 128 + wc * 32 + 8 * fq) = w;
	v_mul_f32_e32 v70, 0xbfb8aa3b, v70
	v_mul_f32_e32 v79, v78, v79
	v_mul_f32_e32 v78, 0xbfb8aa3b, v78
	v_mul_f32_e32 v73, v72, v73
	v_mul_f32_e32 v72, 0xbfb8aa3b, v72
	v_mul_f32_e32 v81, v80, v81
	v_mul_f32_e32 v80, 0xbfb8aa3b, v80
	v_mul_f32_e32 v67, v66, v67
	v_mul_f32_e32 v66, 0xbfb8aa3b, v66
	v_mul_f32_e32 v75, v74, v75
	v_mul_f32_e32 v74, 0xbfb8aa3b, v74
	v_exp_f32_e32 v68, v68
	v_exp_f32_e32 v82, v82
	v_exp_f32_e32 v70, v70
	v_exp_f32_e32 v78, v78
	v_exp_f32_e32 v72, v72
	v_exp_f32_e32 v80, v80
	v_exp_f32_e32 v66, v66
	v_exp_f32_e32 v74, v74
	v_add_f32_e32 v68, 1.0, v68
	v_add_f32_e32 v82, 1.0, v82
	v_add_f32_e32 v70, 1.0, v70
	v_add_f32_e32 v78, 1.0, v78
	v_add_f32_e32 v72, 1.0, v72
	v_add_f32_e32 v80, 1.0, v80
	v_add_f32_e32 v66, 1.0, v66
	v_add_f32_e32 v74, 1.0, v74
	v_rcp_f32_e32 v68, v68
	v_rcp_f32_e32 v82, v82
	v_rcp_f32_e32 v70, v70
	v_rcp_f32_e32 v78, v78
	v_rcp_f32_e32 v72, v72
	v_rcp_f32_e32 v80, v80
	v_rcp_f32_e32 v66, v66
	v_rcp_f32_e32 v74, v74
	v_mul_f32_e32 v69, v69, v68
	v_mul_f32_e32 v82, v83, v82
	v_mul_f32_e32 v70, v71, v70
	v_mul_f32_e32 v71, v79, v78
	v_mul_f32_e32 v72, v73, v72
	v_mul_f32_e32 v73, v81, v80
	v_mul_f32_e32 v78, v67, v66
	v_mul_f32_e32 v74, v75, v74
	v_cvt_pk_bf16_f32 v66, v82, v70
	v_cvt_pk_bf16_f32 v67, v71, v72
	v_cvt_pk_bf16_f32 v68, v73, v78
	v_cvt_pk_bf16_f32 v69, v74, v69
	global_store_dwordx4 v[76:77], v[66:69], off
	s_nop 0
	s_nop 0
	v_mov_b32_e32 v67, v54
	v_mov_b32_e32 v54, v63
	v_mov_b32_e32 v63, v56
	v_mov_b32_e32 v56, v65
	v_mov_b32_e32 v65, v50
	v_mov_b32_e32 v50, v59
	v_mov_b32_e32 v59, v52
	v_mov_b32_e32 v52, v61
	v_mov_b32_e32 v66, v62
	v_mov_b32_e32 v62, v64
	v_mov_b32_e32 v64, v58
	v_mov_b32_e32 v58, v60
	v_add_u32_e32 v60, 0x80, v148
	v_mad_i64_i32 v[60:61], s[70:71], v60, s77, v[122:123]
	v_lshl_add_u64 v[60:61], v[60:61], 0, s[68:69]
	v_lshl_add_u64 v[60:61], v[60:61], 0, s[4:5]
	v_lshl_add_u64 v[60:61], v[60:61], 0, v[138:139]
	v_mov_b32_e32 v68, v174
	v_fmamk_f32 v68, v68, 0x3a800000, v157
	v_mul_f32_e32 v69, 0x4b800000, v68
	v_cmp_gt_f32_e32 vcc, s76, v68
	s_nop 1
	v_cndmask_b32_e32 v68, v68, v69, vcc
	v_rsq_f32_e32 v68, v68
	s_nop 0
	v_mul_f32_e32 v69, 0x45800000, v68
	v_cndmask_b32_e32 v68, v68, v69, vcc
	v_pk_mul_f32 v[52:53], v[52:53], v[68:69] op_sel_hi:[1,0]
	v_pk_mul_f32 v[66:67], v[66:67], v[68:69] op_sel_hi:[1,0]
	v_pk_mul_f32 v[54:55], v[54:55], v[68:69] op_sel_hi:[1,0]
	v_pk_mul_f32 v[62:63], v[62:63], v[68:69] op_sel_hi:[1,0]
	v_pk_mul_f32 v[56:57], v[56:57], v[68:69] op_sel_hi:[1,0]
	v_pk_mul_f32 v[64:65], v[64:65], v[68:69] op_sel_hi:[1,0]
	v_pk_mul_f32 v[50:51], v[50:51], v[68:69] op_sel_hi:[1,0]
	v_pk_mul_f32 v[58:59], v[58:59], v[68:69] op_sel_hi:[1,0]
	v_mul_f32_e32 v53, v52, v53
	v_mul_f32_e32 v52, 0xbfb8aa3b, v52
	v_mul_f32_e32 v67, v66, v67
	v_mul_f32_e32 v66, 0xbfb8aa3b, v66
	v_mul_f32_e32 v55, v54, v55
	v_mul_f32_e32 v54, 0xbfb8aa3b, v54
	v_mul_f32_e32 v63, v62, v63
	v_mul_f32_e32 v62, 0xbfb8aa3b, v62
	v_mul_f32_e32 v57, v56, v57
	v_mul_f32_e32 v56, 0xbfb8aa3b, v56
	v_mul_f32_e32 v65, v64, v65
	v_mul_f32_e32 v64, 0xbfb8aa3b, v64
	v_mul_f32_e32 v51, v50, v51
	v_mul_f32_e32 v50, 0xbfb8aa3b, v50
	v_mul_f32_e32 v59, v58, v59
	v_mul_f32_e32 v58, 0xbfb8aa3b, v58
	v_exp_f32_e32 v52, v52
	v_exp_f32_e32 v66, v66
	v_exp_f32_e32 v54, v54
	v_exp_f32_e32 v62, v62
	v_exp_f32_e32 v56, v56
	v_exp_f32_e32 v64, v64
	v_exp_f32_e32 v50, v50
	v_exp_f32_e32 v58, v58
	v_add_f32_e32 v52, 1.0, v52
	v_add_f32_e32 v66, 1.0, v66
	v_add_f32_e32 v54, 1.0, v54
	v_add_f32_e32 v62, 1.0, v62
	v_add_f32_e32 v56, 1.0, v56
	v_add_f32_e32 v64, 1.0, v64
	v_add_f32_e32 v50, 1.0, v50
	v_add_f32_e32 v58, 1.0, v58
	v_rcp_f32_e32 v52, v52
	v_rcp_f32_e32 v66, v66
	v_rcp_f32_e32 v54, v54
	v_rcp_f32_e32 v62, v62
	v_rcp_f32_e32 v56, v56
	v_rcp_f32_e32 v64, v64
	v_rcp_f32_e32 v50, v50
	v_rcp_f32_e32 v58, v58
	v_mul_f32_e32 v53, v53, v52
	v_mul_f32_e32 v66, v67, v66
	v_mul_f32_e32 v54, v55, v54
	v_mul_f32_e32 v55, v63, v62
	v_mul_f32_e32 v56, v57, v56
	v_mul_f32_e32 v57, v65, v64
	v_mul_f32_e32 v62, v51, v50
	v_mul_f32_e32 v58, v59, v58
	v_cvt_pk_bf16_f32 v50, v66, v54
	v_cvt_pk_bf16_f32 v51, v55, v56
	v_cvt_pk_bf16_f32 v52, v57, v62
	v_cvt_pk_bf16_f32 v53, v58, v53
	global_store_dwordx4 v[60:61], v[50:53], off
	s_nop 0
	s_nop 0
	v_mov_b32_e32 v51, v38
	v_mov_b32_e32 v38, v47
	v_mov_b32_e32 v47, v40
	v_mov_b32_e32 v40, v49
	v_mov_b32_e32 v49, v34
	v_mov_b32_e32 v34, v43
	v_mov_b32_e32 v43, v36
	v_mov_b32_e32 v36, v45
	v_mov_b32_e32 v50, v46
	v_mov_b32_e32 v46, v48
	v_mov_b32_e32 v48, v42
	v_mov_b32_e32 v42, v44
	v_add_u32_e32 v44, 0x90, v148
	v_mad_i64_i32 v[44:45], s[70:71], v44, s77, v[122:123]
	v_lshl_add_u64 v[44:45], v[44:45], 0, s[68:69]
	v_lshl_add_u64 v[44:45], v[44:45], 0, s[4:5]
	v_lshl_add_u64 v[44:45], v[44:45], 0, v[138:139]
	v_mov_b32_e32 v52, v175
	v_fmamk_f32 v52, v52, 0x3a800000, v157
	v_mul_f32_e32 v53, 0x4b800000, v52
	v_cmp_gt_f32_e32 vcc, s76, v52
	s_nop 1
	v_cndmask_b32_e32 v52, v52, v53, vcc
	v_rsq_f32_e32 v52, v52
	s_nop 0
	v_mul_f32_e32 v53, 0x45800000, v52
	v_cndmask_b32_e32 v52, v52, v53, vcc
	v_pk_mul_f32 v[36:37], v[36:37], v[52:53] op_sel_hi:[1,0]
	v_pk_mul_f32 v[50:51], v[50:51], v[52:53] op_sel_hi:[1,0]
	v_pk_mul_f32 v[38:39], v[38:39], v[52:53] op_sel_hi:[1,0]
	v_pk_mul_f32 v[46:47], v[46:47], v[52:53] op_sel_hi:[1,0]
	v_pk_mul_f32 v[40:41], v[40:41], v[52:53] op_sel_hi:[1,0]
	v_pk_mul_f32 v[48:49], v[48:49], v[52:53] op_sel_hi:[1,0]
	v_pk_mul_f32 v[34:35], v[34:35], v[52:53] op_sel_hi:[1,0]
	v_pk_mul_f32 v[42:43], v[42:43], v[52:53] op_sel_hi:[1,0]
	v_mul_f32_e32 v37, v36, v37
	v_mul_f32_e32 v36, 0xbfb8aa3b, v36
	v_mul_f32_e32 v51, v50, v51
	v_mul_f32_e32 v50, 0xbfb8aa3b, v50
; __device__ __forceinline__ unsigned pk(float lo, float hi) { return pg8::cvt_pk_bf16(lo, hi); }
;     __device__ __forceinline__ void operator()(const pg8::f32x4 (&acc)[2][2][4][2], const pg8::Unit& u, int wr, int wc, int fr, int fq) const {
;     ...
;                 const int row = row0 + ai * 128 + m * 16; const float rs = rsqrtf(ss[row] * (1.f / DM) + EPS);
;                 float y[8];
; #pragma unroll
;                 for (int n = 0; n < 2; ++n)
; #pragma unroll
;                     for (int i = 0; i < 4; ++i) { const float g = acc[ai][0][m][n][i] * rs, up = acc[ai][1][m][n][i] * rs; y[4 * n + i] = g * up * __builtin_amdgcn_rcpf(1.f + __expf(-g)); }
;                 u32x4 w; w.x = pk(y[0], y[1]); w.y = pk(y[2], y[3]); w.z = pk(y[4], y[5]); w.w = pk(y[6], y[7]);
;                 *(u32x4*)(act + (size_t)row * DFF + u.pn * 128 + wc * 32 + 8 * fq) = w;
	v_mul_f32_e32 v39, v38, v39
	v_mul_f32_e32 v38, 0xbfb8aa3b, v38
	v_mul_f32_e32 v47, v46, v47
	v_mul_f32_e32 v46, 0xbfb8aa3b, v46
	v_mul_f32_e32 v41, v40, v41
	v_mul_f32_e32 v40, 0xbfb8aa3b, v40
	v_mul_f32_e32 v49, v48, v49
	v_mul_f32_e32 v48, 0xbfb8aa3b, v48
	v_mul_f32_e32 v35, v34, v35
	v_mul_f32_e32 v34, 0xbfb8aa3b, v34
	v_mul_f32_e32 v43, v42, v43
	v_mul_f32_e32 v42, 0xbfb8aa3b, v42
	v_exp_f32_e32 v36, v36
	v_exp_f32_e32 v50, v50
	v_exp_f32_e32 v38, v38
	v_exp_f32_e32 v46, v46
	v_exp_f32_e32 v40, v40
	v_exp_f32_e32 v48, v48
	v_exp_f32_e32 v34, v34
	v_exp_f32_e32 v42, v42
	v_add_f32_e32 v36, 1.0, v36
	v_add_f32_e32 v50, 1.0, v50
	v_add_f32_e32 v38, 1.0, v38
	v_add_f32_e32 v46, 1.0, v46
	v_add_f32_e32 v40, 1.0, v40
	v_add_f32_e32 v48, 1.0, v48
	v_add_f32_e32 v34, 1.0, v34
	v_add_f32_e32 v42, 1.0, v42
	v_rcp_f32_e32 v36, v36
	v_rcp_f32_e32 v50, v50
	v_rcp_f32_e32 v38, v38
	v_rcp_f32_e32 v46, v46
	v_rcp_f32_e32 v40, v40
	v_rcp_f32_e32 v48, v48
	v_rcp_f32_e32 v34, v34
	v_rcp_f32_e32 v42, v42
	v_mul_f32_e32 v37, v37, v36
	v_mul_f32_e32 v50, v51, v50
	v_mul_f32_e32 v38, v39, v38
	v_mul_f32_e32 v39, v47, v46
	v_mul_f32_e32 v40, v41, v40
	v_mul_f32_e32 v41, v49, v48
	v_mul_f32_e32 v46, v35, v34
	v_mul_f32_e32 v42, v43, v42
	v_cvt_pk_bf16_f32 v34, v50, v38
	v_cvt_pk_bf16_f32 v35, v39, v40
	v_cvt_pk_bf16_f32 v36, v41, v46
	v_cvt_pk_bf16_f32 v37, v42, v37
	global_store_dwordx4 v[44:45], v[34:37], off
	s_nop 0
	s_nop 0
	v_mov_b32_e32 v35, v22
	v_mov_b32_e32 v22, v31
	v_mov_b32_e32 v31, v24
	v_mov_b32_e32 v24, v33
	v_mov_b32_e32 v33, v18
	v_mov_b32_e32 v18, v27
	v_mov_b32_e32 v27, v20
	v_mov_b32_e32 v20, v29
	v_mov_b32_e32 v34, v30
	v_mov_b32_e32 v30, v32
	v_mov_b32_e32 v32, v26
	v_mov_b32_e32 v26, v28
	v_add_u32_e32 v28, 0xa0, v148
	v_mad_i64_i32 v[28:29], s[70:71], v28, s77, v[122:123]
	v_lshl_add_u64 v[28:29], v[28:29], 0, s[68:69]
	v_lshl_add_u64 v[28:29], v[28:29], 0, s[4:5]
	v_lshl_add_u64 v[28:29], v[28:29], 0, v[138:139]
	v_mov_b32_e32 v36, v176
	v_fmamk_f32 v36, v36, 0x3a800000, v157
	v_mul_f32_e32 v37, 0x4b800000, v36
	v_cmp_gt_f32_e32 vcc, s76, v36
	s_nop 1
	v_cndmask_b32_e32 v36, v36, v37, vcc
	v_rsq_f32_e32 v36, v36
	s_nop 0
	v_mul_f32_e32 v37, 0x45800000, v36
	v_cndmask_b32_e32 v36, v36, v37, vcc
	v_pk_mul_f32 v[20:21], v[20:21], v[36:37] op_sel_hi:[1,0]
	v_pk_mul_f32 v[34:35], v[34:35], v[36:37] op_sel_hi:[1,0]
	v_pk_mul_f32 v[22:23], v[22:23], v[36:37] op_sel_hi:[1,0]
	v_pk_mul_f32 v[30:31], v[30:31], v[36:37] op_sel_hi:[1,0]
	v_pk_mul_f32 v[24:25], v[24:25], v[36:37] op_sel_hi:[1,0]
	v_pk_mul_f32 v[32:33], v[32:33], v[36:37] op_sel_hi:[1,0]
	v_pk_mul_f32 v[18:19], v[18:19], v[36:37] op_sel_hi:[1,0]
	v_pk_mul_f32 v[26:27], v[26:27], v[36:37] op_sel_hi:[1,0]
	v_mul_f32_e32 v21, v20, v21
	v_mul_f32_e32 v20, 0xbfb8aa3b, v20
	v_mul_f32_e32 v35, v34, v35
	v_mul_f32_e32 v34, 0xbfb8aa3b, v34
	v_mul_f32_e32 v23, v22, v23
	v_mul_f32_e32 v22, 0xbfb8aa3b, v22
	v_mul_f32_e32 v31, v30, v31
	v_mul_f32_e32 v30, 0xbfb8aa3b, v30
	v_mul_f32_e32 v25, v24, v25
	v_mul_f32_e32 v24, 0xbfb8aa3b, v24
	v_mul_f32_e32 v33, v32, v33
	v_mul_f32_e32 v32, 0xbfb8aa3b, v32
	v_mul_f32_e32 v19, v18, v19
	v_mul_f32_e32 v18, 0xbfb8aa3b, v18
	v_mul_f32_e32 v27, v26, v27
	v_mul_f32_e32 v26, 0xbfb8aa3b, v26
	v_exp_f32_e32 v20, v20
	v_exp_f32_e32 v34, v34
	v_exp_f32_e32 v22, v22
	v_exp_f32_e32 v30, v30
	v_exp_f32_e32 v24, v24
	v_exp_f32_e32 v32, v32
	v_exp_f32_e32 v18, v18
	v_exp_f32_e32 v26, v26
	v_add_f32_e32 v20, 1.0, v20
	v_add_f32_e32 v34, 1.0, v34
	v_add_f32_e32 v22, 1.0, v22
	v_add_f32_e32 v30, 1.0, v30
	v_add_f32_e32 v24, 1.0, v24
	v_add_f32_e32 v32, 1.0, v32
; __device__ __forceinline__ unsigned pk(float lo, float hi) { return pg8::cvt_pk_bf16(lo, hi); }
;     __device__ __forceinline__ void operator()(const pg8::f32x4 (&acc)[2][2][4][2], const pg8::Unit& u, int wr, int wc, int fr, int fq) const {
;     ...
;                 const int row = row0 + ai * 128 + m * 16; const float rs = rsqrtf(ss[row] * (1.f / DM) + EPS);
;                 float y[8];
; #pragma unroll
;                 for (int n = 0; n < 2; ++n)
; #pragma unroll
;                     for (int i = 0; i < 4; ++i) { const float g = acc[ai][0][m][n][i] * rs, up = acc[ai][1][m][n][i] * rs; y[4 * n + i] = g * up * __builtin_amdgcn_rcpf(1.f + __expf(-g)); }
;                 u32x4 w; w.x = pk(y[0], y[1]); w.y = pk(y[2], y[3]); w.z = pk(y[4], y[5]); w.w = pk(y[6], y[7]);
;                 *(u32x4*)(act + (size_t)row * DFF + u.pn * 128 + wc * 32 + 8 * fq) = w;
	v_add_f32_e32 v18, 1.0, v18
	v_add_f32_e32 v26, 1.0, v26
	v_rcp_f32_e32 v20, v20
	v_rcp_f32_e32 v34, v34
	v_rcp_f32_e32 v22, v22
	v_rcp_f32_e32 v30, v30
	v_rcp_f32_e32 v24, v24
	v_rcp_f32_e32 v32, v32
	v_rcp_f32_e32 v18, v18
	v_rcp_f32_e32 v26, v26
	v_mul_f32_e32 v21, v21, v20
	v_mul_f32_e32 v34, v35, v34
	v_mul_f32_e32 v22, v23, v22
	v_mul_f32_e32 v23, v31, v30
	v_mul_f32_e32 v24, v25, v24
	v_mul_f32_e32 v25, v33, v32
	v_mul_f32_e32 v30, v19, v18
	v_mul_f32_e32 v26, v27, v26
	v_cvt_pk_bf16_f32 v18, v34, v22
	v_cvt_pk_bf16_f32 v19, v23, v24
	v_cvt_pk_bf16_f32 v20, v25, v30
	v_cvt_pk_bf16_f32 v21, v26, v21
	global_store_dwordx4 v[28:29], v[18:21], off
	s_nop 0
	s_andn2_b64 vcc, exec, s[0:1]
	v_mov_b32_e32 v19, v6
	v_mov_b32_e32 v6, v15
	v_mov_b32_e32 v15, v8
	v_mov_b32_e32 v8, v17
	v_mov_b32_e32 v17, v2
	v_mov_b32_e32 v2, v11
	v_mov_b32_e32 v11, v4
	v_mov_b32_e32 v4, v13
	v_mov_b32_e32 v18, v14
	v_mov_b32_e32 v14, v16
	v_mov_b32_e32 v16, v10
	v_mov_b32_e32 v10, v12
	v_add_u32_e32 v12, 0xb0, v148
	v_mad_i64_i32 v[12:13], s[70:71], v12, s77, v[122:123]
	v_lshl_add_u64 v[12:13], v[12:13], 0, s[68:69]
	v_lshl_add_u64 v[12:13], v[12:13], 0, s[4:5]
	v_lshl_add_u64 v[12:13], v[12:13], 0, v[138:139]
	v_mov_b32_e32 v20, v177
	v_fmamk_f32 v20, v20, 0x3a800000, v157
	v_mul_f32_e32 v21, 0x4b800000, v20
	v_cmp_gt_f32_e64 s[0:1], s76, v20
	s_nop 1
	v_cndmask_b32_e64 v20, v20, v21, s[0:1]
	v_rsq_f32_e32 v20, v20
	s_nop 0
	v_mul_f32_e32 v21, 0x45800000, v20
	v_cndmask_b32_e64 v20, v20, v21, s[0:1]
	v_pk_mul_f32 v[4:5], v[4:5], v[20:21] op_sel_hi:[1,0]
	v_pk_mul_f32 v[18:19], v[18:19], v[20:21] op_sel_hi:[1,0]
	v_pk_mul_f32 v[6:7], v[6:7], v[20:21] op_sel_hi:[1,0]
	v_pk_mul_f32 v[14:15], v[14:15], v[20:21] op_sel_hi:[1,0]
	v_pk_mul_f32 v[8:9], v[8:9], v[20:21] op_sel_hi:[1,0]
	v_pk_mul_f32 v[16:17], v[16:17], v[20:21] op_sel_hi:[1,0]
	v_pk_mul_f32 v[2:3], v[2:3], v[20:21] op_sel_hi:[1,0]
	v_pk_mul_f32 v[10:11], v[10:11], v[20:21] op_sel_hi:[1,0]
	v_mul_f32_e32 v5, v4, v5
	v_mul_f32_e32 v4, 0xbfb8aa3b, v4
	v_mul_f32_e32 v19, v18, v19
	v_mul_f32_e32 v18, 0xbfb8aa3b, v18
	v_mul_f32_e32 v7, v6, v7
	v_mul_f32_e32 v6, 0xbfb8aa3b, v6
	v_mul_f32_e32 v15, v14, v15
	v_mul_f32_e32 v14, 0xbfb8aa3b, v14
	v_mul_f32_e32 v9, v8, v9
	v_mul_f32_e32 v8, 0xbfb8aa3b, v8
	v_mul_f32_e32 v17, v16, v17
	v_mul_f32_e32 v16, 0xbfb8aa3b, v16
	v_mul_f32_e32 v3, v2, v3
	v_mul_f32_e32 v2, 0xbfb8aa3b, v2
	v_mul_f32_e32 v11, v10, v11
	v_mul_f32_e32 v10, 0xbfb8aa3b, v10
	v_exp_f32_e32 v4, v4
	v_exp_f32_e32 v18, v18
	v_exp_f32_e32 v6, v6
	v_exp_f32_e32 v14, v14
	v_exp_f32_e32 v8, v8
	v_exp_f32_e32 v16, v16
	v_exp_f32_e32 v2, v2
	v_exp_f32_e32 v10, v10
	v_add_f32_e32 v4, 1.0, v4
	v_add_f32_e32 v18, 1.0, v18
	v_add_f32_e32 v6, 1.0, v6
	v_add_f32_e32 v14, 1.0, v14
	v_add_f32_e32 v8, 1.0, v8
	v_add_f32_e32 v16, 1.0, v16
	v_add_f32_e32 v2, 1.0, v2
	v_add_f32_e32 v10, 1.0, v10
	v_rcp_f32_e32 v4, v4
	v_rcp_f32_e32 v18, v18
	v_rcp_f32_e32 v6, v6
	v_rcp_f32_e32 v14, v14
	v_rcp_f32_e32 v8, v8
	v_rcp_f32_e32 v16, v16
	v_rcp_f32_e32 v2, v2
	v_rcp_f32_e32 v10, v10
	v_mul_f32_e32 v5, v5, v4
	s_mov_b64 s[0:1], -1
	v_mul_f32_e32 v18, v19, v18
	v_mul_f32_e32 v6, v7, v6
	v_mul_f32_e32 v7, v15, v14
	v_mul_f32_e32 v8, v9, v8
	v_mul_f32_e32 v9, v17, v16
	v_mul_f32_e32 v14, v3, v2
	v_mul_f32_e32 v10, v11, v10
	v_cvt_pk_bf16_f32 v2, v18, v6
	v_cvt_pk_bf16_f32 v3, v7, v8
	v_cvt_pk_bf16_f32 v4, v9, v14
	v_cvt_pk_bf16_f32 v5, v10, v5
	global_store_dwordx4 v[12:13], v[2:5], off
	s_cbranch_vccnz .LBB0_894
	s_andn2_b64 vcc, exec, s[6:7]
	s_cbranch_vccnz .LBB0_893
	s_barrier
	s_branch .LBB0_893

;     __device__ __forceinline__ void operator()(const pg8::f32x4 (&acc)[2][2][4][2], const pg8::Unit& u, int wr, int wc, int fr, int fq) const {
;         const int row0 = u.pm * 256 + wr * 64 + fr;
;         const int sect = u.pn >> 2;
; #pragma unroll
;         for (int ai = 0; ai < 2; ++ai)
; #pragma unroll
;             for (int m = 0; m < 4; ++m) {
;                 const int row = row0 + ai * 128 + m * 16; const float rs = rsqrtf(ss[row] * (1.f / DM) + EPS);
;                 if (u.pn < 12) {
;                     const float sc = (sect == 0) ? rs * QSCALE2 : rs;
.LBB0_1324:
	v_lshl_add_u32 v158, s4, 8, v145
	v_ashrrev_i32_e32 v159, 31, v158
	v_lshl_add_u64 v[160:161], v[158:159], 2, s[40:41]
	global_load_dword v191, v[160:161], off
	global_load_dword v192, v[160:161], off offset:64
	global_load_dword v193, v[160:161], off offset:128
	global_load_dword v194, v[160:161], off offset:192
	global_load_dword v195, v[160:161], off offset:512
	global_load_dword v196, v[160:161], off offset:576
	global_load_dword v197, v[160:161], off offset:640
	global_load_dword v198, v[160:161], off offset:704
	s_ashr_i32 s6, s8, 2
	s_cmp_gt_i32 s8, 11
	s_cselect_b64 s[80:81], -1, 0
	s_cmp_lt_u32 s8, 4
	s_cselect_b64 s[4:5], -1, 0
	s_cmp_eq_u32 s6, 1
	s_cselect_b64 s[10:11], -1, 0
	s_cmp_eq_u32 s6, 2
	s_cselect_b64 s[76:77], -1, 0
	s_cmp_gt_i32 s6, 0
	s_cselect_b64 s[74:75], -1, 0
	s_mov_b64 s[6:7], -1
	s_waitcnt vmcnt(0)
	v_mov_b32_e32 v130, v191
	v_fmamk_f32 v130, v130, 0x3a800000, v186
	v_cmp_gt_f32_e32 vcc, s94, v130
	v_mul_f32_e32 v131, 0x4b800000, v130
	s_nop 0
	v_cndmask_b32_e32 v130, v130, v131, vcc
	v_rsq_f32_e32 v130, v130
	s_nop 0
	v_mul_f32_e32 v131, 0x45800000, v130
	v_cndmask_b32_e32 v190, v130, v131, vcc
	s_and_b64 vcc, exec, s[80:81]
	s_cbranch_vccz .LBB0_1328
	s_and_saveexec_b64 s[78:79], s[48:49]
	s_cbranch_execz .LBB0_1327
; __device__ __forceinline__ float log_sigmoid(float z) { return fminf(z, 0.f) - __logf(1.f + __expf(-fabsf(z))); }
;     __device__ __forceinline__ void operator()(const pg8::f32x4 (&acc)[2][2][4][2], const pg8::Unit& u, int wr, int wc, int fr, int fq) const {
;     ...
;                 } else if (wc == 0 && fq < 2) {
;                     float* d = (row < MP) ? out + O_FLP + (size_t)row * 16 : out + O_FLS + (size_t)(row - MP) * 16;
; #pragma unroll
;                     for (int n = 0; n < 2; ++n) { const f32x4 v = acc[ai][0][m][n] * rs; f32x4 o;
; #pragma unroll
;                         for (int i = 0; i < 4; ++i) o[i] = log_sigmoid(v[i] + bf[8 * fq + 4 * n + i]);
;                         *(f32x4*)(d + 8 * fq + 4 * n) = o; }
	v_cmp_gt_i32_e32 vcc, s86, v158
	v_add_u32_e32 v130, 0xffffc000, v158
	v_readlane_b32 s52, v252, 0
	v_cndmask_b32_e32 v131, 0, v159, vcc
	v_cndmask_b32_e32 v130, v130, v158, vcc
	v_cndmask_b32_e32 v142, v187, v188, vcc
	v_readlane_b32 s58, v252, 6
	v_readlane_b32 s59, v252, 7
	v_lshlrev_b64 v[130:131], 6, v[130:131]
	v_readlane_b32 s53, v252, 1
	v_lshl_add_u64 v[132:133], s[58:59], 0, v[142:143]
	v_lshl_add_u64 v[130:131], v[132:133], 0, v[130:131]
	v_lshlrev_b32_e32 v142, 2, v144
	v_lshl_add_u64 v[162:163], v[130:131], 0, v[142:143]
	global_load_dwordx4 v[130:133], v[148:149], off
	v_readlane_b32 s54, v252, 2
	v_readlane_b32 s55, v252, 3
	v_readlane_b32 s56, v252, 4
	v_readlane_b32 s57, v252, 5
	s_waitcnt vmcnt(0)
	v_fma_f32 v142, v126, v190, v130
	v_min_f32_e32 v130, 0, v142
	v_mul_f32_e64 v142, |v142|, s95
	v_exp_f32_e32 v142, v142
	v_fma_f32 v132, v128, v190, v132
	v_min_f32_e32 v166, 0, v132
	v_mul_f32_e64 v132, |v132|, s95
	v_add_f32_e32 v142, 1.0, v142
	v_cmp_gt_f32_e32 vcc, s94, v142
	v_exp_f32_e32 v132, v132
	v_fmac_f32_e32 v133, v129, v190
	v_cndmask_b32_e64 v164, 0, 32, vcc
	v_ldexp_f32 v142, v142, v164
	v_log_f32_e32 v142, v142
	v_add_f32_e32 v132, 1.0, v132
	v_min_f32_e32 v167, 0, v133
	v_mul_f32_e64 v133, |v133|, s95
	v_mul_f32_e32 v164, 0x3f317217, v142
	v_fma_f32 v164, v142, s96, -v164
	v_fmac_f32_e32 v164, 0x3377d1cf, v142
	v_fmac_f32_e32 v164, 0x3f317217, v142
	v_cmp_lt_f32_e64 s[6:7], |v142|, s97
	v_exp_f32_e32 v133, v133
	s_nop 0
	v_cndmask_b32_e64 v142, v142, v164, s[6:7]
	v_cndmask_b32_e32 v164, 0, v189, vcc
	v_sub_f32_e32 v164, v142, v164
	v_fma_f32 v142, v127, v190, v131
	v_min_f32_e32 v131, 0, v142
	v_mul_f32_e64 v142, |v142|, s95
	v_exp_f32_e32 v142, v142
	v_add_f32_e32 v133, 1.0, v133
	v_add_f32_e32 v142, 1.0, v142
	v_cmp_gt_f32_e32 vcc, s94, v142
	s_nop 1
	v_cndmask_b32_e64 v165, 0, 32, vcc
	v_ldexp_f32 v142, v142, v165
	v_log_f32_e32 v142, v142
	s_nop 0
	v_mul_f32_e32 v165, 0x3f317217, v142
	v_fma_f32 v165, v142, s96, -v165
	v_fmac_f32_e32 v165, 0x3377d1cf, v142
	v_fmac_f32_e32 v165, 0x3f317217, v142
	v_cmp_lt_f32_e64 s[6:7], |v142|, s97
	s_nop 1
	v_cndmask_b32_e64 v142, v142, v165, s[6:7]
	v_cndmask_b32_e32 v165, 0, v189, vcc
	v_cmp_gt_f32_e32 vcc, s94, v132
	v_sub_f32_e32 v165, v142, v165
	v_pk_add_f32 v[130:131], v[130:131], v[164:165] neg_lo:[0,1] neg_hi:[0,1]
	v_cndmask_b32_e64 v142, 0, 32, vcc
	v_ldexp_f32 v132, v132, v142
	v_log_f32_e32 v132, v132
	s_nop 0
	v_mul_f32_e32 v142, 0x3f317217, v132
	v_fma_f32 v142, v132, s96, -v142
	v_fmac_f32_e32 v142, 0x3377d1cf, v132
	v_fmac_f32_e32 v142, 0x3f317217, v132
	v_cmp_lt_f32_e64 s[6:7], |v132|, s97
	s_nop 1
	v_cndmask_b32_e64 v132, v132, v142, s[6:7]
	v_cndmask_b32_e32 v142, 0, v189, vcc
	v_cmp_gt_f32_e32 vcc, s94, v133
	v_sub_f32_e32 v132, v132, v142
	s_nop 0
	v_cndmask_b32_e64 v142, 0, 32, vcc
	v_ldexp_f32 v133, v133, v142
	v_log_f32_e32 v133, v133
	s_nop 0
	v_mul_f32_e32 v142, 0x3f317217, v133
	v_fma_f32 v142, v133, s96, -v142
	v_fmac_f32_e32 v142, 0x3377d1cf, v133
	v_fmac_f32_e32 v142, 0x3f317217, v133
	v_cmp_lt_f32_e64 s[6:7], |v133|, s97
	s_nop 1
	v_cndmask_b32_e64 v133, v133, v142, s[6:7]
	v_cndmask_b32_e32 v142, 0, v189, vcc
	v_sub_f32_e32 v133, v133, v142
	v_pk_add_f32 v[132:133], v[166:167], v[132:133] neg_lo:[0,1] neg_hi:[0,1]
	global_store_dwordx4 v[162:163], v[130:133], off
	global_load_dwordx4 v[130:133], v[148:149], off offset:16
	s_waitcnt vmcnt(0)
	v_fma_f32 v142, v122, v190, v130
	v_min_f32_e32 v130, 0, v142
	v_mul_f32_e64 v142, |v142|, s95
	v_exp_f32_e32 v142, v142
	v_fma_f32 v132, v124, v190, v132
	v_min_f32_e32 v166, 0, v132
	v_mul_f32_e64 v132, |v132|, s95
	v_add_f32_e32 v142, 1.0, v142
	v_cmp_gt_f32_e32 vcc, s94, v142
	v_exp_f32_e32 v132, v132
	v_fmac_f32_e32 v133, v125, v190
	v_cndmask_b32_e64 v164, 0, 32, vcc
	v_ldexp_f32 v142, v142, v164
	v_log_f32_e32 v142, v142
	v_add_f32_e32 v132, 1.0, v132
	v_min_f32_e32 v167, 0, v133
	v_mul_f32_e64 v133, |v133|, s95
	v_mul_f32_e32 v164, 0x3f317217, v142
	v_fma_f32 v164, v142, s96, -v164
	v_fmac_f32_e32 v164, 0x3377d1cf, v142
	v_fmac_f32_e32 v164, 0x3f317217, v142
	v_cmp_lt_f32_e64 s[6:7], |v142|, s97
	v_exp_f32_e32 v133, v133
	s_nop 0
	v_cndmask_b32_e64 v142, v142, v164, s[6:7]
	v_cndmask_b32_e32 v164, 0, v189, vcc
	v_sub_f32_e32 v164, v142, v164
	v_fma_f32 v142, v123, v190, v131
	v_min_f32_e32 v131, 0, v142
	v_mul_f32_e64 v142, |v142|, s95
	v_exp_f32_e32 v142, v142
	v_add_f32_e32 v133, 1.0, v133
	v_add_f32_e32 v142, 1.0, v142
	v_cmp_gt_f32_e32 vcc, s94, v142
	s_nop 1
	v_cndmask_b32_e64 v165, 0, 32, vcc
	v_ldexp_f32 v142, v142, v165
	v_log_f32_e32 v142, v142
	s_nop 0
	v_mul_f32_e32 v165, 0x3f317217, v142
	v_fma_f32 v165, v142, s96, -v165
	v_fmac_f32_e32 v165, 0x3377d1cf, v142
	v_fmac_f32_e32 v165, 0x3f317217, v142
	v_cmp_lt_f32_e64 s[6:7], |v142|, s97
	s_nop 1
	v_cndmask_b32_e64 v142, v142, v165, s[6:7]
	v_cndmask_b32_e32 v165, 0, v189, vcc
	v_cmp_gt_f32_e32 vcc, s94, v132
	v_sub_f32_e32 v165, v142, v165
	v_pk_add_f32 v[130:131], v[130:131], v[164:165] neg_lo:[0,1] neg_hi:[0,1]
	v_cndmask_b32_e64 v142, 0, 32, vcc
	v_ldexp_f32 v132, v132, v142
	v_log_f32_e32 v132, v132
	s_nop 0
	v_mul_f32_e32 v142, 0x3f317217, v132
	v_fma_f32 v142, v132, s96, -v142
	v_fmac_f32_e32 v142, 0x3377d1cf, v132
	v_fmac_f32_e32 v142, 0x3f317217, v132
	v_cmp_lt_f32_e64 s[6:7], |v132|, s97
	s_nop 1
	v_cndmask_b32_e64 v132, v132, v142, s[6:7]
	v_cndmask_b32_e32 v142, 0, v189, vcc
	v_cmp_gt_f32_e32 vcc, s94, v133
	v_sub_f32_e32 v132, v132, v142
	s_nop 0
	v_cndmask_b32_e64 v142, 0, 32, vcc
	v_ldexp_f32 v133, v133, v142
	v_log_f32_e32 v133, v133
	s_nop 0
	v_mul_f32_e32 v142, 0x3f317217, v133
	v_fma_f32 v142, v133, s96, -v142
	v_fmac_f32_e32 v142, 0x3377d1cf, v133
	v_fmac_f32_e32 v142, 0x3f317217, v133
	v_cmp_lt_f32_e64 s[6:7], |v133|, s97
	s_nop 1
	v_cndmask_b32_e64 v133, v133, v142, s[6:7]
	v_cndmask_b32_e32 v142, 0, v189, vcc
	v_sub_f32_e32 v133, v133, v142
	v_pk_add_f32 v[132:133], v[166:167], v[132:133] neg_lo:[0,1] neg_hi:[0,1]
	global_store_dwordx4 v[162:163], v[130:133], off offset:16

; __device__ __forceinline__ unsigned pk(float lo, float hi) { return pg8::cvt_pk_bf16(lo, hi); }
; __device__ __forceinline__ float log_sigmoid(float z) { return fminf(z, 0.f) - __logf(1.f + __expf(-fabsf(z))); }
;     __device__ __forceinline__ void operator()(const pg8::f32x4 (&acc)[2][2][4][2], const pg8::Unit& u, int wr, int wc, int fr, int fq) const {
;     ...
;                 const int row = row0 + ai * 128 + m * 16; const float rs = rsqrtf(ss[row] * (1.f / DM) + EPS);
;                 if (u.pn < 12) {
;                     const float sc = (sect == 0) ? rs * QSCALE2 : rs;
;                     float* fdst = nullptr;
;                     if (sect == 1) fdst = (row < MP) ? out + O_FKP + (size_t)row * DM : out + O_FKS + (size_t)(row - MP) * DM;
;                     if (sect == 2) fdst = (row < MP) ? out + O_FVP + (size_t)row * DM : out + O_FVS + (size_t)(row - MP) * DM;
; #pragma unroll
;                     for (int bj = 0; bj < 2; ++bj) { const f32x4 v0 = acc[ai][bj][m][0] * sc, v1 = acc[ai][bj][m][1] * sc;
;                         u32x4 w; w.x = pk(v0[0], v0[1]); w.y = pk(v0[2], v0[3]); w.z = pk(v1[0], v1[1]); w.w = pk(v1[2], v1[3]);
;                         const int cl = bj * 128 + wc * 32 + 8 * fq;
;                         *(u32x4*)(qkv + (size_t)row * NPJ + u.pn * 256 + cl) = w;
;                         if (sect > 0) { float* d = fdst + (u.pn & 3) * 256 + cl; __builtin_nontemporal_store(v0, (f32x4*)d); __builtin_nontemporal_store(v1, (f32x4*)(d + 4)); } }
;                 } else if (wc == 0 && fq < 2) {
;                     float* d = (row < MP) ? out + O_FLP + (size_t)row * 16 : out + O_FLS + (size_t)(row - MP) * 16;
; #pragma unroll
;                     for (int n = 0; n < 2; ++n) { const f32x4 v = acc[ai][0][m][n] * rs; f32x4 o;
; #pragma unroll
;                         for (int i = 0; i < 4; ++i) o[i] = log_sigmoid(v[i] + bf[8 * fq + 4 * n + i]);
;                         *(f32x4*)(d + 8 * fq + 4 * n) = o; }
.LBB0_1345:
	s_nop 0
	v_or_b32_e32 v118, 16, v158
	v_ashrrev_i32_e32 v119, 31, v118
	v_lshl_add_u64 v[114:115], v[118:119], 2, s[40:41]
	s_nop 0
	s_andn2_b64 vcc, exec, s[80:81]
	v_mov_b32_e32 v114, v192
	v_fmamk_f32 v114, v114, 0x3a800000, v186
	v_mul_f32_e32 v115, 0x4b800000, v114
	v_cmp_gt_f32_e64 s[10:11], s94, v114
	s_nop 1
	v_cndmask_b32_e64 v114, v114, v115, s[10:11]
	v_rsq_f32_e32 v114, v114
	v_cndmask_b32_e64 v115, 0, 1, s[80:81]
	v_cmp_ne_u32_e64 s[8:9], 1, v115
	v_mul_f32_e32 v115, 0x45800000, v114
	v_cndmask_b32_e64 v126, v114, v115, s[10:11]
	s_mov_b64 s[10:11], -1
	s_cbranch_vccnz .LBB0_1349
	s_and_saveexec_b64 s[80:81], s[48:49]
	s_cbranch_execz .LBB0_1348
	v_cmp_gt_i32_e32 vcc, s86, v118
	v_add_u32_e32 v114, 0xffffc010, v158
	v_readlane_b32 s52, v252, 0
	v_cndmask_b32_e32 v115, 0, v119, vcc
	v_cndmask_b32_e32 v114, v114, v118, vcc
	v_cndmask_b32_e32 v142, v187, v188, vcc
	v_readlane_b32 s58, v252, 6
	v_readlane_b32 s59, v252, 7
	v_lshlrev_b64 v[114:115], 6, v[114:115]
	v_readlane_b32 s53, v252, 1
	v_lshl_add_u64 v[116:117], s[58:59], 0, v[142:143]
	v_lshl_add_u64 v[114:115], v[116:117], 0, v[114:115]
	v_lshlrev_b32_e32 v142, 2, v144
	v_lshl_add_u64 v[120:121], v[114:115], 0, v[142:143]
	global_load_dwordx4 v[114:117], v[148:149], off
	v_readlane_b32 s54, v252, 2
	v_readlane_b32 s55, v252, 3
	v_readlane_b32 s56, v252, 4
	v_readlane_b32 s57, v252, 5
	s_waitcnt vmcnt(0)
	v_fma_f32 v122, v110, v126, v114
	v_min_f32_e32 v114, 0, v122
	v_mul_f32_e64 v122, |v122|, s95
	v_exp_f32_e32 v122, v122
	v_fma_f32 v116, v112, v126, v116
	v_fmac_f32_e32 v117, v113, v126
	v_add_f32_e32 v122, 1.0, v122
	v_cmp_gt_f32_e32 vcc, s94, v122
	s_nop 1
	v_cndmask_b32_e64 v123, 0, 32, vcc
	v_ldexp_f32 v122, v122, v123
	v_log_f32_e32 v122, v122
	s_nop 0
	v_mul_f32_e32 v123, 0x3f317217, v122
	v_fma_f32 v123, v122, s96, -v123
	v_fmac_f32_e32 v123, 0x3377d1cf, v122
	v_fmac_f32_e32 v123, 0x3f317217, v122
	v_cmp_lt_f32_e64 s[10:11], |v122|, s97
	s_nop 1
	v_cndmask_b32_e64 v122, v122, v123, s[10:11]
	v_cndmask_b32_e32 v123, 0, v189, vcc
	v_sub_f32_e32 v122, v122, v123
	v_fma_f32 v123, v111, v126, v115
	v_min_f32_e32 v115, 0, v123
	v_mul_f32_e64 v123, |v123|, s95
	v_exp_f32_e32 v123, v123
	s_nop 0
	v_add_f32_e32 v123, 1.0, v123
	v_cmp_gt_f32_e32 vcc, s94, v123
	s_nop 1
	v_cndmask_b32_e64 v124, 0, 32, vcc
	v_ldexp_f32 v123, v123, v124
	v_log_f32_e32 v123, v123
	s_nop 0
	v_mul_f32_e32 v124, 0x3f317217, v123
	v_fma_f32 v124, v123, s96, -v124
	v_fmac_f32_e32 v124, 0x3377d1cf, v123
	v_fmac_f32_e32 v124, 0x3f317217, v123
	v_cmp_lt_f32_e64 s[10:11], |v123|, s97
	s_nop 1
	v_cndmask_b32_e64 v123, v123, v124, s[10:11]
	v_cndmask_b32_e32 v124, 0, v189, vcc
	v_sub_f32_e32 v123, v123, v124
	v_min_f32_e32 v124, 0, v116
	v_mul_f32_e64 v116, |v116|, s95
	v_exp_f32_e32 v116, v116
	v_pk_add_f32 v[114:115], v[114:115], v[122:123] neg_lo:[0,1] neg_hi:[0,1]
	v_add_f32_e32 v116, 1.0, v116
	v_cmp_gt_f32_e32 vcc, s94, v116
	s_nop 1
	v_cndmask_b32_e64 v125, 0, 32, vcc
	v_ldexp_f32 v116, v116, v125
	v_log_f32_e32 v116, v116
	s_nop 0
	v_mul_f32_e32 v125, 0x3f317217, v116
	v_fma_f32 v125, v116, s96, -v125
	v_fmac_f32_e32 v125, 0x3377d1cf, v116
	v_fmac_f32_e32 v125, 0x3f317217, v116
	v_cmp_lt_f32_e64 s[10:11], |v116|, s97
	s_nop 1
	v_cndmask_b32_e64 v116, v116, v125, s[10:11]
	v_cndmask_b32_e32 v125, 0, v189, vcc
	v_sub_f32_e32 v116, v116, v125
	v_min_f32_e32 v125, 0, v117
	v_mul_f32_e64 v117, |v117|, s95
	v_exp_f32_e32 v117, v117
	s_nop 0
	v_add_f32_e32 v117, 1.0, v117
	v_cmp_gt_f32_e32 vcc, s94, v117
	s_nop 1
	v_cndmask_b32_e64 v127, 0, 32, vcc
	v_ldexp_f32 v117, v117, v127
	v_log_f32_e32 v117, v117
	s_nop 0
	v_mul_f32_e32 v127, 0x3f317217, v117
	v_fma_f32 v127, v117, s96, -v127
	v_fmac_f32_e32 v127, 0x3377d1cf, v117
	v_fmac_f32_e32 v127, 0x3f317217, v117
	v_cmp_lt_f32_e64 s[10:11], |v117|, s97
	s_nop 1
	v_cndmask_b32_e64 v117, v117, v127, s[10:11]
	v_cndmask_b32_e32 v127, 0, v189, vcc
	v_sub_f32_e32 v117, v117, v127
	v_pk_add_f32 v[116:117], v[124:125], v[116:117] neg_lo:[0,1] neg_hi:[0,1]
	global_store_dwordx4 v[120:121], v[114:117], off
	global_load_dwordx4 v[114:117], v[148:149], off offset:16
	s_waitcnt vmcnt(0)
	v_fma_f32 v122, v106, v126, v114
	v_min_f32_e32 v114, 0, v122
	v_mul_f32_e64 v122, |v122|, s95
	v_exp_f32_e32 v122, v122
	v_fma_f32 v116, v108, v126, v116
	v_fmac_f32_e32 v117, v109, v126
	v_add_f32_e32 v122, 1.0, v122
	v_cmp_gt_f32_e32 vcc, s94, v122
	s_nop 1
	v_cndmask_b32_e64 v123, 0, 32, vcc
	v_ldexp_f32 v122, v122, v123
	v_log_f32_e32 v122, v122
	s_nop 0
	v_mul_f32_e32 v123, 0x3f317217, v122
	v_fma_f32 v123, v122, s96, -v123
	v_fmac_f32_e32 v123, 0x3377d1cf, v122
	v_fmac_f32_e32 v123, 0x3f317217, v122
	v_cmp_lt_f32_e64 s[10:11], |v122|, s97
	s_nop 1
	v_cndmask_b32_e64 v122, v122, v123, s[10:11]
	v_cndmask_b32_e32 v123, 0, v189, vcc
	v_sub_f32_e32 v122, v122, v123
	v_fma_f32 v123, v107, v126, v115
	v_min_f32_e32 v115, 0, v123
	v_mul_f32_e64 v123, |v123|, s95
	v_exp_f32_e32 v123, v123
	s_nop 0
	v_add_f32_e32 v123, 1.0, v123
	v_cmp_gt_f32_e32 vcc, s94, v123
	s_nop 1
	v_cndmask_b32_e64 v124, 0, 32, vcc
	v_ldexp_f32 v123, v123, v124
	v_log_f32_e32 v123, v123
	s_nop 0
	v_mul_f32_e32 v124, 0x3f317217, v123
	v_fma_f32 v124, v123, s96, -v124
	v_fmac_f32_e32 v124, 0x3377d1cf, v123
	v_fmac_f32_e32 v124, 0x3f317217, v123
	v_cmp_lt_f32_e64 s[10:11], |v123|, s97
	s_nop 1
	v_cndmask_b32_e64 v123, v123, v124, s[10:11]
	v_cndmask_b32_e32 v124, 0, v189, vcc
	v_sub_f32_e32 v123, v123, v124
	v_min_f32_e32 v124, 0, v116
	v_mul_f32_e64 v116, |v116|, s95
	v_exp_f32_e32 v116, v116
	v_pk_add_f32 v[114:115], v[114:115], v[122:123] neg_lo:[0,1] neg_hi:[0,1]
	v_add_f32_e32 v116, 1.0, v116
	v_cmp_gt_f32_e32 vcc, s94, v116
	s_nop 1
	v_cndmask_b32_e64 v125, 0, 32, vcc
	v_ldexp_f32 v116, v116, v125
	v_log_f32_e32 v116, v116
	s_nop 0
	v_mul_f32_e32 v125, 0x3f317217, v116
	v_fma_f32 v125, v116, s96, -v125
	v_fmac_f32_e32 v125, 0x3377d1cf, v116
	v_fmac_f32_e32 v125, 0x3f317217, v116
	v_cmp_lt_f32_e64 s[10:11], |v116|, s97
	s_nop 1
	v_cndmask_b32_e64 v116, v116, v125, s[10:11]
	v_cndmask_b32_e32 v125, 0, v189, vcc
	v_sub_f32_e32 v116, v116, v125
	v_min_f32_e32 v125, 0, v117
	v_mul_f32_e64 v117, |v117|, s95
	v_exp_f32_e32 v117, v117
	s_nop 0
	v_add_f32_e32 v117, 1.0, v117
	v_cmp_gt_f32_e32 vcc, s94, v117
	s_nop 1
	v_cndmask_b32_e64 v127, 0, 32, vcc
	v_ldexp_f32 v117, v117, v127
	v_log_f32_e32 v117, v117
	s_nop 0
	v_mul_f32_e32 v127, 0x3f317217, v117
	v_fma_f32 v127, v117, s96, -v127
	v_fmac_f32_e32 v127, 0x3377d1cf, v117
	v_fmac_f32_e32 v127, 0x3f317217, v117
	v_cmp_lt_f32_e64 s[10:11], |v117|, s97
	s_nop 1
	v_cndmask_b32_e64 v117, v117, v127, s[10:11]
	v_cndmask_b32_e32 v127, 0, v189, vcc
	v_sub_f32_e32 v117, v117, v127
	v_pk_add_f32 v[116:117], v[124:125], v[116:117] neg_lo:[0,1] neg_hi:[0,1]
	global_store_dwordx4 v[120:121], v[114:117], off offset:16

; __device__ __forceinline__ unsigned pk(float lo, float hi) { return pg8::cvt_pk_bf16(lo, hi); }
; __device__ __forceinline__ float log_sigmoid(float z) { return fminf(z, 0.f) - __logf(1.f + __expf(-fabsf(z))); }
;     __device__ __forceinline__ void operator()(const pg8::f32x4 (&acc)[2][2][4][2], const pg8::Unit& u, int wr, int wc, int fr, int fq) const {
;     ...
;                 const int row = row0 + ai * 128 + m * 16; const float rs = rsqrtf(ss[row] * (1.f / DM) + EPS);
;                 if (u.pn < 12) {
;                     const float sc = (sect == 0) ? rs * QSCALE2 : rs;
;                     float* fdst = nullptr;
;                     if (sect == 1) fdst = (row < MP) ? out + O_FKP + (size_t)row * DM : out + O_FKS + (size_t)(row - MP) * DM;
;                     if (sect == 2) fdst = (row < MP) ? out + O_FVP + (size_t)row * DM : out + O_FVS + (size_t)(row - MP) * DM;
; #pragma unroll
;                     for (int bj = 0; bj < 2; ++bj) { const f32x4 v0 = acc[ai][bj][m][0] * sc, v1 = acc[ai][bj][m][1] * sc;
;                         u32x4 w; w.x = pk(v0[0], v0[1]); w.y = pk(v0[2], v0[3]); w.z = pk(v1[0], v1[1]); w.w = pk(v1[2], v1[3]);
;                         const int cl = bj * 128 + wc * 32 + 8 * fq;
;                         *(u32x4*)(qkv + (size_t)row * NPJ + u.pn * 256 + cl) = w;
;                         if (sect > 0) { float* d = fdst + (u.pn & 3) * 256 + cl; __builtin_nontemporal_store(v0, (f32x4*)d); __builtin_nontemporal_store(v1, (f32x4*)(d + 4)); } }
;                 } else if (wc == 0 && fq < 2) {
;                     float* d = (row < MP) ? out + O_FLP + (size_t)row * 16 : out + O_FLS + (size_t)(row - MP) * 16;
; #pragma unroll
;                     for (int n = 0; n < 2; ++n) { const f32x4 v = acc[ai][0][m][n] * rs; f32x4 o;
; #pragma unroll
;                         for (int i = 0; i < 4; ++i) o[i] = log_sigmoid(v[i] + bf[8 * fq + 4 * n + i]);
;                         *(f32x4*)(d + 8 * fq + 4 * n) = o; }
.LBB0_1366:
	s_nop 0
	v_or_b32_e32 v102, 32, v158
	v_ashrrev_i32_e32 v103, 31, v102
	v_lshl_add_u64 v[98:99], v[102:103], 2, s[40:41]
	s_nop 0
	s_and_b64 vcc, exec, s[8:9]
	v_mov_b32_e32 v98, v193
	v_fmamk_f32 v98, v98, 0x3a800000, v186
	v_mul_f32_e32 v99, 0x4b800000, v98
	v_cmp_gt_f32_e64 s[10:11], s94, v98
	s_nop 1
	v_cndmask_b32_e64 v98, v98, v99, s[10:11]
	v_rsq_f32_e32 v98, v98
	s_nop 0
	v_mul_f32_e32 v99, 0x45800000, v98
	v_cndmask_b32_e64 v110, v98, v99, s[10:11]
	s_mov_b64 s[10:11], -1
	s_cbranch_vccnz .LBB0_1370
	s_and_saveexec_b64 s[80:81], s[48:49]
	s_cbranch_execz .LBB0_1369
	v_cmp_gt_i32_e32 vcc, s86, v102
	v_add_u32_e32 v98, 0xffffc020, v158
	v_readlane_b32 s52, v252, 0
	v_cndmask_b32_e32 v99, 0, v103, vcc
	v_cndmask_b32_e32 v98, v98, v102, vcc
	v_cndmask_b32_e32 v142, v187, v188, vcc
	v_readlane_b32 s58, v252, 6
	v_readlane_b32 s59, v252, 7
	v_lshlrev_b64 v[98:99], 6, v[98:99]
	v_readlane_b32 s53, v252, 1
	v_lshl_add_u64 v[100:101], s[58:59], 0, v[142:143]
	v_lshl_add_u64 v[98:99], v[100:101], 0, v[98:99]
	v_lshlrev_b32_e32 v142, 2, v144
	v_lshl_add_u64 v[104:105], v[98:99], 0, v[142:143]
	global_load_dwordx4 v[98:101], v[148:149], off
	v_readlane_b32 s54, v252, 2
	v_readlane_b32 s55, v252, 3
	v_readlane_b32 s56, v252, 4
	v_readlane_b32 s57, v252, 5
	s_waitcnt vmcnt(0)
	v_fma_f32 v106, v94, v110, v98
	v_min_f32_e32 v98, 0, v106
	v_mul_f32_e64 v106, |v106|, s95
	v_exp_f32_e32 v106, v106
	v_fma_f32 v100, v96, v110, v100
	v_fmac_f32_e32 v101, v97, v110
	v_add_f32_e32 v106, 1.0, v106
	v_cmp_gt_f32_e32 vcc, s94, v106
	s_nop 1
	v_cndmask_b32_e64 v107, 0, 32, vcc
	v_ldexp_f32 v106, v106, v107
	v_log_f32_e32 v106, v106
	s_nop 0
	v_mul_f32_e32 v107, 0x3f317217, v106
	v_fma_f32 v107, v106, s96, -v107
	v_fmac_f32_e32 v107, 0x3377d1cf, v106
	v_fmac_f32_e32 v107, 0x3f317217, v106
	v_cmp_lt_f32_e64 s[10:11], |v106|, s97
	s_nop 1
	v_cndmask_b32_e64 v106, v106, v107, s[10:11]
	v_cndmask_b32_e32 v107, 0, v189, vcc
	v_sub_f32_e32 v106, v106, v107
	v_fma_f32 v107, v95, v110, v99
	v_min_f32_e32 v99, 0, v107
	v_mul_f32_e64 v107, |v107|, s95
	v_exp_f32_e32 v107, v107
	s_nop 0
	v_add_f32_e32 v107, 1.0, v107
	v_cmp_gt_f32_e32 vcc, s94, v107
	s_nop 1
	v_cndmask_b32_e64 v108, 0, 32, vcc
	v_ldexp_f32 v107, v107, v108
	v_log_f32_e32 v107, v107
	s_nop 0
	v_mul_f32_e32 v108, 0x3f317217, v107
	v_fma_f32 v108, v107, s96, -v108
	v_fmac_f32_e32 v108, 0x3377d1cf, v107
	v_fmac_f32_e32 v108, 0x3f317217, v107
	v_cmp_lt_f32_e64 s[10:11], |v107|, s97
	s_nop 1
	v_cndmask_b32_e64 v107, v107, v108, s[10:11]
	v_cndmask_b32_e32 v108, 0, v189, vcc
	v_sub_f32_e32 v107, v107, v108
	v_min_f32_e32 v108, 0, v100
	v_mul_f32_e64 v100, |v100|, s95
	v_exp_f32_e32 v100, v100
	v_pk_add_f32 v[98:99], v[98:99], v[106:107] neg_lo:[0,1] neg_hi:[0,1]
	v_add_f32_e32 v100, 1.0, v100
	v_cmp_gt_f32_e32 vcc, s94, v100
	s_nop 1
	v_cndmask_b32_e64 v109, 0, 32, vcc
	v_ldexp_f32 v100, v100, v109
	v_log_f32_e32 v100, v100
	s_nop 0
	v_mul_f32_e32 v109, 0x3f317217, v100
	v_fma_f32 v109, v100, s96, -v109
	v_fmac_f32_e32 v109, 0x3377d1cf, v100
	v_fmac_f32_e32 v109, 0x3f317217, v100
	v_cmp_lt_f32_e64 s[10:11], |v100|, s97
	s_nop 1
	v_cndmask_b32_e64 v100, v100, v109, s[10:11]
	v_cndmask_b32_e32 v109, 0, v189, vcc
	v_sub_f32_e32 v100, v100, v109
	v_min_f32_e32 v109, 0, v101
	v_mul_f32_e64 v101, |v101|, s95
	v_exp_f32_e32 v101, v101
	s_nop 0
	v_add_f32_e32 v101, 1.0, v101
	v_cmp_gt_f32_e32 vcc, s94, v101
	s_nop 1
	v_cndmask_b32_e64 v111, 0, 32, vcc
	v_ldexp_f32 v101, v101, v111
	v_log_f32_e32 v101, v101
	s_nop 0
	v_mul_f32_e32 v111, 0x3f317217, v101
	v_fma_f32 v111, v101, s96, -v111
	v_fmac_f32_e32 v111, 0x3377d1cf, v101
	v_fmac_f32_e32 v111, 0x3f317217, v101
	v_cmp_lt_f32_e64 s[10:11], |v101|, s97
	s_nop 1
	v_cndmask_b32_e64 v101, v101, v111, s[10:11]
	v_cndmask_b32_e32 v111, 0, v189, vcc
	v_sub_f32_e32 v101, v101, v111
	v_pk_add_f32 v[100:101], v[108:109], v[100:101] neg_lo:[0,1] neg_hi:[0,1]
	global_store_dwordx4 v[104:105], v[98:101], off
	global_load_dwordx4 v[98:101], v[148:149], off offset:16
	s_waitcnt vmcnt(0)
	v_fma_f32 v106, v90, v110, v98
	v_min_f32_e32 v98, 0, v106
	v_mul_f32_e64 v106, |v106|, s95
	v_exp_f32_e32 v106, v106
	v_fma_f32 v100, v92, v110, v100
	v_fmac_f32_e32 v101, v93, v110
	v_add_f32_e32 v106, 1.0, v106
	v_cmp_gt_f32_e32 vcc, s94, v106
	s_nop 1
	v_cndmask_b32_e64 v107, 0, 32, vcc
	v_ldexp_f32 v106, v106, v107
	v_log_f32_e32 v106, v106
	s_nop 0
	v_mul_f32_e32 v107, 0x3f317217, v106
	v_fma_f32 v107, v106, s96, -v107
	v_fmac_f32_e32 v107, 0x3377d1cf, v106
	v_fmac_f32_e32 v107, 0x3f317217, v106
	v_cmp_lt_f32_e64 s[10:11], |v106|, s97
	s_nop 1
	v_cndmask_b32_e64 v106, v106, v107, s[10:11]
	v_cndmask_b32_e32 v107, 0, v189, vcc
	v_sub_f32_e32 v106, v106, v107
	v_fma_f32 v107, v91, v110, v99
	v_min_f32_e32 v99, 0, v107
	v_mul_f32_e64 v107, |v107|, s95
	v_exp_f32_e32 v107, v107
	s_nop 0
	v_add_f32_e32 v107, 1.0, v107
	v_cmp_gt_f32_e32 vcc, s94, v107
	s_nop 1
	v_cndmask_b32_e64 v108, 0, 32, vcc
	v_ldexp_f32 v107, v107, v108
	v_log_f32_e32 v107, v107
	s_nop 0
	v_mul_f32_e32 v108, 0x3f317217, v107
	v_fma_f32 v108, v107, s96, -v108
	v_fmac_f32_e32 v108, 0x3377d1cf, v107
	v_fmac_f32_e32 v108, 0x3f317217, v107
	v_cmp_lt_f32_e64 s[10:11], |v107|, s97
	s_nop 1
	v_cndmask_b32_e64 v107, v107, v108, s[10:11]
	v_cndmask_b32_e32 v108, 0, v189, vcc
	v_sub_f32_e32 v107, v107, v108
	v_min_f32_e32 v108, 0, v100
	v_mul_f32_e64 v100, |v100|, s95
	v_exp_f32_e32 v100, v100
	v_pk_add_f32 v[98:99], v[98:99], v[106:107] neg_lo:[0,1] neg_hi:[0,1]
	v_add_f32_e32 v100, 1.0, v100
	v_cmp_gt_f32_e32 vcc, s94, v100
	s_nop 1
	v_cndmask_b32_e64 v109, 0, 32, vcc
	v_ldexp_f32 v100, v100, v109
	v_log_f32_e32 v100, v100
	s_nop 0
	v_mul_f32_e32 v109, 0x3f317217, v100
	v_fma_f32 v109, v100, s96, -v109
	v_fmac_f32_e32 v109, 0x3377d1cf, v100
	v_fmac_f32_e32 v109, 0x3f317217, v100
	v_cmp_lt_f32_e64 s[10:11], |v100|, s97
	s_nop 1
	v_cndmask_b32_e64 v100, v100, v109, s[10:11]
	v_cndmask_b32_e32 v109, 0, v189, vcc
	v_sub_f32_e32 v100, v100, v109
	v_min_f32_e32 v109, 0, v101
	v_mul_f32_e64 v101, |v101|, s95
	v_exp_f32_e32 v101, v101
	s_nop 0
	v_add_f32_e32 v101, 1.0, v101
	v_cmp_gt_f32_e32 vcc, s94, v101
	s_nop 1
	v_cndmask_b32_e64 v111, 0, 32, vcc
	v_ldexp_f32 v101, v101, v111
	v_log_f32_e32 v101, v101
	s_nop 0
	v_mul_f32_e32 v111, 0x3f317217, v101
	v_fma_f32 v111, v101, s96, -v111
	v_fmac_f32_e32 v111, 0x3377d1cf, v101
	v_fmac_f32_e32 v111, 0x3f317217, v101
	v_cmp_lt_f32_e64 s[10:11], |v101|, s97
	s_nop 1
	v_cndmask_b32_e64 v101, v101, v111, s[10:11]
	v_cndmask_b32_e32 v111, 0, v189, vcc
	v_sub_f32_e32 v101, v101, v111
	v_pk_add_f32 v[100:101], v[108:109], v[100:101] neg_lo:[0,1] neg_hi:[0,1]
	global_store_dwordx4 v[104:105], v[98:101], off offset:16

; __device__ __forceinline__ unsigned pk(float lo, float hi) { return pg8::cvt_pk_bf16(lo, hi); }
; __device__ __forceinline__ float log_sigmoid(float z) { return fminf(z, 0.f) - __logf(1.f + __expf(-fabsf(z))); }
;     __device__ __forceinline__ void operator()(const pg8::f32x4 (&acc)[2][2][4][2], const pg8::Unit& u, int wr, int wc, int fr, int fq) const {
;     ...
;                 const int row = row0 + ai * 128 + m * 16; const float rs = rsqrtf(ss[row] * (1.f / DM) + EPS);
;                 if (u.pn < 12) {
;                     const float sc = (sect == 0) ? rs * QSCALE2 : rs;
;                     float* fdst = nullptr;
;                     if (sect == 1) fdst = (row < MP) ? out + O_FKP + (size_t)row * DM : out + O_FKS + (size_t)(row - MP) * DM;
;                     if (sect == 2) fdst = (row < MP) ? out + O_FVP + (size_t)row * DM : out + O_FVS + (size_t)(row - MP) * DM;
; #pragma unroll
;                     for (int bj = 0; bj < 2; ++bj) { const f32x4 v0 = acc[ai][bj][m][0] * sc, v1 = acc[ai][bj][m][1] * sc;
;                         u32x4 w; w.x = pk(v0[0], v0[1]); w.y = pk(v0[2], v0[3]); w.z = pk(v1[0], v1[1]); w.w = pk(v1[2], v1[3]);
;                         const int cl = bj * 128 + wc * 32 + 8 * fq;
;                         *(u32x4*)(qkv + (size_t)row * NPJ + u.pn * 256 + cl) = w;
;                         if (sect > 0) { float* d = fdst + (u.pn & 3) * 256 + cl; __builtin_nontemporal_store(v0, (f32x4*)d); __builtin_nontemporal_store(v1, (f32x4*)(d + 4)); } }
;                 } else if (wc == 0 && fq < 2) {
;                     float* d = (row < MP) ? out + O_FLP + (size_t)row * 16 : out + O_FLS + (size_t)(row - MP) * 16;
; #pragma unroll
;                     for (int n = 0; n < 2; ++n) { const f32x4 v = acc[ai][0][m][n] * rs; f32x4 o;
; #pragma unroll
;                         for (int i = 0; i < 4; ++i) o[i] = log_sigmoid(v[i] + bf[8 * fq + 4 * n + i]);
;                         *(f32x4*)(d + 8 * fq + 4 * n) = o; }
.LBB0_1387:
	s_nop 0
	v_or_b32_e32 v86, 48, v158
	v_ashrrev_i32_e32 v87, 31, v86
	v_lshl_add_u64 v[82:83], v[86:87], 2, s[40:41]
	s_nop 0
	s_and_b64 vcc, exec, s[8:9]
	v_mov_b32_e32 v82, v194
	v_fmamk_f32 v82, v82, 0x3a800000, v186
	v_mul_f32_e32 v83, 0x4b800000, v82
	v_cmp_gt_f32_e64 s[10:11], s94, v82
	s_nop 1
	v_cndmask_b32_e64 v82, v82, v83, s[10:11]
	v_rsq_f32_e32 v82, v82
	s_nop 0
	v_mul_f32_e32 v83, 0x45800000, v82
	v_cndmask_b32_e64 v94, v82, v83, s[10:11]
	s_mov_b64 s[10:11], -1
	s_cbranch_vccnz .LBB0_1391
	s_and_saveexec_b64 s[80:81], s[48:49]
	s_cbranch_execz .LBB0_1390
	v_cmp_gt_i32_e32 vcc, s86, v86
	v_add_u32_e32 v82, 0xffffc030, v158
	v_readlane_b32 s52, v252, 0
	v_cndmask_b32_e32 v83, 0, v87, vcc
	v_cndmask_b32_e32 v82, v82, v86, vcc
	v_cndmask_b32_e32 v142, v187, v188, vcc
	v_readlane_b32 s58, v252, 6
	v_readlane_b32 s59, v252, 7
	v_lshlrev_b64 v[82:83], 6, v[82:83]
	v_readlane_b32 s53, v252, 1
	v_lshl_add_u64 v[84:85], s[58:59], 0, v[142:143]
	v_lshl_add_u64 v[82:83], v[84:85], 0, v[82:83]
	v_lshlrev_b32_e32 v142, 2, v144
	v_lshl_add_u64 v[88:89], v[82:83], 0, v[142:143]
	global_load_dwordx4 v[82:85], v[148:149], off
	v_readlane_b32 s54, v252, 2
	v_readlane_b32 s55, v252, 3
	v_readlane_b32 s56, v252, 4
	v_readlane_b32 s57, v252, 5
	s_waitcnt vmcnt(0)
	v_fma_f32 v90, v78, v94, v82
	v_min_f32_e32 v82, 0, v90
	v_mul_f32_e64 v90, |v90|, s95
	v_exp_f32_e32 v90, v90
	v_fma_f32 v84, v80, v94, v84
	v_fmac_f32_e32 v85, v81, v94
	v_add_f32_e32 v90, 1.0, v90
	v_cmp_gt_f32_e32 vcc, s94, v90
	s_nop 1
	v_cndmask_b32_e64 v91, 0, 32, vcc
	v_ldexp_f32 v90, v90, v91
	v_log_f32_e32 v90, v90
	s_nop 0
	v_mul_f32_e32 v91, 0x3f317217, v90
	v_fma_f32 v91, v90, s96, -v91
	v_fmac_f32_e32 v91, 0x3377d1cf, v90
	v_fmac_f32_e32 v91, 0x3f317217, v90
	v_cmp_lt_f32_e64 s[10:11], |v90|, s97
	s_nop 1
	v_cndmask_b32_e64 v90, v90, v91, s[10:11]
	v_cndmask_b32_e32 v91, 0, v189, vcc
	v_sub_f32_e32 v90, v90, v91
	v_fma_f32 v91, v79, v94, v83
	v_min_f32_e32 v83, 0, v91
	v_mul_f32_e64 v91, |v91|, s95
	v_exp_f32_e32 v91, v91
	s_nop 0
	v_add_f32_e32 v91, 1.0, v91
	v_cmp_gt_f32_e32 vcc, s94, v91
	s_nop 1
	v_cndmask_b32_e64 v92, 0, 32, vcc
	v_ldexp_f32 v91, v91, v92
	v_log_f32_e32 v91, v91
	s_nop 0
	v_mul_f32_e32 v92, 0x3f317217, v91
	v_fma_f32 v92, v91, s96, -v92
	v_fmac_f32_e32 v92, 0x3377d1cf, v91
	v_fmac_f32_e32 v92, 0x3f317217, v91
	v_cmp_lt_f32_e64 s[10:11], |v91|, s97
	s_nop 1
	v_cndmask_b32_e64 v91, v91, v92, s[10:11]
	v_cndmask_b32_e32 v92, 0, v189, vcc
	v_sub_f32_e32 v91, v91, v92
	v_min_f32_e32 v92, 0, v84
	v_mul_f32_e64 v84, |v84|, s95
	v_exp_f32_e32 v84, v84
	v_pk_add_f32 v[82:83], v[82:83], v[90:91] neg_lo:[0,1] neg_hi:[0,1]
	v_add_f32_e32 v84, 1.0, v84
	v_cmp_gt_f32_e32 vcc, s94, v84
	s_nop 1
	v_cndmask_b32_e64 v93, 0, 32, vcc
	v_ldexp_f32 v84, v84, v93
	v_log_f32_e32 v84, v84
	s_nop 0
	v_mul_f32_e32 v93, 0x3f317217, v84
	v_fma_f32 v93, v84, s96, -v93
	v_fmac_f32_e32 v93, 0x3377d1cf, v84
	v_fmac_f32_e32 v93, 0x3f317217, v84
	v_cmp_lt_f32_e64 s[10:11], |v84|, s97
	s_nop 1
	v_cndmask_b32_e64 v84, v84, v93, s[10:11]
	v_cndmask_b32_e32 v93, 0, v189, vcc
	v_sub_f32_e32 v84, v84, v93
	v_min_f32_e32 v93, 0, v85
	v_mul_f32_e64 v85, |v85|, s95
	v_exp_f32_e32 v85, v85
	s_nop 0
	v_add_f32_e32 v85, 1.0, v85
	v_cmp_gt_f32_e32 vcc, s94, v85
	s_nop 1
	v_cndmask_b32_e64 v95, 0, 32, vcc
	v_ldexp_f32 v85, v85, v95
	v_log_f32_e32 v85, v85
	s_nop 0
	v_mul_f32_e32 v95, 0x3f317217, v85
	v_fma_f32 v95, v85, s96, -v95
	v_fmac_f32_e32 v95, 0x3377d1cf, v85
	v_fmac_f32_e32 v95, 0x3f317217, v85
	v_cmp_lt_f32_e64 s[10:11], |v85|, s97
	s_nop 1
	v_cndmask_b32_e64 v85, v85, v95, s[10:11]
	v_cndmask_b32_e32 v95, 0, v189, vcc
	v_sub_f32_e32 v85, v85, v95
	v_pk_add_f32 v[84:85], v[92:93], v[84:85] neg_lo:[0,1] neg_hi:[0,1]
	global_store_dwordx4 v[88:89], v[82:85], off
	global_load_dwordx4 v[82:85], v[148:149], off offset:16
	s_waitcnt vmcnt(0)
	v_fma_f32 v90, v74, v94, v82
	v_min_f32_e32 v82, 0, v90
	v_mul_f32_e64 v90, |v90|, s95
	v_exp_f32_e32 v90, v90
	v_fma_f32 v84, v76, v94, v84
	v_fmac_f32_e32 v85, v77, v94
	v_add_f32_e32 v90, 1.0, v90
	v_cmp_gt_f32_e32 vcc, s94, v90
	s_nop 1
	v_cndmask_b32_e64 v91, 0, 32, vcc
	v_ldexp_f32 v90, v90, v91
	v_log_f32_e32 v90, v90
	s_nop 0
	v_mul_f32_e32 v91, 0x3f317217, v90
	v_fma_f32 v91, v90, s96, -v91
	v_fmac_f32_e32 v91, 0x3377d1cf, v90
	v_fmac_f32_e32 v91, 0x3f317217, v90
	v_cmp_lt_f32_e64 s[10:11], |v90|, s97
	s_nop 1
	v_cndmask_b32_e64 v90, v90, v91, s[10:11]
	v_cndmask_b32_e32 v91, 0, v189, vcc
	v_sub_f32_e32 v90, v90, v91
	v_fma_f32 v91, v75, v94, v83
	v_min_f32_e32 v83, 0, v91
	v_mul_f32_e64 v91, |v91|, s95
	v_exp_f32_e32 v91, v91
	s_nop 0
	v_add_f32_e32 v91, 1.0, v91
	v_cmp_gt_f32_e32 vcc, s94, v91
	s_nop 1
	v_cndmask_b32_e64 v92, 0, 32, vcc
	v_ldexp_f32 v91, v91, v92
	v_log_f32_e32 v91, v91
	s_nop 0
	v_mul_f32_e32 v92, 0x3f317217, v91
	v_fma_f32 v92, v91, s96, -v92
	v_fmac_f32_e32 v92, 0x3377d1cf, v91
	v_fmac_f32_e32 v92, 0x3f317217, v91
	v_cmp_lt_f32_e64 s[10:11], |v91|, s97
	s_nop 1
	v_cndmask_b32_e64 v91, v91, v92, s[10:11]
	v_cndmask_b32_e32 v92, 0, v189, vcc
	v_sub_f32_e32 v91, v91, v92
	v_min_f32_e32 v92, 0, v84
	v_mul_f32_e64 v84, |v84|, s95
	v_exp_f32_e32 v84, v84
	v_pk_add_f32 v[82:83], v[82:83], v[90:91] neg_lo:[0,1] neg_hi:[0,1]
	v_add_f32_e32 v84, 1.0, v84
	v_cmp_gt_f32_e32 vcc, s94, v84
	s_nop 1
	v_cndmask_b32_e64 v93, 0, 32, vcc
	v_ldexp_f32 v84, v84, v93
	v_log_f32_e32 v84, v84
	s_nop 0
	v_mul_f32_e32 v93, 0x3f317217, v84
	v_fma_f32 v93, v84, s96, -v93
	v_fmac_f32_e32 v93, 0x3377d1cf, v84
	v_fmac_f32_e32 v93, 0x3f317217, v84
	v_cmp_lt_f32_e64 s[10:11], |v84|, s97
	s_nop 1
	v_cndmask_b32_e64 v84, v84, v93, s[10:11]
	v_cndmask_b32_e32 v93, 0, v189, vcc
	v_sub_f32_e32 v84, v84, v93
	v_min_f32_e32 v93, 0, v85
	v_mul_f32_e64 v85, |v85|, s95
	v_exp_f32_e32 v85, v85
	s_nop 0
	v_add_f32_e32 v85, 1.0, v85
	v_cmp_gt_f32_e32 vcc, s94, v85
	s_nop 1
	v_cndmask_b32_e64 v95, 0, 32, vcc
	v_ldexp_f32 v85, v85, v95
	v_log_f32_e32 v85, v85
	s_nop 0
	v_mul_f32_e32 v95, 0x3f317217, v85
	v_fma_f32 v95, v85, s96, -v95
	v_fmac_f32_e32 v95, 0x3377d1cf, v85
	v_fmac_f32_e32 v95, 0x3f317217, v85
	v_cmp_lt_f32_e64 s[10:11], |v85|, s97
	s_nop 1
	v_cndmask_b32_e64 v85, v85, v95, s[10:11]
	v_cndmask_b32_e32 v95, 0, v189, vcc
	v_sub_f32_e32 v85, v85, v95
	v_pk_add_f32 v[84:85], v[92:93], v[84:85] neg_lo:[0,1] neg_hi:[0,1]
	global_store_dwordx4 v[88:89], v[82:85], off offset:16

; __device__ __forceinline__ unsigned pk(float lo, float hi) { return pg8::cvt_pk_bf16(lo, hi); }
; __device__ __forceinline__ float log_sigmoid(float z) { return fminf(z, 0.f) - __logf(1.f + __expf(-fabsf(z))); }
;     __device__ __forceinline__ void operator()(const pg8::f32x4 (&acc)[2][2][4][2], const pg8::Unit& u, int wr, int wc, int fr, int fq) const {
;     ...
;                 const int row = row0 + ai * 128 + m * 16; const float rs = rsqrtf(ss[row] * (1.f / DM) + EPS);
;                 if (u.pn < 12) {
;                     const float sc = (sect == 0) ? rs * QSCALE2 : rs;
;                     float* fdst = nullptr;
;                     if (sect == 1) fdst = (row < MP) ? out + O_FKP + (size_t)row * DM : out + O_FKS + (size_t)(row - MP) * DM;
;                     if (sect == 2) fdst = (row < MP) ? out + O_FVP + (size_t)row * DM : out + O_FVS + (size_t)(row - MP) * DM;
; #pragma unroll
;                     for (int bj = 0; bj < 2; ++bj) { const f32x4 v0 = acc[ai][bj][m][0] * sc, v1 = acc[ai][bj][m][1] * sc;
;                         u32x4 w; w.x = pk(v0[0], v0[1]); w.y = pk(v0[2], v0[3]); w.z = pk(v1[0], v1[1]); w.w = pk(v1[2], v1[3]);
;                         const int cl = bj * 128 + wc * 32 + 8 * fq;
;                         *(u32x4*)(qkv + (size_t)row * NPJ + u.pn * 256 + cl) = w;
;                         if (sect > 0) { float* d = fdst + (u.pn & 3) * 256 + cl; __builtin_nontemporal_store(v0, (f32x4*)d); __builtin_nontemporal_store(v1, (f32x4*)(d + 4)); } }
;                 } else if (wc == 0 && fq < 2) {
;                     float* d = (row < MP) ? out + O_FLP + (size_t)row * 16 : out + O_FLS + (size_t)(row - MP) * 16;
; #pragma unroll
;                     for (int n = 0; n < 2; ++n) { const f32x4 v = acc[ai][0][m][n] * rs; f32x4 o;
; #pragma unroll
;                         for (int i = 0; i < 4; ++i) o[i] = log_sigmoid(v[i] + bf[8 * fq + 4 * n + i]);
;                         *(f32x4*)(d + 8 * fq + 4 * n) = o; }
.LBB0_1408:
	s_nop 0
	v_add_u32_e32 v70, 0x80, v158
	s_and_b64 vcc, exec, s[8:9]
	v_ashrrev_i32_e32 v71, 31, v70
	v_mov_b32_e32 v66, v195
	v_fmamk_f32 v66, v66, 0x3a800000, v186
	v_mul_f32_e32 v67, 0x4b800000, v66
	v_cmp_gt_f32_e64 s[10:11], s94, v66
	s_nop 1
	v_cndmask_b32_e64 v66, v66, v67, s[10:11]
	v_rsq_f32_e32 v66, v66
	s_nop 0
	v_mul_f32_e32 v67, 0x45800000, v66
	v_cndmask_b32_e64 v78, v66, v67, s[10:11]
	s_mov_b64 s[10:11], -1
	s_cbranch_vccnz .LBB0_1412
	s_and_saveexec_b64 s[80:81], s[48:49]
	s_cbranch_execz .LBB0_1411
	s_movk_i32 s10, 0x3f80
	v_cmp_gt_i32_e32 vcc, s10, v158
	v_add_u32_e32 v66, 0xffffc080, v158
	v_readlane_b32 s52, v252, 0
	v_cndmask_b32_e32 v67, 0, v71, vcc
	v_cndmask_b32_e32 v66, v66, v70, vcc
	v_cndmask_b32_e32 v142, v187, v188, vcc
	v_readlane_b32 s58, v252, 6
	v_readlane_b32 s59, v252, 7
	v_lshlrev_b64 v[66:67], 6, v[66:67]
	v_readlane_b32 s53, v252, 1
	v_lshl_add_u64 v[68:69], s[58:59], 0, v[142:143]
	v_lshl_add_u64 v[66:67], v[68:69], 0, v[66:67]
	v_lshlrev_b32_e32 v142, 2, v144
	v_lshl_add_u64 v[72:73], v[66:67], 0, v[142:143]
	global_load_dwordx4 v[66:69], v[148:149], off
	v_readlane_b32 s54, v252, 2
	v_readlane_b32 s55, v252, 3
	v_readlane_b32 s56, v252, 4
	v_readlane_b32 s57, v252, 5
	s_waitcnt vmcnt(0)
	v_fma_f32 v74, v62, v78, v66
	v_min_f32_e32 v66, 0, v74
	v_mul_f32_e64 v74, |v74|, s95
	v_exp_f32_e32 v74, v74
	v_fma_f32 v68, v64, v78, v68
	v_fmac_f32_e32 v69, v65, v78
	v_add_f32_e32 v74, 1.0, v74
	v_cmp_gt_f32_e32 vcc, s94, v74
	s_nop 1
	v_cndmask_b32_e64 v75, 0, 32, vcc
	v_ldexp_f32 v74, v74, v75
	v_log_f32_e32 v74, v74
	s_nop 0
	v_mul_f32_e32 v75, 0x3f317217, v74
	v_fma_f32 v75, v74, s96, -v75
	v_fmac_f32_e32 v75, 0x3377d1cf, v74
	v_fmac_f32_e32 v75, 0x3f317217, v74
	v_cmp_lt_f32_e64 s[10:11], |v74|, s97
	s_nop 1
	v_cndmask_b32_e64 v74, v74, v75, s[10:11]
	v_cndmask_b32_e32 v75, 0, v189, vcc
	v_sub_f32_e32 v74, v74, v75
	v_fma_f32 v75, v63, v78, v67
	v_min_f32_e32 v67, 0, v75
	v_mul_f32_e64 v75, |v75|, s95
	v_exp_f32_e32 v75, v75
	s_nop 0
	v_add_f32_e32 v75, 1.0, v75
	v_cmp_gt_f32_e32 vcc, s94, v75
	s_nop 1
	v_cndmask_b32_e64 v76, 0, 32, vcc
	v_ldexp_f32 v75, v75, v76
	v_log_f32_e32 v75, v75
	s_nop 0
	v_mul_f32_e32 v76, 0x3f317217, v75
	v_fma_f32 v76, v75, s96, -v76
	v_fmac_f32_e32 v76, 0x3377d1cf, v75
	v_fmac_f32_e32 v76, 0x3f317217, v75
	v_cmp_lt_f32_e64 s[10:11], |v75|, s97
	s_nop 1
	v_cndmask_b32_e64 v75, v75, v76, s[10:11]
	v_cndmask_b32_e32 v76, 0, v189, vcc
	v_sub_f32_e32 v75, v75, v76
	v_min_f32_e32 v76, 0, v68
	v_mul_f32_e64 v68, |v68|, s95
	v_exp_f32_e32 v68, v68
	v_pk_add_f32 v[66:67], v[66:67], v[74:75] neg_lo:[0,1] neg_hi:[0,1]
	v_add_f32_e32 v68, 1.0, v68
	v_cmp_gt_f32_e32 vcc, s94, v68
	s_nop 1
	v_cndmask_b32_e64 v77, 0, 32, vcc
	v_ldexp_f32 v68, v68, v77
	v_log_f32_e32 v68, v68
	s_nop 0
	v_mul_f32_e32 v77, 0x3f317217, v68
	v_fma_f32 v77, v68, s96, -v77
	v_fmac_f32_e32 v77, 0x3377d1cf, v68
	v_fmac_f32_e32 v77, 0x3f317217, v68
	v_cmp_lt_f32_e64 s[10:11], |v68|, s97
	s_nop 1
	v_cndmask_b32_e64 v68, v68, v77, s[10:11]
	v_cndmask_b32_e32 v77, 0, v189, vcc
	v_sub_f32_e32 v68, v68, v77
	v_min_f32_e32 v77, 0, v69
	v_mul_f32_e64 v69, |v69|, s95
	v_exp_f32_e32 v69, v69
	s_nop 0
	v_add_f32_e32 v69, 1.0, v69
	v_cmp_gt_f32_e32 vcc, s94, v69
	s_nop 1
	v_cndmask_b32_e64 v79, 0, 32, vcc
	v_ldexp_f32 v69, v69, v79
	v_log_f32_e32 v69, v69
	s_nop 0
	v_mul_f32_e32 v79, 0x3f317217, v69
	v_fma_f32 v79, v69, s96, -v79
	v_fmac_f32_e32 v79, 0x3377d1cf, v69
	v_fmac_f32_e32 v79, 0x3f317217, v69
	v_cmp_lt_f32_e64 s[10:11], |v69|, s97
	s_nop 1
	v_cndmask_b32_e64 v69, v69, v79, s[10:11]
	v_cndmask_b32_e32 v79, 0, v189, vcc
	v_sub_f32_e32 v69, v69, v79
	v_pk_add_f32 v[68:69], v[76:77], v[68:69] neg_lo:[0,1] neg_hi:[0,1]
	global_store_dwordx4 v[72:73], v[66:69], off
	global_load_dwordx4 v[66:69], v[148:149], off offset:16
	s_waitcnt vmcnt(0)
	v_fma_f32 v74, v58, v78, v66
	v_min_f32_e32 v66, 0, v74
	v_mul_f32_e64 v74, |v74|, s95
	v_exp_f32_e32 v74, v74
	v_fma_f32 v68, v60, v78, v68
	v_fmac_f32_e32 v69, v61, v78
	v_add_f32_e32 v74, 1.0, v74
	v_cmp_gt_f32_e32 vcc, s94, v74
	s_nop 1
	v_cndmask_b32_e64 v75, 0, 32, vcc
	v_ldexp_f32 v74, v74, v75
	v_log_f32_e32 v74, v74
	s_nop 0
	v_mul_f32_e32 v75, 0x3f317217, v74
	v_fma_f32 v75, v74, s96, -v75
	v_fmac_f32_e32 v75, 0x3377d1cf, v74
	v_fmac_f32_e32 v75, 0x3f317217, v74
	v_cmp_lt_f32_e64 s[10:11], |v74|, s97
	s_nop 1
	v_cndmask_b32_e64 v74, v74, v75, s[10:11]
	v_cndmask_b32_e32 v75, 0, v189, vcc
	v_sub_f32_e32 v74, v74, v75
	v_fma_f32 v75, v59, v78, v67
	v_min_f32_e32 v67, 0, v75
	v_mul_f32_e64 v75, |v75|, s95
	v_exp_f32_e32 v75, v75
	s_nop 0
	v_add_f32_e32 v75, 1.0, v75
	v_cmp_gt_f32_e32 vcc, s94, v75
	s_nop 1
	v_cndmask_b32_e64 v76, 0, 32, vcc
	v_ldexp_f32 v75, v75, v76
	v_log_f32_e32 v75, v75
	s_nop 0
	v_mul_f32_e32 v76, 0x3f317217, v75
	v_fma_f32 v76, v75, s96, -v76
	v_fmac_f32_e32 v76, 0x3377d1cf, v75
	v_fmac_f32_e32 v76, 0x3f317217, v75
	v_cmp_lt_f32_e64 s[10:11], |v75|, s97
	s_nop 1
	v_cndmask_b32_e64 v75, v75, v76, s[10:11]
	v_cndmask_b32_e32 v76, 0, v189, vcc
	v_sub_f32_e32 v75, v75, v76
	v_min_f32_e32 v76, 0, v68
	v_mul_f32_e64 v68, |v68|, s95
	v_exp_f32_e32 v68, v68
	v_pk_add_f32 v[66:67], v[66:67], v[74:75] neg_lo:[0,1] neg_hi:[0,1]
	v_add_f32_e32 v68, 1.0, v68
	v_cmp_gt_f32_e32 vcc, s94, v68
	s_nop 1
	v_cndmask_b32_e64 v77, 0, 32, vcc
	v_ldexp_f32 v68, v68, v77
	v_log_f32_e32 v68, v68
	s_nop 0
	v_mul_f32_e32 v77, 0x3f317217, v68
	v_fma_f32 v77, v68, s96, -v77
	v_fmac_f32_e32 v77, 0x3377d1cf, v68
	v_fmac_f32_e32 v77, 0x3f317217, v68
	v_cmp_lt_f32_e64 s[10:11], |v68|, s97
	s_nop 1
	v_cndmask_b32_e64 v68, v68, v77, s[10:11]
	v_cndmask_b32_e32 v77, 0, v189, vcc
	v_sub_f32_e32 v68, v68, v77
	v_min_f32_e32 v77, 0, v69
	v_mul_f32_e64 v69, |v69|, s95
	v_exp_f32_e32 v69, v69
	s_nop 0
	v_add_f32_e32 v69, 1.0, v69
	v_cmp_gt_f32_e32 vcc, s94, v69
	s_nop 1
	v_cndmask_b32_e64 v79, 0, 32, vcc
	v_ldexp_f32 v69, v69, v79
	v_log_f32_e32 v69, v69
	s_nop 0
	v_mul_f32_e32 v79, 0x3f317217, v69
	v_fma_f32 v79, v69, s96, -v79
	v_fmac_f32_e32 v79, 0x3377d1cf, v69
	v_fmac_f32_e32 v79, 0x3f317217, v69
	v_cmp_lt_f32_e64 s[10:11], |v69|, s97
	s_nop 1
	v_cndmask_b32_e64 v69, v69, v79, s[10:11]
	v_cndmask_b32_e32 v79, 0, v189, vcc
	v_sub_f32_e32 v69, v69, v79
	v_pk_add_f32 v[68:69], v[76:77], v[68:69] neg_lo:[0,1] neg_hi:[0,1]
	global_store_dwordx4 v[72:73], v[66:69], off offset:16

; __device__ __forceinline__ unsigned pk(float lo, float hi) { return pg8::cvt_pk_bf16(lo, hi); }
; __device__ __forceinline__ float log_sigmoid(float z) { return fminf(z, 0.f) - __logf(1.f + __expf(-fabsf(z))); }
;     __device__ __forceinline__ void operator()(const pg8::f32x4 (&acc)[2][2][4][2], const pg8::Unit& u, int wr, int wc, int fr, int fq) const {
;     ...
;                 const int row = row0 + ai * 128 + m * 16; const float rs = rsqrtf(ss[row] * (1.f / DM) + EPS);
;                 if (u.pn < 12) {
;                     const float sc = (sect == 0) ? rs * QSCALE2 : rs;
;                     float* fdst = nullptr;
;                     if (sect == 1) fdst = (row < MP) ? out + O_FKP + (size_t)row * DM : out + O_FKS + (size_t)(row - MP) * DM;
;                     if (sect == 2) fdst = (row < MP) ? out + O_FVP + (size_t)row * DM : out + O_FVS + (size_t)(row - MP) * DM;
; #pragma unroll
;                     for (int bj = 0; bj < 2; ++bj) { const f32x4 v0 = acc[ai][bj][m][0] * sc, v1 = acc[ai][bj][m][1] * sc;
;                         u32x4 w; w.x = pk(v0[0], v0[1]); w.y = pk(v0[2], v0[3]); w.z = pk(v1[0], v1[1]); w.w = pk(v1[2], v1[3]);
;                         const int cl = bj * 128 + wc * 32 + 8 * fq;
;                         *(u32x4*)(qkv + (size_t)row * NPJ + u.pn * 256 + cl) = w;
;                         if (sect > 0) { float* d = fdst + (u.pn & 3) * 256 + cl; __builtin_nontemporal_store(v0, (f32x4*)d); __builtin_nontemporal_store(v1, (f32x4*)(d + 4)); } }
;                 } else if (wc == 0 && fq < 2) {
;                     float* d = (row < MP) ? out + O_FLP + (size_t)row * 16 : out + O_FLS + (size_t)(row - MP) * 16;
; #pragma unroll
;                     for (int n = 0; n < 2; ++n) { const f32x4 v = acc[ai][0][m][n] * rs; f32x4 o;
; #pragma unroll
;                         for (int i = 0; i < 4; ++i) o[i] = log_sigmoid(v[i] + bf[8 * fq + 4 * n + i]);
;                         *(f32x4*)(d + 8 * fq + 4 * n) = o; }
.LBB0_1429:
	s_nop 0
	v_add_u32_e32 v54, 0x90, v158
	s_and_b64 vcc, exec, s[8:9]
	v_ashrrev_i32_e32 v55, 31, v54
	v_mov_b32_e32 v50, v196
	v_fmamk_f32 v50, v50, 0x3a800000, v186
	v_mul_f32_e32 v51, 0x4b800000, v50
	v_cmp_gt_f32_e64 s[10:11], s94, v50
	s_nop 1
	v_cndmask_b32_e64 v50, v50, v51, s[10:11]
	v_rsq_f32_e32 v50, v50
	s_nop 0
	v_mul_f32_e32 v51, 0x45800000, v50
	v_cndmask_b32_e64 v62, v50, v51, s[10:11]
	s_mov_b64 s[10:11], -1
	s_cbranch_vccnz .LBB0_1433
	s_and_saveexec_b64 s[80:81], s[48:49]
	s_cbranch_execz .LBB0_1432
	s_movk_i32 s10, 0x3f70
	v_cmp_gt_i32_e32 vcc, s10, v158
	v_add_u32_e32 v50, 0xffffc090, v158
	v_readlane_b32 s52, v252, 0
	v_cndmask_b32_e32 v51, 0, v55, vcc
	v_cndmask_b32_e32 v50, v50, v54, vcc
	v_cndmask_b32_e32 v142, v187, v188, vcc
	v_readlane_b32 s58, v252, 6
	v_readlane_b32 s59, v252, 7
	v_lshlrev_b64 v[50:51], 6, v[50:51]
	v_readlane_b32 s53, v252, 1
	v_lshl_add_u64 v[52:53], s[58:59], 0, v[142:143]
	v_lshl_add_u64 v[50:51], v[52:53], 0, v[50:51]
	v_lshlrev_b32_e32 v142, 2, v144
	v_lshl_add_u64 v[56:57], v[50:51], 0, v[142:143]
	global_load_dwordx4 v[50:53], v[148:149], off
	v_readlane_b32 s54, v252, 2
	v_readlane_b32 s55, v252, 3
	v_readlane_b32 s56, v252, 4
	v_readlane_b32 s57, v252, 5
	s_waitcnt vmcnt(0)
	v_fma_f32 v58, v46, v62, v50
	v_min_f32_e32 v50, 0, v58
	v_mul_f32_e64 v58, |v58|, s95
	v_exp_f32_e32 v58, v58
	v_fma_f32 v52, v48, v62, v52
	v_fmac_f32_e32 v53, v49, v62
	v_add_f32_e32 v58, 1.0, v58
	v_cmp_gt_f32_e32 vcc, s94, v58
	s_nop 1
	v_cndmask_b32_e64 v59, 0, 32, vcc
	v_ldexp_f32 v58, v58, v59
	v_log_f32_e32 v58, v58
	s_nop 0
	v_mul_f32_e32 v59, 0x3f317217, v58
	v_fma_f32 v59, v58, s96, -v59
	v_fmac_f32_e32 v59, 0x3377d1cf, v58
	v_fmac_f32_e32 v59, 0x3f317217, v58
	v_cmp_lt_f32_e64 s[10:11], |v58|, s97
	s_nop 1
	v_cndmask_b32_e64 v58, v58, v59, s[10:11]
	v_cndmask_b32_e32 v59, 0, v189, vcc
	v_sub_f32_e32 v58, v58, v59
	v_fma_f32 v59, v47, v62, v51
	v_min_f32_e32 v51, 0, v59
	v_mul_f32_e64 v59, |v59|, s95
	v_exp_f32_e32 v59, v59
	s_nop 0
	v_add_f32_e32 v59, 1.0, v59
	v_cmp_gt_f32_e32 vcc, s94, v59
	s_nop 1
	v_cndmask_b32_e64 v60, 0, 32, vcc
	v_ldexp_f32 v59, v59, v60
	v_log_f32_e32 v59, v59
	s_nop 0
	v_mul_f32_e32 v60, 0x3f317217, v59
	v_fma_f32 v60, v59, s96, -v60
	v_fmac_f32_e32 v60, 0x3377d1cf, v59
	v_fmac_f32_e32 v60, 0x3f317217, v59
	v_cmp_lt_f32_e64 s[10:11], |v59|, s97
	s_nop 1
	v_cndmask_b32_e64 v59, v59, v60, s[10:11]
	v_cndmask_b32_e32 v60, 0, v189, vcc
	v_sub_f32_e32 v59, v59, v60
	v_min_f32_e32 v60, 0, v52
	v_mul_f32_e64 v52, |v52|, s95
	v_exp_f32_e32 v52, v52
	v_pk_add_f32 v[50:51], v[50:51], v[58:59] neg_lo:[0,1] neg_hi:[0,1]
	v_add_f32_e32 v52, 1.0, v52
	v_cmp_gt_f32_e32 vcc, s94, v52
	s_nop 1
	v_cndmask_b32_e64 v61, 0, 32, vcc
	v_ldexp_f32 v52, v52, v61
	v_log_f32_e32 v52, v52
	s_nop 0
	v_mul_f32_e32 v61, 0x3f317217, v52
	v_fma_f32 v61, v52, s96, -v61
	v_fmac_f32_e32 v61, 0x3377d1cf, v52
	v_fmac_f32_e32 v61, 0x3f317217, v52
	v_cmp_lt_f32_e64 s[10:11], |v52|, s97
	s_nop 1
	v_cndmask_b32_e64 v52, v52, v61, s[10:11]
	v_cndmask_b32_e32 v61, 0, v189, vcc
	v_sub_f32_e32 v52, v52, v61
	v_min_f32_e32 v61, 0, v53
	v_mul_f32_e64 v53, |v53|, s95
	v_exp_f32_e32 v53, v53
	s_nop 0
	v_add_f32_e32 v53, 1.0, v53
	v_cmp_gt_f32_e32 vcc, s94, v53
	s_nop 1
	v_cndmask_b32_e64 v63, 0, 32, vcc
	v_ldexp_f32 v53, v53, v63
	v_log_f32_e32 v53, v53
	s_nop 0
	v_mul_f32_e32 v63, 0x3f317217, v53
	v_fma_f32 v63, v53, s96, -v63
	v_fmac_f32_e32 v63, 0x3377d1cf, v53
	v_fmac_f32_e32 v63, 0x3f317217, v53
	v_cmp_lt_f32_e64 s[10:11], |v53|, s97
	s_nop 1
	v_cndmask_b32_e64 v53, v53, v63, s[10:11]
	v_cndmask_b32_e32 v63, 0, v189, vcc
	v_sub_f32_e32 v53, v53, v63
	v_pk_add_f32 v[52:53], v[60:61], v[52:53] neg_lo:[0,1] neg_hi:[0,1]
	global_store_dwordx4 v[56:57], v[50:53], off
	global_load_dwordx4 v[50:53], v[148:149], off offset:16
	s_waitcnt vmcnt(0)
	v_fma_f32 v58, v42, v62, v50
	v_min_f32_e32 v50, 0, v58
	v_mul_f32_e64 v58, |v58|, s95
	v_exp_f32_e32 v58, v58
	v_fma_f32 v52, v44, v62, v52
	v_fmac_f32_e32 v53, v45, v62
	v_add_f32_e32 v58, 1.0, v58
	v_cmp_gt_f32_e32 vcc, s94, v58
	s_nop 1
	v_cndmask_b32_e64 v59, 0, 32, vcc
	v_ldexp_f32 v58, v58, v59
	v_log_f32_e32 v58, v58
	s_nop 0
	v_mul_f32_e32 v59, 0x3f317217, v58
	v_fma_f32 v59, v58, s96, -v59
	v_fmac_f32_e32 v59, 0x3377d1cf, v58
	v_fmac_f32_e32 v59, 0x3f317217, v58
	v_cmp_lt_f32_e64 s[10:11], |v58|, s97
	s_nop 1
	v_cndmask_b32_e64 v58, v58, v59, s[10:11]
	v_cndmask_b32_e32 v59, 0, v189, vcc
	v_sub_f32_e32 v58, v58, v59
	v_fma_f32 v59, v43, v62, v51
	v_min_f32_e32 v51, 0, v59
	v_mul_f32_e64 v59, |v59|, s95
	v_exp_f32_e32 v59, v59
	s_nop 0
	v_add_f32_e32 v59, 1.0, v59
	v_cmp_gt_f32_e32 vcc, s94, v59
	s_nop 1
	v_cndmask_b32_e64 v60, 0, 32, vcc
	v_ldexp_f32 v59, v59, v60
	v_log_f32_e32 v59, v59
	s_nop 0
	v_mul_f32_e32 v60, 0x3f317217, v59
	v_fma_f32 v60, v59, s96, -v60
	v_fmac_f32_e32 v60, 0x3377d1cf, v59
	v_fmac_f32_e32 v60, 0x3f317217, v59
	v_cmp_lt_f32_e64 s[10:11], |v59|, s97
	s_nop 1
	v_cndmask_b32_e64 v59, v59, v60, s[10:11]
	v_cndmask_b32_e32 v60, 0, v189, vcc
	v_sub_f32_e32 v59, v59, v60
	v_min_f32_e32 v60, 0, v52
	v_mul_f32_e64 v52, |v52|, s95
	v_exp_f32_e32 v52, v52
	v_pk_add_f32 v[50:51], v[50:51], v[58:59] neg_lo:[0,1] neg_hi:[0,1]
	v_add_f32_e32 v52, 1.0, v52
	v_cmp_gt_f32_e32 vcc, s94, v52
	s_nop 1
	v_cndmask_b32_e64 v61, 0, 32, vcc
	v_ldexp_f32 v52, v52, v61
	v_log_f32_e32 v52, v52
	s_nop 0
	v_mul_f32_e32 v61, 0x3f317217, v52
	v_fma_f32 v61, v52, s96, -v61
	v_fmac_f32_e32 v61, 0x3377d1cf, v52
	v_fmac_f32_e32 v61, 0x3f317217, v52
	v_cmp_lt_f32_e64 s[10:11], |v52|, s97
	s_nop 1
	v_cndmask_b32_e64 v52, v52, v61, s[10:11]
	v_cndmask_b32_e32 v61, 0, v189, vcc
	v_sub_f32_e32 v52, v52, v61
	v_min_f32_e32 v61, 0, v53
	v_mul_f32_e64 v53, |v53|, s95
	v_exp_f32_e32 v53, v53
	s_nop 0
	v_add_f32_e32 v53, 1.0, v53
	v_cmp_gt_f32_e32 vcc, s94, v53
	s_nop 1
	v_cndmask_b32_e64 v63, 0, 32, vcc
	v_ldexp_f32 v53, v53, v63
	v_log_f32_e32 v53, v53
	s_nop 0
	v_mul_f32_e32 v63, 0x3f317217, v53
	v_fma_f32 v63, v53, s96, -v63
	v_fmac_f32_e32 v63, 0x3377d1cf, v53
	v_fmac_f32_e32 v63, 0x3f317217, v53
	v_cmp_lt_f32_e64 s[10:11], |v53|, s97
	s_nop 1
	v_cndmask_b32_e64 v53, v53, v63, s[10:11]
	v_cndmask_b32_e32 v63, 0, v189, vcc
	v_sub_f32_e32 v53, v53, v63
	v_pk_add_f32 v[52:53], v[60:61], v[52:53] neg_lo:[0,1] neg_hi:[0,1]
	global_store_dwordx4 v[56:57], v[50:53], off offset:16

; __device__ __forceinline__ unsigned pk(float lo, float hi) { return pg8::cvt_pk_bf16(lo, hi); }
; __device__ __forceinline__ float log_sigmoid(float z) { return fminf(z, 0.f) - __logf(1.f + __expf(-fabsf(z))); }
;     __device__ __forceinline__ void operator()(const pg8::f32x4 (&acc)[2][2][4][2], const pg8::Unit& u, int wr, int wc, int fr, int fq) const {
;     ...
;                 const int row = row0 + ai * 128 + m * 16; const float rs = rsqrtf(ss[row] * (1.f / DM) + EPS);
;                 if (u.pn < 12) {
;                     const float sc = (sect == 0) ? rs * QSCALE2 : rs;
;                     float* fdst = nullptr;
;                     if (sect == 1) fdst = (row < MP) ? out + O_FKP + (size_t)row * DM : out + O_FKS + (size_t)(row - MP) * DM;
;                     if (sect == 2) fdst = (row < MP) ? out + O_FVP + (size_t)row * DM : out + O_FVS + (size_t)(row - MP) * DM;
; #pragma unroll
;                     for (int bj = 0; bj < 2; ++bj) { const f32x4 v0 = acc[ai][bj][m][0] * sc, v1 = acc[ai][bj][m][1] * sc;
;                         u32x4 w; w.x = pk(v0[0], v0[1]); w.y = pk(v0[2], v0[3]); w.z = pk(v1[0], v1[1]); w.w = pk(v1[2], v1[3]);
;                         const int cl = bj * 128 + wc * 32 + 8 * fq;
;                         *(u32x4*)(qkv + (size_t)row * NPJ + u.pn * 256 + cl) = w;
;                         if (sect > 0) { float* d = fdst + (u.pn & 3) * 256 + cl; __builtin_nontemporal_store(v0, (f32x4*)d); __builtin_nontemporal_store(v1, (f32x4*)(d + 4)); } }
;                 } else if (wc == 0 && fq < 2) {
;                     float* d = (row < MP) ? out + O_FLP + (size_t)row * 16 : out + O_FLS + (size_t)(row - MP) * 16;
; #pragma unroll
;                     for (int n = 0; n < 2; ++n) { const f32x4 v = acc[ai][0][m][n] * rs; f32x4 o;
; #pragma unroll
;                         for (int i = 0; i < 4; ++i) o[i] = log_sigmoid(v[i] + bf[8 * fq + 4 * n + i]);
;                         *(f32x4*)(d + 8 * fq + 4 * n) = o; }
.LBB0_1450:
	s_nop 0
	v_add_u32_e32 v38, 0xa0, v158
	s_and_b64 vcc, exec, s[8:9]
	v_ashrrev_i32_e32 v39, 31, v38
	v_mov_b32_e32 v34, v197
	v_fmamk_f32 v34, v34, 0x3a800000, v186
	v_mul_f32_e32 v35, 0x4b800000, v34
	v_cmp_gt_f32_e64 s[10:11], s94, v34
	s_nop 1
	v_cndmask_b32_e64 v34, v34, v35, s[10:11]
	v_rsq_f32_e32 v34, v34
	s_nop 0
	v_mul_f32_e32 v35, 0x45800000, v34
	v_cndmask_b32_e64 v46, v34, v35, s[10:11]
	s_mov_b64 s[10:11], -1
	s_cbranch_vccnz .LBB0_1454
	s_and_saveexec_b64 s[80:81], s[48:49]
	s_cbranch_execz .LBB0_1453
	s_movk_i32 s10, 0x3f60
	v_cmp_gt_i32_e32 vcc, s10, v158
	v_add_u32_e32 v34, 0xffffc0a0, v158
	v_readlane_b32 s52, v252, 0
	v_cndmask_b32_e32 v35, 0, v39, vcc
	v_cndmask_b32_e32 v34, v34, v38, vcc
	v_cndmask_b32_e32 v142, v187, v188, vcc
	v_readlane_b32 s58, v252, 6
	v_readlane_b32 s59, v252, 7
	v_lshlrev_b64 v[34:35], 6, v[34:35]
	v_readlane_b32 s53, v252, 1
	v_lshl_add_u64 v[36:37], s[58:59], 0, v[142:143]
	v_lshl_add_u64 v[34:35], v[36:37], 0, v[34:35]
	v_lshlrev_b32_e32 v142, 2, v144
	v_lshl_add_u64 v[40:41], v[34:35], 0, v[142:143]
	global_load_dwordx4 v[34:37], v[148:149], off
	v_readlane_b32 s54, v252, 2
	v_readlane_b32 s55, v252, 3
	v_readlane_b32 s56, v252, 4
	v_readlane_b32 s57, v252, 5
	s_waitcnt vmcnt(0)
	v_fma_f32 v42, v30, v46, v34
	v_min_f32_e32 v34, 0, v42
	v_mul_f32_e64 v42, |v42|, s95
	v_exp_f32_e32 v42, v42
	v_fma_f32 v36, v32, v46, v36
	v_fmac_f32_e32 v37, v33, v46
	v_add_f32_e32 v42, 1.0, v42
	v_cmp_gt_f32_e32 vcc, s94, v42
	s_nop 1
	v_cndmask_b32_e64 v43, 0, 32, vcc
	v_ldexp_f32 v42, v42, v43
	v_log_f32_e32 v42, v42
	s_nop 0
	v_mul_f32_e32 v43, 0x3f317217, v42
	v_fma_f32 v43, v42, s96, -v43
	v_fmac_f32_e32 v43, 0x3377d1cf, v42
	v_fmac_f32_e32 v43, 0x3f317217, v42
	v_cmp_lt_f32_e64 s[10:11], |v42|, s97
	s_nop 1
	v_cndmask_b32_e64 v42, v42, v43, s[10:11]
	v_cndmask_b32_e32 v43, 0, v189, vcc
	v_sub_f32_e32 v42, v42, v43
	v_fma_f32 v43, v31, v46, v35
	v_min_f32_e32 v35, 0, v43
	v_mul_f32_e64 v43, |v43|, s95
	v_exp_f32_e32 v43, v43
	s_nop 0
	v_add_f32_e32 v43, 1.0, v43
	v_cmp_gt_f32_e32 vcc, s94, v43
	s_nop 1
	v_cndmask_b32_e64 v44, 0, 32, vcc
	v_ldexp_f32 v43, v43, v44
	v_log_f32_e32 v43, v43
	s_nop 0
	v_mul_f32_e32 v44, 0x3f317217, v43
	v_fma_f32 v44, v43, s96, -v44
	v_fmac_f32_e32 v44, 0x3377d1cf, v43
	v_fmac_f32_e32 v44, 0x3f317217, v43
	v_cmp_lt_f32_e64 s[10:11], |v43|, s97
	s_nop 1
	v_cndmask_b32_e64 v43, v43, v44, s[10:11]
	v_cndmask_b32_e32 v44, 0, v189, vcc
	v_sub_f32_e32 v43, v43, v44
	v_min_f32_e32 v44, 0, v36
	v_mul_f32_e64 v36, |v36|, s95
	v_exp_f32_e32 v36, v36
	v_pk_add_f32 v[34:35], v[34:35], v[42:43] neg_lo:[0,1] neg_hi:[0,1]
	v_add_f32_e32 v36, 1.0, v36
	v_cmp_gt_f32_e32 vcc, s94, v36
	s_nop 1
	v_cndmask_b32_e64 v45, 0, 32, vcc
	v_ldexp_f32 v36, v36, v45
	v_log_f32_e32 v36, v36
	s_nop 0
	v_mul_f32_e32 v45, 0x3f317217, v36
	v_fma_f32 v45, v36, s96, -v45
	v_fmac_f32_e32 v45, 0x3377d1cf, v36
	v_fmac_f32_e32 v45, 0x3f317217, v36
	v_cmp_lt_f32_e64 s[10:11], |v36|, s97
	s_nop 1
	v_cndmask_b32_e64 v36, v36, v45, s[10:11]
	v_cndmask_b32_e32 v45, 0, v189, vcc
	v_sub_f32_e32 v36, v36, v45
	v_min_f32_e32 v45, 0, v37
	v_mul_f32_e64 v37, |v37|, s95
	v_exp_f32_e32 v37, v37
	s_nop 0
	v_add_f32_e32 v37, 1.0, v37
	v_cmp_gt_f32_e32 vcc, s94, v37
	s_nop 1
	v_cndmask_b32_e64 v47, 0, 32, vcc
	v_ldexp_f32 v37, v37, v47
	v_log_f32_e32 v37, v37
	s_nop 0
	v_mul_f32_e32 v47, 0x3f317217, v37
	v_fma_f32 v47, v37, s96, -v47
	v_fmac_f32_e32 v47, 0x3377d1cf, v37
	v_fmac_f32_e32 v47, 0x3f317217, v37
	v_cmp_lt_f32_e64 s[10:11], |v37|, s97
	s_nop 1
	v_cndmask_b32_e64 v37, v37, v47, s[10:11]
	v_cndmask_b32_e32 v47, 0, v189, vcc
	v_sub_f32_e32 v37, v37, v47
	v_pk_add_f32 v[36:37], v[44:45], v[36:37] neg_lo:[0,1] neg_hi:[0,1]
	global_store_dwordx4 v[40:41], v[34:37], off
	global_load_dwordx4 v[34:37], v[148:149], off offset:16
	s_waitcnt vmcnt(0)
	v_fma_f32 v42, v26, v46, v34
	v_min_f32_e32 v34, 0, v42
	v_mul_f32_e64 v42, |v42|, s95
	v_exp_f32_e32 v42, v42
	v_fma_f32 v36, v28, v46, v36
	v_fmac_f32_e32 v37, v29, v46
	v_add_f32_e32 v42, 1.0, v42
	v_cmp_gt_f32_e32 vcc, s94, v42
	s_nop 1
	v_cndmask_b32_e64 v43, 0, 32, vcc
	v_ldexp_f32 v42, v42, v43
	v_log_f32_e32 v42, v42
	s_nop 0
	v_mul_f32_e32 v43, 0x3f317217, v42
	v_fma_f32 v43, v42, s96, -v43
	v_fmac_f32_e32 v43, 0x3377d1cf, v42
	v_fmac_f32_e32 v43, 0x3f317217, v42
	v_cmp_lt_f32_e64 s[10:11], |v42|, s97
	s_nop 1
	v_cndmask_b32_e64 v42, v42, v43, s[10:11]
	v_cndmask_b32_e32 v43, 0, v189, vcc
	v_sub_f32_e32 v42, v42, v43
	v_fma_f32 v43, v27, v46, v35
	v_min_f32_e32 v35, 0, v43
	v_mul_f32_e64 v43, |v43|, s95
	v_exp_f32_e32 v43, v43
	s_nop 0
	v_add_f32_e32 v43, 1.0, v43
	v_cmp_gt_f32_e32 vcc, s94, v43
	s_nop 1
	v_cndmask_b32_e64 v44, 0, 32, vcc
	v_ldexp_f32 v43, v43, v44
	v_log_f32_e32 v43, v43
	s_nop 0
	v_mul_f32_e32 v44, 0x3f317217, v43
	v_fma_f32 v44, v43, s96, -v44
	v_fmac_f32_e32 v44, 0x3377d1cf, v43
	v_fmac_f32_e32 v44, 0x3f317217, v43
	v_cmp_lt_f32_e64 s[10:11], |v43|, s97
	s_nop 1
	v_cndmask_b32_e64 v43, v43, v44, s[10:11]
	v_cndmask_b32_e32 v44, 0, v189, vcc
	v_sub_f32_e32 v43, v43, v44
	v_min_f32_e32 v44, 0, v36
	v_mul_f32_e64 v36, |v36|, s95
	v_exp_f32_e32 v36, v36
	v_pk_add_f32 v[34:35], v[34:35], v[42:43] neg_lo:[0,1] neg_hi:[0,1]
	v_add_f32_e32 v36, 1.0, v36
	v_cmp_gt_f32_e32 vcc, s94, v36
	s_nop 1
	v_cndmask_b32_e64 v45, 0, 32, vcc
	v_ldexp_f32 v36, v36, v45
	v_log_f32_e32 v36, v36
	s_nop 0
	v_mul_f32_e32 v45, 0x3f317217, v36
	v_fma_f32 v45, v36, s96, -v45
	v_fmac_f32_e32 v45, 0x3377d1cf, v36
	v_fmac_f32_e32 v45, 0x3f317217, v36
	v_cmp_lt_f32_e64 s[10:11], |v36|, s97
	s_nop 1
	v_cndmask_b32_e64 v36, v36, v45, s[10:11]
	v_cndmask_b32_e32 v45, 0, v189, vcc
	v_sub_f32_e32 v36, v36, v45
	v_min_f32_e32 v45, 0, v37
	v_mul_f32_e64 v37, |v37|, s95
	v_exp_f32_e32 v37, v37
	s_nop 0
	v_add_f32_e32 v37, 1.0, v37
	v_cmp_gt_f32_e32 vcc, s94, v37
	s_nop 1
	v_cndmask_b32_e64 v47, 0, 32, vcc
	v_ldexp_f32 v37, v37, v47
	v_log_f32_e32 v37, v37
	s_nop 0
	v_mul_f32_e32 v47, 0x3f317217, v37
	v_fma_f32 v47, v37, s96, -v47
	v_fmac_f32_e32 v47, 0x3377d1cf, v37
	v_fmac_f32_e32 v47, 0x3f317217, v37
	v_cmp_lt_f32_e64 s[10:11], |v37|, s97
	s_nop 1
	v_cndmask_b32_e64 v37, v37, v47, s[10:11]
	v_cndmask_b32_e32 v47, 0, v189, vcc
	v_sub_f32_e32 v37, v37, v47
	v_pk_add_f32 v[36:37], v[44:45], v[36:37] neg_lo:[0,1] neg_hi:[0,1]
	global_store_dwordx4 v[40:41], v[34:37], off offset:16

; __device__ __forceinline__ unsigned pk(float lo, float hi) { return pg8::cvt_pk_bf16(lo, hi); }
; __device__ __forceinline__ float log_sigmoid(float z) { return fminf(z, 0.f) - __logf(1.f + __expf(-fabsf(z))); }
;     __device__ __forceinline__ void operator()(const pg8::f32x4 (&acc)[2][2][4][2], const pg8::Unit& u, int wr, int wc, int fr, int fq) const {
;     ...
;                 const int row = row0 + ai * 128 + m * 16; const float rs = rsqrtf(ss[row] * (1.f / DM) + EPS);
;                 if (u.pn < 12) {
;                     const float sc = (sect == 0) ? rs * QSCALE2 : rs;
;                     float* fdst = nullptr;
;                     if (sect == 1) fdst = (row < MP) ? out + O_FKP + (size_t)row * DM : out + O_FKS + (size_t)(row - MP) * DM;
;                     if (sect == 2) fdst = (row < MP) ? out + O_FVP + (size_t)row * DM : out + O_FVS + (size_t)(row - MP) * DM;
; #pragma unroll
;                     for (int bj = 0; bj < 2; ++bj) { const f32x4 v0 = acc[ai][bj][m][0] * sc, v1 = acc[ai][bj][m][1] * sc;
;                         u32x4 w; w.x = pk(v0[0], v0[1]); w.y = pk(v0[2], v0[3]); w.z = pk(v1[0], v1[1]); w.w = pk(v1[2], v1[3]);
;                         const int cl = bj * 128 + wc * 32 + 8 * fq;
;                         *(u32x4*)(qkv + (size_t)row * NPJ + u.pn * 256 + cl) = w;
;                         if (sect > 0) { float* d = fdst + (u.pn & 3) * 256 + cl; __builtin_nontemporal_store(v0, (f32x4*)d); __builtin_nontemporal_store(v1, (f32x4*)(d + 4)); } }
;                 } else if (wc == 0 && fq < 2) {
;                     float* d = (row < MP) ? out + O_FLP + (size_t)row * 16 : out + O_FLS + (size_t)(row - MP) * 16;
; #pragma unroll
;                     for (int n = 0; n < 2; ++n) { const f32x4 v = acc[ai][0][m][n] * rs; f32x4 o;
; #pragma unroll
;                         for (int i = 0; i < 4; ++i) o[i] = log_sigmoid(v[i] + bf[8 * fq + 4 * n + i]);
;                         *(f32x4*)(d + 8 * fq + 4 * n) = o; }
.LBB0_1471:
	s_nop 0
	v_add_u32_e32 v22, 0xb0, v158
	s_and_b64 vcc, exec, s[8:9]
	v_ashrrev_i32_e32 v23, 31, v22
	s_mov_b64 s[8:9], -1
	v_mov_b32_e32 v18, v198
	v_fmamk_f32 v18, v18, 0x3a800000, v186
	v_mul_f32_e32 v19, 0x4b800000, v18
	v_cmp_gt_f32_e64 s[10:11], s94, v18
	s_nop 1
	v_cndmask_b32_e64 v18, v18, v19, s[10:11]
	v_rsq_f32_e32 v18, v18
	s_nop 0
	v_mul_f32_e32 v19, 0x45800000, v18
	v_cndmask_b32_e64 v30, v18, v19, s[10:11]
	s_cbranch_vccnz .LBB0_1475
	s_and_saveexec_b64 s[10:11], s[48:49]
	s_cbranch_execz .LBB0_1474
	s_movk_i32 s8, 0x3f50
	v_cmp_gt_i32_e32 vcc, s8, v158
	v_add_u32_e32 v18, 0xffffc0b0, v158
	v_readlane_b32 s52, v252, 0
	v_cndmask_b32_e32 v19, 0, v23, vcc
	v_cndmask_b32_e32 v18, v18, v22, vcc
	v_cndmask_b32_e32 v142, v187, v188, vcc
	v_readlane_b32 s58, v252, 6
	v_readlane_b32 s59, v252, 7
	v_lshlrev_b64 v[18:19], 6, v[18:19]
	v_readlane_b32 s53, v252, 1
	v_lshl_add_u64 v[20:21], s[58:59], 0, v[142:143]
	v_lshl_add_u64 v[18:19], v[20:21], 0, v[18:19]
	v_lshlrev_b32_e32 v142, 2, v144
	v_lshl_add_u64 v[24:25], v[18:19], 0, v[142:143]
	global_load_dwordx4 v[18:21], v[148:149], off
	v_readlane_b32 s54, v252, 2
	v_readlane_b32 s55, v252, 3
	v_readlane_b32 s56, v252, 4
	v_readlane_b32 s57, v252, 5
	s_waitcnt vmcnt(0)
	v_fma_f32 v26, v14, v30, v18
	v_min_f32_e32 v18, 0, v26
	v_mul_f32_e64 v26, |v26|, s95
	v_exp_f32_e32 v26, v26
	v_fma_f32 v20, v16, v30, v20
	v_fmac_f32_e32 v21, v17, v30
	v_add_f32_e32 v26, 1.0, v26
	v_cmp_gt_f32_e32 vcc, s94, v26
	s_nop 1
	v_cndmask_b32_e64 v27, 0, 32, vcc
	v_ldexp_f32 v26, v26, v27
	v_log_f32_e32 v26, v26
	s_nop 0
	v_mul_f32_e32 v27, 0x3f317217, v26
	v_fma_f32 v27, v26, s96, -v27
	v_fmac_f32_e32 v27, 0x3377d1cf, v26
	v_fmac_f32_e32 v27, 0x3f317217, v26
	v_cmp_lt_f32_e64 s[8:9], |v26|, s97
	s_nop 1
	v_cndmask_b32_e64 v26, v26, v27, s[8:9]
	v_cndmask_b32_e32 v27, 0, v189, vcc
	v_sub_f32_e32 v26, v26, v27
	v_fma_f32 v27, v15, v30, v19
	v_min_f32_e32 v19, 0, v27
	v_mul_f32_e64 v27, |v27|, s95
	v_exp_f32_e32 v27, v27
	s_nop 0
	v_add_f32_e32 v27, 1.0, v27
	v_cmp_gt_f32_e32 vcc, s94, v27
	s_nop 1
	v_cndmask_b32_e64 v28, 0, 32, vcc
	v_ldexp_f32 v27, v27, v28
	v_log_f32_e32 v27, v27
	s_nop 0
	v_mul_f32_e32 v28, 0x3f317217, v27
	v_fma_f32 v28, v27, s96, -v28
	v_fmac_f32_e32 v28, 0x3377d1cf, v27
	v_fmac_f32_e32 v28, 0x3f317217, v27
	v_cmp_lt_f32_e64 s[8:9], |v27|, s97
	s_nop 1
	v_cndmask_b32_e64 v27, v27, v28, s[8:9]
	v_cndmask_b32_e32 v28, 0, v189, vcc
	v_sub_f32_e32 v27, v27, v28
	v_min_f32_e32 v28, 0, v20
	v_mul_f32_e64 v20, |v20|, s95
	v_exp_f32_e32 v20, v20
	v_pk_add_f32 v[18:19], v[18:19], v[26:27] neg_lo:[0,1] neg_hi:[0,1]
	v_add_f32_e32 v20, 1.0, v20
	v_cmp_gt_f32_e32 vcc, s94, v20
	s_nop 1
	v_cndmask_b32_e64 v29, 0, 32, vcc
	v_ldexp_f32 v20, v20, v29
	v_log_f32_e32 v20, v20
	s_nop 0
	v_mul_f32_e32 v29, 0x3f317217, v20
	v_fma_f32 v29, v20, s96, -v29
	v_fmac_f32_e32 v29, 0x3377d1cf, v20
	v_fmac_f32_e32 v29, 0x3f317217, v20
	v_cmp_lt_f32_e64 s[8:9], |v20|, s97
	s_nop 1
	v_cndmask_b32_e64 v20, v20, v29, s[8:9]
	v_cndmask_b32_e32 v29, 0, v189, vcc
	v_sub_f32_e32 v20, v20, v29
	v_min_f32_e32 v29, 0, v21
	v_mul_f32_e64 v21, |v21|, s95
	v_exp_f32_e32 v21, v21
	s_nop 0
	v_add_f32_e32 v21, 1.0, v21
	v_cmp_gt_f32_e32 vcc, s94, v21
	s_nop 1
	v_cndmask_b32_e64 v31, 0, 32, vcc
	v_ldexp_f32 v21, v21, v31
	v_log_f32_e32 v21, v21
	s_nop 0
	v_mul_f32_e32 v31, 0x3f317217, v21
	v_fma_f32 v31, v21, s96, -v31
	v_fmac_f32_e32 v31, 0x3377d1cf, v21
	v_fmac_f32_e32 v31, 0x3f317217, v21
	v_cmp_lt_f32_e64 s[8:9], |v21|, s97
	s_nop 1
	v_cndmask_b32_e64 v21, v21, v31, s[8:9]
	v_cndmask_b32_e32 v31, 0, v189, vcc
	v_sub_f32_e32 v21, v21, v31
	v_pk_add_f32 v[20:21], v[28:29], v[20:21] neg_lo:[0,1] neg_hi:[0,1]
	global_store_dwordx4 v[24:25], v[18:21], off
	global_load_dwordx4 v[18:21], v[148:149], off offset:16
	s_waitcnt vmcnt(0)
	v_fma_f32 v26, v10, v30, v18
	v_min_f32_e32 v18, 0, v26
	v_mul_f32_e64 v26, |v26|, s95
	v_exp_f32_e32 v26, v26
	v_fma_f32 v20, v12, v30, v20
	v_fmac_f32_e32 v21, v13, v30
	v_add_f32_e32 v26, 1.0, v26
	v_cmp_gt_f32_e32 vcc, s94, v26
	s_nop 1
	v_cndmask_b32_e64 v27, 0, 32, vcc
	v_ldexp_f32 v26, v26, v27
	v_log_f32_e32 v26, v26
	s_nop 0
	v_mul_f32_e32 v27, 0x3f317217, v26
	v_fma_f32 v27, v26, s96, -v27
	v_fmac_f32_e32 v27, 0x3377d1cf, v26
	v_fmac_f32_e32 v27, 0x3f317217, v26
	v_cmp_lt_f32_e64 s[8:9], |v26|, s97
	s_nop 1
	v_cndmask_b32_e64 v26, v26, v27, s[8:9]
	v_cndmask_b32_e32 v27, 0, v189, vcc
	v_sub_f32_e32 v26, v26, v27
	v_fma_f32 v27, v11, v30, v19
	v_min_f32_e32 v19, 0, v27
	v_mul_f32_e64 v27, |v27|, s95
	v_exp_f32_e32 v27, v27
	s_nop 0
	v_add_f32_e32 v27, 1.0, v27
	v_cmp_gt_f32_e32 vcc, s94, v27
	s_nop 1
	v_cndmask_b32_e64 v28, 0, 32, vcc
	v_ldexp_f32 v27, v27, v28
	v_log_f32_e32 v27, v27
	s_nop 0
	v_mul_f32_e32 v28, 0x3f317217, v27
	v_fma_f32 v28, v27, s96, -v28
	v_fmac_f32_e32 v28, 0x3377d1cf, v27
	v_fmac_f32_e32 v28, 0x3f317217, v27
	v_cmp_lt_f32_e64 s[8:9], |v27|, s97
	s_nop 1
	v_cndmask_b32_e64 v27, v27, v28, s[8:9]
	v_cndmask_b32_e32 v28, 0, v189, vcc
	v_sub_f32_e32 v27, v27, v28
	v_min_f32_e32 v28, 0, v20
	v_mul_f32_e64 v20, |v20|, s95
	v_exp_f32_e32 v20, v20
	v_pk_add_f32 v[18:19], v[18:19], v[26:27] neg_lo:[0,1] neg_hi:[0,1]
	v_add_f32_e32 v20, 1.0, v20
	v_cmp_gt_f32_e32 vcc, s94, v20
	s_nop 1
	v_cndmask_b32_e64 v29, 0, 32, vcc
	v_ldexp_f32 v20, v20, v29
	v_log_f32_e32 v20, v20
	s_nop 0
	v_mul_f32_e32 v29, 0x3f317217, v20
	v_fma_f32 v29, v20, s96, -v29
	v_fmac_f32_e32 v29, 0x3377d1cf, v20
	v_fmac_f32_e32 v29, 0x3f317217, v20
	v_cmp_lt_f32_e64 s[8:9], |v20|, s97
	s_nop 1
	v_cndmask_b32_e64 v20, v20, v29, s[8:9]
	v_cndmask_b32_e32 v29, 0, v189, vcc
	v_sub_f32_e32 v20, v20, v29
	v_min_f32_e32 v29, 0, v21
	v_mul_f32_e64 v21, |v21|, s95
	v_exp_f32_e32 v21, v21
	s_nop 0
	v_add_f32_e32 v21, 1.0, v21
	v_cmp_gt_f32_e32 vcc, s94, v21
	s_nop 1
	v_cndmask_b32_e64 v31, 0, 32, vcc
	v_ldexp_f32 v21, v21, v31
	v_log_f32_e32 v21, v21
	s_nop 0
	v_mul_f32_e32 v31, 0x3f317217, v21
	v_fma_f32 v31, v21, s96, -v31
	v_fmac_f32_e32 v31, 0x3377d1cf, v21
	v_fmac_f32_e32 v31, 0x3f317217, v21
	v_cmp_lt_f32_e64 s[8:9], |v21|, s97
	s_nop 1
	v_cndmask_b32_e64 v21, v21, v31, s[8:9]
	v_cndmask_b32_e32 v31, 0, v189, vcc
	v_sub_f32_e32 v21, v21, v31
	v_pk_add_f32 v[20:21], v[28:29], v[20:21] neg_lo:[0,1] neg_hi:[0,1]
	global_store_dwordx4 v[24:25], v[18:21], off offset:16

; __device__ __forceinline__ unsigned pk(float lo, float hi) { return pg8::cvt_pk_bf16(lo, hi); }
;     __device__ __forceinline__ void operator()(const pg8::f32x4 (&acc)[2][2][4][2], const pg8::Unit& u, int wr, int wc, int fr, int fq) const {
;         const int row0 = u.pm * 256 + wr * 64 + fr;
; #pragma unroll
;         for (int ai = 0; ai < 2; ++ai)
; #pragma unroll
;             for (int m = 0; m < 4; ++m) {
;                 const int row = row0 + ai * 128 + m * 16; const float rs = rsqrtf(ss[row] * (1.f / DM) + EPS);
;                 float y[8];
; #pragma unroll
;                 for (int n = 0; n < 2; ++n)
; #pragma unroll
;                     for (int i = 0; i < 4; ++i) { const float g = acc[ai][0][m][n][i] * rs, up = acc[ai][1][m][n][i] * rs; y[4 * n + i] = g * up * __builtin_amdgcn_rcpf(1.f + __expf(-g)); }
;                 u32x4 w; w.x = pk(y[0], y[1]); w.y = pk(y[2], y[3]); w.z = pk(y[4], y[5]); w.w = pk(y[6], y[7]);
;                 *(u32x4*)(act + (size_t)row * DFF + u.pn * 128 + wc * 32 + 8 * fq) = w;
.LBB0_1938:
	v_lshl_add_u32 v148, s26, 8, v152
	v_ashrrev_i32_e32 v149, 31, v148
	v_lshl_add_u64 v[150:151], v[148:149], 2, s[8:9]
	global_load_dword v184, v[150:151], off
	global_load_dword v185, v[150:151], off offset:64
	global_load_dword v186, v[150:151], off offset:128
	global_load_dword v187, v[150:151], off offset:192
	global_load_dword v188, v[150:151], off offset:512
	global_load_dword v189, v[150:151], off offset:576
	global_load_dword v190, v[150:151], off offset:640
	global_load_dword v191, v[150:151], off offset:704
	v_or_b32_e32 v162, 16, v148
	v_ashrrev_i32_e32 v163, 31, v162
	v_mov_b32_e32 v161, v116
	v_mov_b32_e32 v116, v125
	v_mov_b32_e32 v158, v126
	v_mov_b32_e32 v159, v118
	v_mov_b32_e32 v118, v127
	v_mov_b32_e32 v126, v128
	v_mov_b32_e32 v127, v120
	v_mov_b32_e32 v120, v129
	v_mov_b32_e32 v128, v122
	v_mov_b32_e32 v129, v114
	v_mov_b32_e32 v114, v123
	v_mov_b32_e32 v160, v124
	s_lshl_b32 s26, s27, 7
	v_mov_b64_e32 v[122:123], s[12:13]
	s_ashr_i32 s27, s26, 31
	v_mad_i64_i32 v[124:125], s[36:37], v148, s55, v[122:123]
	s_lshl_b64 s[26:27], s[26:27], 1
	v_lshl_add_u64 v[124:125], v[124:125], 0, s[26:27]
	v_lshl_add_u64 v[124:125], v[124:125], 0, s[4:5]
	v_lshl_add_u64 v[124:125], v[124:125], 0, v[138:139]
	s_waitcnt vmcnt(0)
	v_mov_b32_e32 v149, v184
	v_fmamk_f32 v149, v149, 0x3a800000, v157
	v_mul_f32_e32 v164, 0x4b800000, v149
	v_cmp_gt_f32_e32 vcc, s54, v149
	s_nop 1
	v_cndmask_b32_e32 v149, v149, v164, vcc
	v_rsq_f32_e32 v149, v149
	v_lshl_add_u64 v[164:165], v[162:163], 2, s[8:9]
	v_mul_f32_e32 v163, 0x45800000, v149
	v_cndmask_b32_e32 v166, v149, v163, vcc
	v_pk_mul_f32 v[116:117], v[116:117], v[166:167] op_sel_hi:[1,0]
	v_pk_mul_f32 v[158:159], v[158:159], v[166:167] op_sel_hi:[1,0]
	v_pk_mul_f32 v[118:119], v[118:119], v[166:167] op_sel_hi:[1,0]
	v_pk_mul_f32 v[126:127], v[126:127], v[166:167] op_sel_hi:[1,0]
	v_pk_mul_f32 v[120:121], v[120:121], v[166:167] op_sel_hi:[1,0]
	v_pk_mul_f32 v[128:129], v[128:129], v[166:167] op_sel_hi:[1,0]
	v_pk_mul_f32 v[114:115], v[114:115], v[166:167] op_sel_hi:[1,0]
	v_pk_mul_f32 v[160:161], v[160:161], v[166:167] op_sel_hi:[1,0]
	v_mul_f32_e32 v117, v116, v117
	v_mul_f32_e32 v116, 0xbfb8aa3b, v116
	v_mul_f32_e32 v149, v158, v159
	v_mul_f32_e32 v158, 0xbfb8aa3b, v158
	v_mul_f32_e32 v119, v118, v119
	v_mul_f32_e32 v118, 0xbfb8aa3b, v118
	v_mul_f32_e32 v127, v126, v127
	v_mul_f32_e32 v126, 0xbfb8aa3b, v126
	v_mul_f32_e32 v121, v120, v121
	v_mul_f32_e32 v120, 0xbfb8aa3b, v120
	v_mul_f32_e32 v129, v128, v129
	v_mul_f32_e32 v128, 0xbfb8aa3b, v128
	v_mul_f32_e32 v115, v114, v115
	v_mul_f32_e32 v114, 0xbfb8aa3b, v114
	v_mul_f32_e32 v159, v160, v161
	v_mul_f32_e32 v160, 0xbfb8aa3b, v160
	v_exp_f32_e32 v116, v116
	v_exp_f32_e32 v158, v158
	v_exp_f32_e32 v118, v118
	v_exp_f32_e32 v126, v126
	v_exp_f32_e32 v120, v120
	v_exp_f32_e32 v128, v128
	v_exp_f32_e32 v114, v114
	v_exp_f32_e32 v160, v160
	v_add_f32_e32 v116, 1.0, v116
	v_add_f32_e32 v158, 1.0, v158
	v_add_f32_e32 v118, 1.0, v118
	v_add_f32_e32 v126, 1.0, v126
	v_add_f32_e32 v120, 1.0, v120
	v_add_f32_e32 v128, 1.0, v128
	v_add_f32_e32 v114, 1.0, v114
	v_add_f32_e32 v160, 1.0, v160
	v_rcp_f32_e32 v116, v116
	v_rcp_f32_e32 v158, v158
	v_rcp_f32_e32 v118, v118
	v_rcp_f32_e32 v126, v126
	v_rcp_f32_e32 v120, v120
	v_rcp_f32_e32 v128, v128
	v_rcp_f32_e32 v114, v114
	v_rcp_f32_e32 v160, v160
	v_mul_f32_e32 v117, v117, v116
	v_mul_f32_e32 v149, v149, v158
	v_mul_f32_e32 v118, v119, v118
	v_mul_f32_e32 v119, v127, v126
	v_mul_f32_e32 v120, v121, v120
	v_mul_f32_e32 v121, v129, v128
	v_mul_f32_e32 v126, v115, v114
	v_mul_f32_e32 v127, v159, v160
	v_cvt_pk_bf16_f32 v114, v149, v118
	v_cvt_pk_bf16_f32 v115, v119, v120
	v_cvt_pk_bf16_f32 v116, v121, v126
	v_cvt_pk_bf16_f32 v117, v127, v117
	global_store_dwordx4 v[124:125], v[114:117], off
	s_nop 0
	v_mov_b32_e32 v118, v185
	v_fmamk_f32 v118, v118, 0x3a800000, v157
	v_mul_f32_e32 v119, 0x4b800000, v118
	v_cmp_gt_f32_e32 vcc, s54, v118
	v_mov_b32_e32 v114, v110
	v_mov_b32_e32 v110, v112
	v_cndmask_b32_e32 v118, v118, v119, vcc
	v_rsq_f32_e32 v120, v118
	v_mov_b32_e32 v112, v106
	v_mov_b32_e32 v106, v108
	v_or_b32_e32 v108, 32, v148
	v_mov_b32_e32 v115, v102
	v_mov_b32_e32 v102, v111
	v_mov_b32_e32 v111, v104
	v_mov_b32_e32 v104, v113
	v_mov_b32_e32 v113, v98
	v_mov_b32_e32 v98, v107
	v_mov_b32_e32 v107, v100
	v_mov_b32_e32 v100, v109
	v_ashrrev_i32_e32 v109, 31, v108
	v_lshl_add_u64 v[118:119], v[108:109], 2, s[8:9]
	v_mul_f32_e32 v109, 0x45800000, v120
	v_cndmask_b32_e32 v120, v120, v109, vcc
	v_pk_mul_f32 v[100:101], v[100:101], v[120:121] op_sel_hi:[1,0]
	v_pk_mul_f32 v[114:115], v[114:115], v[120:121] op_sel_hi:[1,0]
	v_pk_mul_f32 v[102:103], v[102:103], v[120:121] op_sel_hi:[1,0]
	v_pk_mul_f32 v[110:111], v[110:111], v[120:121] op_sel_hi:[1,0]
	v_pk_mul_f32 v[104:105], v[104:105], v[120:121] op_sel_hi:[1,0]
	v_pk_mul_f32 v[112:113], v[112:113], v[120:121] op_sel_hi:[1,0]
	v_pk_mul_f32 v[98:99], v[98:99], v[120:121] op_sel_hi:[1,0]
	v_pk_mul_f32 v[106:107], v[106:107], v[120:121] op_sel_hi:[1,0]
	v_mul_f32_e32 v101, v100, v101
	v_mul_f32_e32 v100, 0xbfb8aa3b, v100
	v_mul_f32_e32 v109, v114, v115
	v_mul_f32_e32 v114, 0xbfb8aa3b, v114
	v_mul_f32_e32 v103, v102, v103
	v_mul_f32_e32 v102, 0xbfb8aa3b, v102
	v_mul_f32_e32 v111, v110, v111
	v_mul_f32_e32 v110, 0xbfb8aa3b, v110
	v_mul_f32_e32 v105, v104, v105
	v_mul_f32_e32 v104, 0xbfb8aa3b, v104
	v_mul_f32_e32 v113, v112, v113
	v_mul_f32_e32 v112, 0xbfb8aa3b, v112
	v_mul_f32_e32 v99, v98, v99
	v_mul_f32_e32 v98, 0xbfb8aa3b, v98
	v_mul_f32_e32 v107, v106, v107
	v_mul_f32_e32 v106, 0xbfb8aa3b, v106
	v_exp_f32_e32 v100, v100
	v_exp_f32_e32 v114, v114
; __device__ __forceinline__ unsigned pk(float lo, float hi) { return pg8::cvt_pk_bf16(lo, hi); }
;     __device__ __forceinline__ void operator()(const pg8::f32x4 (&acc)[2][2][4][2], const pg8::Unit& u, int wr, int wc, int fr, int fq) const {
;     ...
;                 const int row = row0 + ai * 128 + m * 16; const float rs = rsqrtf(ss[row] * (1.f / DM) + EPS);
;                 float y[8];
; #pragma unroll
;                 for (int n = 0; n < 2; ++n)
; #pragma unroll
;                     for (int i = 0; i < 4; ++i) { const float g = acc[ai][0][m][n][i] * rs, up = acc[ai][1][m][n][i] * rs; y[4 * n + i] = g * up * __builtin_amdgcn_rcpf(1.f + __expf(-g)); }
;                 u32x4 w; w.x = pk(y[0], y[1]); w.y = pk(y[2], y[3]); w.z = pk(y[4], y[5]); w.w = pk(y[6], y[7]);
;                 *(u32x4*)(act + (size_t)row * DFF + u.pn * 128 + wc * 32 + 8 * fq) = w;
	v_exp_f32_e32 v102, v102
	v_exp_f32_e32 v110, v110
	v_exp_f32_e32 v104, v104
	v_exp_f32_e32 v112, v112
	v_exp_f32_e32 v98, v98
	v_exp_f32_e32 v106, v106
	v_add_f32_e32 v100, 1.0, v100
	v_add_f32_e32 v114, 1.0, v114
	v_add_f32_e32 v102, 1.0, v102
	v_add_f32_e32 v110, 1.0, v110
	v_add_f32_e32 v104, 1.0, v104
	v_add_f32_e32 v112, 1.0, v112
	v_add_f32_e32 v98, 1.0, v98
	v_add_f32_e32 v106, 1.0, v106
	v_rcp_f32_e32 v100, v100
	v_mad_i64_i32 v[116:117], s[36:37], v162, s55, v[122:123]
	v_rcp_f32_e32 v114, v114
	v_rcp_f32_e32 v102, v102
	v_rcp_f32_e32 v110, v110
	v_rcp_f32_e32 v104, v104
	v_rcp_f32_e32 v112, v112
	v_rcp_f32_e32 v98, v98
	v_rcp_f32_e32 v106, v106
	v_lshl_add_u64 v[116:117], v[116:117], 0, s[26:27]
	v_lshl_add_u64 v[116:117], v[116:117], 0, s[4:5]
	v_lshl_add_u64 v[116:117], v[116:117], 0, v[138:139]
	v_mul_f32_e32 v101, v101, v100
	v_mul_f32_e32 v109, v109, v114
	v_mul_f32_e32 v102, v103, v102
	v_mul_f32_e32 v103, v111, v110
	v_mul_f32_e32 v104, v105, v104
	v_mul_f32_e32 v105, v113, v112
	v_mul_f32_e32 v110, v99, v98
	v_mul_f32_e32 v106, v107, v106
	v_cvt_pk_bf16_f32 v98, v109, v102
	v_cvt_pk_bf16_f32 v99, v103, v104
	v_cvt_pk_bf16_f32 v100, v105, v110
	v_cvt_pk_bf16_f32 v101, v106, v101
	global_store_dwordx4 v[116:117], v[98:101], off
	s_nop 0
	v_mov_b32_e32 v102, v186
	v_fmamk_f32 v102, v102, 0x3a800000, v157
	v_mul_f32_e32 v103, 0x4b800000, v102
	v_cmp_gt_f32_e32 vcc, s54, v102
	v_mov_b32_e32 v98, v94
	v_mov_b32_e32 v94, v96
	v_cndmask_b32_e32 v102, v102, v103, vcc
	v_rsq_f32_e32 v104, v102
	v_mov_b32_e32 v96, v90
	v_mov_b32_e32 v90, v92
	v_or_b32_e32 v92, 48, v148
	v_mov_b32_e32 v99, v86
	v_mov_b32_e32 v86, v95
	v_mov_b32_e32 v95, v88
	v_mov_b32_e32 v88, v97
	v_mov_b32_e32 v97, v82
	v_mov_b32_e32 v82, v91
	v_mov_b32_e32 v91, v84
	v_mov_b32_e32 v84, v93
	v_ashrrev_i32_e32 v93, 31, v92
	v_lshl_add_u64 v[102:103], v[92:93], 2, s[8:9]
	v_mul_f32_e32 v93, 0x45800000, v104
	v_cndmask_b32_e32 v104, v104, v93, vcc
	v_pk_mul_f32 v[84:85], v[84:85], v[104:105] op_sel_hi:[1,0]
	v_pk_mul_f32 v[98:99], v[98:99], v[104:105] op_sel_hi:[1,0]
	v_pk_mul_f32 v[86:87], v[86:87], v[104:105] op_sel_hi:[1,0]
	v_pk_mul_f32 v[94:95], v[94:95], v[104:105] op_sel_hi:[1,0]
	v_pk_mul_f32 v[88:89], v[88:89], v[104:105] op_sel_hi:[1,0]
	v_pk_mul_f32 v[96:97], v[96:97], v[104:105] op_sel_hi:[1,0]
	v_pk_mul_f32 v[82:83], v[82:83], v[104:105] op_sel_hi:[1,0]
	v_pk_mul_f32 v[90:91], v[90:91], v[104:105] op_sel_hi:[1,0]
	v_mul_f32_e32 v85, v84, v85
	v_mul_f32_e32 v84, 0xbfb8aa3b, v84
	v_mul_f32_e32 v93, v98, v99
	v_mul_f32_e32 v98, 0xbfb8aa3b, v98
	v_mul_f32_e32 v87, v86, v87
	v_mul_f32_e32 v86, 0xbfb8aa3b, v86
	v_mul_f32_e32 v95, v94, v95
	v_mul_f32_e32 v94, 0xbfb8aa3b, v94
	v_mul_f32_e32 v89, v88, v89
	v_mul_f32_e32 v88, 0xbfb8aa3b, v88
	v_mul_f32_e32 v97, v96, v97
	v_mul_f32_e32 v96, 0xbfb8aa3b, v96
	v_mul_f32_e32 v83, v82, v83
	v_mul_f32_e32 v82, 0xbfb8aa3b, v82
	v_mul_f32_e32 v91, v90, v91
	v_mul_f32_e32 v90, 0xbfb8aa3b, v90
	v_exp_f32_e32 v84, v84
	v_exp_f32_e32 v98, v98
	v_exp_f32_e32 v86, v86
	v_exp_f32_e32 v94, v94
	v_exp_f32_e32 v88, v88
	v_exp_f32_e32 v96, v96
	v_exp_f32_e32 v82, v82
	v_exp_f32_e32 v90, v90
	v_add_f32_e32 v84, 1.0, v84
	v_add_f32_e32 v98, 1.0, v98
	v_add_f32_e32 v86, 1.0, v86
	v_add_f32_e32 v94, 1.0, v94
	v_add_f32_e32 v88, 1.0, v88
	v_add_f32_e32 v96, 1.0, v96
	v_add_f32_e32 v82, 1.0, v82
	v_add_f32_e32 v90, 1.0, v90
	v_rcp_f32_e32 v84, v84
	v_mad_i64_i32 v[100:101], s[36:37], v108, s55, v[122:123]
	v_rcp_f32_e32 v98, v98
	v_rcp_f32_e32 v86, v86
	v_rcp_f32_e32 v94, v94
	v_rcp_f32_e32 v88, v88
	v_rcp_f32_e32 v96, v96
	v_rcp_f32_e32 v82, v82
	v_rcp_f32_e32 v90, v90
	v_lshl_add_u64 v[100:101], v[100:101], 0, s[26:27]
	v_lshl_add_u64 v[100:101], v[100:101], 0, s[4:5]
	v_lshl_add_u64 v[100:101], v[100:101], 0, v[138:139]
	v_mul_f32_e32 v85, v85, v84
	v_mul_f32_e32 v93, v93, v98
	v_mul_f32_e32 v86, v87, v86
	v_mul_f32_e32 v87, v95, v94
	v_mul_f32_e32 v88, v89, v88
	v_mul_f32_e32 v89, v97, v96
	v_mul_f32_e32 v94, v83, v82
	v_mul_f32_e32 v90, v91, v90
	v_cvt_pk_bf16_f32 v82, v93, v86
	v_cvt_pk_bf16_f32 v83, v87, v88
	v_cvt_pk_bf16_f32 v84, v89, v94
	v_cvt_pk_bf16_f32 v85, v90, v85
	global_store_dwordx4 v[100:101], v[82:85], off
	s_nop 0
	s_nop 0
	v_mov_b32_e32 v83, v70
	v_mov_b32_e32 v70, v79
	v_mov_b32_e32 v79, v72
	v_mov_b32_e32 v72, v81
	v_mov_b32_e32 v81, v66
	v_mov_b32_e32 v66, v75
	v_mov_b32_e32 v75, v68
	v_mov_b32_e32 v68, v77
	v_mov_b32_e32 v82, v78
	v_mov_b32_e32 v78, v80
	v_mov_b32_e32 v80, v74
	v_mov_b32_e32 v74, v76
	v_mad_i64_i32 v[76:77], s[36:37], v92, s55, v[122:123]
	v_lshl_add_u64 v[76:77], v[76:77], 0, s[26:27]
	v_lshl_add_u64 v[76:77], v[76:77], 0, s[4:5]
	v_lshl_add_u64 v[76:77], v[76:77], 0, v[138:139]
	v_mov_b32_e32 v84, v187
	v_fmamk_f32 v84, v84, 0x3a800000, v157
	v_mul_f32_e32 v85, 0x4b800000, v84
	v_cmp_gt_f32_e32 vcc, s54, v84
	s_nop 1
	v_cndmask_b32_e32 v84, v84, v85, vcc
	v_rsq_f32_e32 v84, v84
	s_nop 0
	v_mul_f32_e32 v85, 0x45800000, v84
	v_cndmask_b32_e32 v84, v84, v85, vcc
	v_pk_mul_f32 v[68:69], v[68:69], v[84:85] op_sel_hi:[1,0]
	v_pk_mul_f32 v[82:83], v[82:83], v[84:85] op_sel_hi:[1,0]
	v_pk_mul_f32 v[70:71], v[70:71], v[84:85] op_sel_hi:[1,0]
	v_pk_mul_f32 v[78:79], v[78:79], v[84:85] op_sel_hi:[1,0]
	v_pk_mul_f32 v[72:73], v[72:73], v[84:85] op_sel_hi:[1,0]
	v_pk_mul_f32 v[80:81], v[80:81], v[84:85] op_sel_hi:[1,0]
	v_pk_mul_f32 v[66:67], v[66:67], v[84:85] op_sel_hi:[1,0]
	v_pk_mul_f32 v[74:75], v[74:75], v[84:85] op_sel_hi:[1,0]
	v_mul_f32_e32 v69, v68, v69
	v_mul_f32_e32 v68, 0xbfb8aa3b, v68
	v_mul_f32_e32 v83, v82, v83
	v_mul_f32_e32 v82, 0xbfb8aa3b, v82
	v_mul_f32_e32 v71, v70, v71
; __device__ __forceinline__ unsigned pk(float lo, float hi) { return pg8::cvt_pk_bf16(lo, hi); }
;     __device__ __forceinline__ void operator()(const pg8::f32x4 (&acc)[2][2][4][2], const pg8::Unit& u, int wr, int wc, int fr, int fq) const {
;     ...
;                 const int row = row0 + ai * 128 + m * 16; const float rs = rsqrtf(ss[row] * (1.f / DM) + EPS);
;                 float y[8];
; #pragma unroll
;                 for (int n = 0; n < 2; ++n)
; #pragma unroll
;                     for (int i = 0; i < 4; ++i) { const float g = acc[ai][0][m][n][i] * rs, up = acc[ai][1][m][n][i] * rs; y[4 * n + i] = g * up * __builtin_amdgcn_rcpf(1.f + __expf(-g)); }
;                 u32x4 w; w.x = pk(y[0], y[1]); w.y = pk(y[2], y[3]); w.z = pk(y[4], y[5]); w.w = pk(y[6], y[7]);
;                 *(u32x4*)(act + (size_t)row * DFF + u.pn * 128 + wc * 32 + 8 * fq) = w;
	v_mul_f32_e32 v70, 0xbfb8aa3b, v70
	v_mul_f32_e32 v79, v78, v79
	v_mul_f32_e32 v78, 0xbfb8aa3b, v78
	v_mul_f32_e32 v73, v72, v73
	v_mul_f32_e32 v72, 0xbfb8aa3b, v72
	v_mul_f32_e32 v81, v80, v81
	v_mul_f32_e32 v80, 0xbfb8aa3b, v80
	v_mul_f32_e32 v67, v66, v67
	v_mul_f32_e32 v66, 0xbfb8aa3b, v66
	v_mul_f32_e32 v75, v74, v75
	v_mul_f32_e32 v74, 0xbfb8aa3b, v74
	v_exp_f32_e32 v68, v68
	v_exp_f32_e32 v82, v82
	v_exp_f32_e32 v70, v70
	v_exp_f32_e32 v78, v78
	v_exp_f32_e32 v72, v72
	v_exp_f32_e32 v80, v80
	v_exp_f32_e32 v66, v66
	v_exp_f32_e32 v74, v74
	v_add_f32_e32 v68, 1.0, v68
	v_add_f32_e32 v82, 1.0, v82
	v_add_f32_e32 v70, 1.0, v70
	v_add_f32_e32 v78, 1.0, v78
	v_add_f32_e32 v72, 1.0, v72
	v_add_f32_e32 v80, 1.0, v80
	v_add_f32_e32 v66, 1.0, v66
	v_add_f32_e32 v74, 1.0, v74
	v_rcp_f32_e32 v68, v68
	v_rcp_f32_e32 v82, v82
	v_rcp_f32_e32 v70, v70
	v_rcp_f32_e32 v78, v78
	v_rcp_f32_e32 v72, v72
	v_rcp_f32_e32 v80, v80
	v_rcp_f32_e32 v66, v66
	v_rcp_f32_e32 v74, v74
	v_mul_f32_e32 v69, v69, v68
	v_mul_f32_e32 v82, v83, v82
	v_mul_f32_e32 v70, v71, v70
	v_mul_f32_e32 v71, v79, v78
	v_mul_f32_e32 v72, v73, v72
	v_mul_f32_e32 v73, v81, v80
	v_mul_f32_e32 v78, v67, v66
	v_mul_f32_e32 v74, v75, v74
	v_cvt_pk_bf16_f32 v66, v82, v70
	v_cvt_pk_bf16_f32 v67, v71, v72
	v_cvt_pk_bf16_f32 v68, v73, v78
	v_cvt_pk_bf16_f32 v69, v74, v69
	global_store_dwordx4 v[76:77], v[66:69], off
	s_nop 0
	s_nop 0
	v_mov_b32_e32 v67, v54
	v_mov_b32_e32 v54, v63
	v_mov_b32_e32 v63, v56
	v_mov_b32_e32 v56, v65
	v_mov_b32_e32 v65, v50
	v_mov_b32_e32 v50, v59
	v_mov_b32_e32 v59, v52
	v_mov_b32_e32 v52, v61
	v_mov_b32_e32 v66, v62
	v_mov_b32_e32 v62, v64
	v_mov_b32_e32 v64, v58
	v_mov_b32_e32 v58, v60
	v_add_u32_e32 v60, 0x80, v148
	v_mad_i64_i32 v[60:61], s[36:37], v60, s55, v[122:123]
	v_lshl_add_u64 v[60:61], v[60:61], 0, s[26:27]
	v_lshl_add_u64 v[60:61], v[60:61], 0, s[4:5]
	v_lshl_add_u64 v[60:61], v[60:61], 0, v[138:139]
	v_mov_b32_e32 v68, v188
	v_fmamk_f32 v68, v68, 0x3a800000, v157
	v_mul_f32_e32 v69, 0x4b800000, v68
	v_cmp_gt_f32_e32 vcc, s54, v68
	s_nop 1
	v_cndmask_b32_e32 v68, v68, v69, vcc
	v_rsq_f32_e32 v68, v68
	s_nop 0
	v_mul_f32_e32 v69, 0x45800000, v68
	v_cndmask_b32_e32 v68, v68, v69, vcc
	v_pk_mul_f32 v[52:53], v[52:53], v[68:69] op_sel_hi:[1,0]
	v_pk_mul_f32 v[66:67], v[66:67], v[68:69] op_sel_hi:[1,0]
	v_pk_mul_f32 v[54:55], v[54:55], v[68:69] op_sel_hi:[1,0]
	v_pk_mul_f32 v[62:63], v[62:63], v[68:69] op_sel_hi:[1,0]
	v_pk_mul_f32 v[56:57], v[56:57], v[68:69] op_sel_hi:[1,0]
	v_pk_mul_f32 v[64:65], v[64:65], v[68:69] op_sel_hi:[1,0]
	v_pk_mul_f32 v[50:51], v[50:51], v[68:69] op_sel_hi:[1,0]
	v_pk_mul_f32 v[58:59], v[58:59], v[68:69] op_sel_hi:[1,0]
	v_mul_f32_e32 v53, v52, v53
	v_mul_f32_e32 v52, 0xbfb8aa3b, v52
	v_mul_f32_e32 v67, v66, v67
	v_mul_f32_e32 v66, 0xbfb8aa3b, v66
	v_mul_f32_e32 v55, v54, v55
	v_mul_f32_e32 v54, 0xbfb8aa3b, v54
	v_mul_f32_e32 v63, v62, v63
	v_mul_f32_e32 v62, 0xbfb8aa3b, v62
	v_mul_f32_e32 v57, v56, v57
	v_mul_f32_e32 v56, 0xbfb8aa3b, v56
	v_mul_f32_e32 v65, v64, v65
	v_mul_f32_e32 v64, 0xbfb8aa3b, v64
	v_mul_f32_e32 v51, v50, v51
	v_mul_f32_e32 v50, 0xbfb8aa3b, v50
	v_mul_f32_e32 v59, v58, v59
	v_mul_f32_e32 v58, 0xbfb8aa3b, v58
	v_exp_f32_e32 v52, v52
	v_exp_f32_e32 v66, v66
	v_exp_f32_e32 v54, v54
	v_exp_f32_e32 v62, v62
	v_exp_f32_e32 v56, v56
	v_exp_f32_e32 v64, v64
	v_exp_f32_e32 v50, v50
	v_exp_f32_e32 v58, v58
	v_add_f32_e32 v52, 1.0, v52
	v_add_f32_e32 v66, 1.0, v66
	v_add_f32_e32 v54, 1.0, v54
	v_add_f32_e32 v62, 1.0, v62
	v_add_f32_e32 v56, 1.0, v56
	v_add_f32_e32 v64, 1.0, v64
	v_add_f32_e32 v50, 1.0, v50
	v_add_f32_e32 v58, 1.0, v58
	v_rcp_f32_e32 v52, v52
	v_rcp_f32_e32 v66, v66
	v_rcp_f32_e32 v54, v54
	v_rcp_f32_e32 v62, v62
	v_rcp_f32_e32 v56, v56
	v_rcp_f32_e32 v64, v64
	v_rcp_f32_e32 v50, v50
	v_rcp_f32_e32 v58, v58
	v_mul_f32_e32 v53, v53, v52
	v_mul_f32_e32 v66, v67, v66
	v_mul_f32_e32 v54, v55, v54
	v_mul_f32_e32 v55, v63, v62
	v_mul_f32_e32 v56, v57, v56
	v_mul_f32_e32 v57, v65, v64
	v_mul_f32_e32 v62, v51, v50
	v_mul_f32_e32 v58, v59, v58
	v_cvt_pk_bf16_f32 v50, v66, v54
	v_cvt_pk_bf16_f32 v51, v55, v56
	v_cvt_pk_bf16_f32 v52, v57, v62
	v_cvt_pk_bf16_f32 v53, v58, v53
	global_store_dwordx4 v[60:61], v[50:53], off
	s_nop 0
	s_nop 0
	v_mov_b32_e32 v51, v38
	v_mov_b32_e32 v38, v47
	v_mov_b32_e32 v47, v40
	v_mov_b32_e32 v40, v49
	v_mov_b32_e32 v49, v34
	v_mov_b32_e32 v34, v43
	v_mov_b32_e32 v43, v36
	v_mov_b32_e32 v36, v45
	v_mov_b32_e32 v50, v46
	v_mov_b32_e32 v46, v48
	v_mov_b32_e32 v48, v42
	v_mov_b32_e32 v42, v44
	v_add_u32_e32 v44, 0x90, v148
	v_mad_i64_i32 v[44:45], s[36:37], v44, s55, v[122:123]
	v_lshl_add_u64 v[44:45], v[44:45], 0, s[26:27]
	v_lshl_add_u64 v[44:45], v[44:45], 0, s[4:5]
	v_lshl_add_u64 v[44:45], v[44:45], 0, v[138:139]
	v_mov_b32_e32 v52, v189
	v_fmamk_f32 v52, v52, 0x3a800000, v157
	v_mul_f32_e32 v53, 0x4b800000, v52
	v_cmp_gt_f32_e32 vcc, s54, v52
	s_nop 1
	v_cndmask_b32_e32 v52, v52, v53, vcc
	v_rsq_f32_e32 v52, v52
	s_nop 0
	v_mul_f32_e32 v53, 0x45800000, v52
	v_cndmask_b32_e32 v52, v52, v53, vcc
	v_pk_mul_f32 v[36:37], v[36:37], v[52:53] op_sel_hi:[1,0]
	v_pk_mul_f32 v[50:51], v[50:51], v[52:53] op_sel_hi:[1,0]
	v_pk_mul_f32 v[38:39], v[38:39], v[52:53] op_sel_hi:[1,0]
	v_pk_mul_f32 v[46:47], v[46:47], v[52:53] op_sel_hi:[1,0]
	v_pk_mul_f32 v[40:41], v[40:41], v[52:53] op_sel_hi:[1,0]
	v_pk_mul_f32 v[48:49], v[48:49], v[52:53] op_sel_hi:[1,0]
	v_pk_mul_f32 v[34:35], v[34:35], v[52:53] op_sel_hi:[1,0]
	v_pk_mul_f32 v[42:43], v[42:43], v[52:53] op_sel_hi:[1,0]
	v_mul_f32_e32 v37, v36, v37
	v_mul_f32_e32 v36, 0xbfb8aa3b, v36
	v_mul_f32_e32 v51, v50, v51
	v_mul_f32_e32 v50, 0xbfb8aa3b, v50
; __device__ __forceinline__ unsigned pk(float lo, float hi) { return pg8::cvt_pk_bf16(lo, hi); }
;     __device__ __forceinline__ void operator()(const pg8::f32x4 (&acc)[2][2][4][2], const pg8::Unit& u, int wr, int wc, int fr, int fq) const {
;     ...
;                 const int row = row0 + ai * 128 + m * 16; const float rs = rsqrtf(ss[row] * (1.f / DM) + EPS);
;                 float y[8];
; #pragma unroll
;                 for (int n = 0; n < 2; ++n)
; #pragma unroll
;                     for (int i = 0; i < 4; ++i) { const float g = acc[ai][0][m][n][i] * rs, up = acc[ai][1][m][n][i] * rs; y[4 * n + i] = g * up * __builtin_amdgcn_rcpf(1.f + __expf(-g)); }
;                 u32x4 w; w.x = pk(y[0], y[1]); w.y = pk(y[2], y[3]); w.z = pk(y[4], y[5]); w.w = pk(y[6], y[7]);
;                 *(u32x4*)(act + (size_t)row * DFF + u.pn * 128 + wc * 32 + 8 * fq) = w;
	v_mul_f32_e32 v39, v38, v39
	v_mul_f32_e32 v38, 0xbfb8aa3b, v38
	v_mul_f32_e32 v47, v46, v47
	v_mul_f32_e32 v46, 0xbfb8aa3b, v46
	v_mul_f32_e32 v41, v40, v41
	v_mul_f32_e32 v40, 0xbfb8aa3b, v40
	v_mul_f32_e32 v49, v48, v49
	v_mul_f32_e32 v48, 0xbfb8aa3b, v48
	v_mul_f32_e32 v35, v34, v35
	v_mul_f32_e32 v34, 0xbfb8aa3b, v34
	v_mul_f32_e32 v43, v42, v43
	v_mul_f32_e32 v42, 0xbfb8aa3b, v42
	v_exp_f32_e32 v36, v36
	v_exp_f32_e32 v50, v50
	v_exp_f32_e32 v38, v38
	v_exp_f32_e32 v46, v46
	v_exp_f32_e32 v40, v40
	v_exp_f32_e32 v48, v48
	v_exp_f32_e32 v34, v34
	v_exp_f32_e32 v42, v42
	v_add_f32_e32 v36, 1.0, v36
	v_add_f32_e32 v50, 1.0, v50
	v_add_f32_e32 v38, 1.0, v38
	v_add_f32_e32 v46, 1.0, v46
	v_add_f32_e32 v40, 1.0, v40
	v_add_f32_e32 v48, 1.0, v48
	v_add_f32_e32 v34, 1.0, v34
	v_add_f32_e32 v42, 1.0, v42
	v_rcp_f32_e32 v36, v36
	v_rcp_f32_e32 v50, v50
	v_rcp_f32_e32 v38, v38
	v_rcp_f32_e32 v46, v46
	v_rcp_f32_e32 v40, v40
	v_rcp_f32_e32 v48, v48
	v_rcp_f32_e32 v34, v34
	v_rcp_f32_e32 v42, v42
	v_mul_f32_e32 v37, v37, v36
	v_mul_f32_e32 v50, v51, v50
	v_mul_f32_e32 v38, v39, v38
	v_mul_f32_e32 v39, v47, v46
	v_mul_f32_e32 v40, v41, v40
	v_mul_f32_e32 v41, v49, v48
	v_mul_f32_e32 v46, v35, v34
	v_mul_f32_e32 v42, v43, v42
	v_cvt_pk_bf16_f32 v34, v50, v38
	v_cvt_pk_bf16_f32 v35, v39, v40
	v_cvt_pk_bf16_f32 v36, v41, v46
	v_cvt_pk_bf16_f32 v37, v42, v37
	global_store_dwordx4 v[44:45], v[34:37], off
	s_nop 0
	s_nop 0
	v_mov_b32_e32 v35, v22
	v_mov_b32_e32 v22, v31
	v_mov_b32_e32 v31, v24
	v_mov_b32_e32 v24, v33
	v_mov_b32_e32 v33, v18
	v_mov_b32_e32 v18, v27
	v_mov_b32_e32 v27, v20
	v_mov_b32_e32 v20, v29
	v_mov_b32_e32 v34, v30
	v_mov_b32_e32 v30, v32
	v_mov_b32_e32 v32, v26
	v_mov_b32_e32 v26, v28
	v_add_u32_e32 v28, 0xa0, v148
	v_mad_i64_i32 v[28:29], s[36:37], v28, s55, v[122:123]
	v_lshl_add_u64 v[28:29], v[28:29], 0, s[26:27]
	v_lshl_add_u64 v[28:29], v[28:29], 0, s[4:5]
	v_lshl_add_u64 v[28:29], v[28:29], 0, v[138:139]
	v_mov_b32_e32 v36, v190
	v_fmamk_f32 v36, v36, 0x3a800000, v157
	v_mul_f32_e32 v37, 0x4b800000, v36
	v_cmp_gt_f32_e32 vcc, s54, v36
	s_nop 1
	v_cndmask_b32_e32 v36, v36, v37, vcc
	v_rsq_f32_e32 v36, v36
	s_nop 0
	v_mul_f32_e32 v37, 0x45800000, v36
	v_cndmask_b32_e32 v36, v36, v37, vcc
	v_pk_mul_f32 v[20:21], v[20:21], v[36:37] op_sel_hi:[1,0]
	v_pk_mul_f32 v[34:35], v[34:35], v[36:37] op_sel_hi:[1,0]
	v_pk_mul_f32 v[22:23], v[22:23], v[36:37] op_sel_hi:[1,0]
	v_pk_mul_f32 v[30:31], v[30:31], v[36:37] op_sel_hi:[1,0]
	v_pk_mul_f32 v[24:25], v[24:25], v[36:37] op_sel_hi:[1,0]
	v_pk_mul_f32 v[32:33], v[32:33], v[36:37] op_sel_hi:[1,0]
	v_pk_mul_f32 v[18:19], v[18:19], v[36:37] op_sel_hi:[1,0]
	v_pk_mul_f32 v[26:27], v[26:27], v[36:37] op_sel_hi:[1,0]
	v_mul_f32_e32 v21, v20, v21
	v_mul_f32_e32 v20, 0xbfb8aa3b, v20
	v_mul_f32_e32 v35, v34, v35
	v_mul_f32_e32 v34, 0xbfb8aa3b, v34
	v_mul_f32_e32 v23, v22, v23
	v_mul_f32_e32 v22, 0xbfb8aa3b, v22
	v_mul_f32_e32 v31, v30, v31
	v_mul_f32_e32 v30, 0xbfb8aa3b, v30
	v_mul_f32_e32 v25, v24, v25
	v_mul_f32_e32 v24, 0xbfb8aa3b, v24
	v_mul_f32_e32 v33, v32, v33
	v_mul_f32_e32 v32, 0xbfb8aa3b, v32
	v_mul_f32_e32 v19, v18, v19
	v_mul_f32_e32 v18, 0xbfb8aa3b, v18
	v_mul_f32_e32 v27, v26, v27
	v_mul_f32_e32 v26, 0xbfb8aa3b, v26
	v_exp_f32_e32 v20, v20
	v_exp_f32_e32 v34, v34
	v_exp_f32_e32 v22, v22
	v_exp_f32_e32 v30, v30
	v_exp_f32_e32 v24, v24
	v_exp_f32_e32 v32, v32
	v_exp_f32_e32 v18, v18
	v_exp_f32_e32 v26, v26
	v_add_f32_e32 v20, 1.0, v20
	v_add_f32_e32 v34, 1.0, v34
	v_add_f32_e32 v22, 1.0, v22
	v_add_f32_e32 v30, 1.0, v30
	v_add_f32_e32 v24, 1.0, v24
	v_add_f32_e32 v32, 1.0, v32
; __device__ __forceinline__ unsigned pk(float lo, float hi) { return pg8::cvt_pk_bf16(lo, hi); }
;     __device__ __forceinline__ void operator()(const pg8::f32x4 (&acc)[2][2][4][2], const pg8::Unit& u, int wr, int wc, int fr, int fq) const {
;     ...
;                 const int row = row0 + ai * 128 + m * 16; const float rs = rsqrtf(ss[row] * (1.f / DM) + EPS);
;                 float y[8];
; #pragma unroll
;                 for (int n = 0; n < 2; ++n)
; #pragma unroll
;                     for (int i = 0; i < 4; ++i) { const float g = acc[ai][0][m][n][i] * rs, up = acc[ai][1][m][n][i] * rs; y[4 * n + i] = g * up * __builtin_amdgcn_rcpf(1.f + __expf(-g)); }
;                 u32x4 w; w.x = pk(y[0], y[1]); w.y = pk(y[2], y[3]); w.z = pk(y[4], y[5]); w.w = pk(y[6], y[7]);
;                 *(u32x4*)(act + (size_t)row * DFF + u.pn * 128 + wc * 32 + 8 * fq) = w;
	v_add_f32_e32 v18, 1.0, v18
	v_add_f32_e32 v26, 1.0, v26
	v_rcp_f32_e32 v20, v20
	v_rcp_f32_e32 v34, v34
	v_rcp_f32_e32 v22, v22
	v_rcp_f32_e32 v30, v30
	v_rcp_f32_e32 v24, v24
	v_rcp_f32_e32 v32, v32
	v_rcp_f32_e32 v18, v18
	v_rcp_f32_e32 v26, v26
	v_mul_f32_e32 v21, v21, v20
	v_mul_f32_e32 v34, v35, v34
	v_mul_f32_e32 v22, v23, v22
	v_mul_f32_e32 v23, v31, v30
	v_mul_f32_e32 v24, v25, v24
	v_mul_f32_e32 v25, v33, v32
	v_mul_f32_e32 v30, v19, v18
	v_mul_f32_e32 v26, v27, v26
	v_cvt_pk_bf16_f32 v18, v34, v22
	v_cvt_pk_bf16_f32 v19, v23, v24
	v_cvt_pk_bf16_f32 v20, v25, v30
	v_cvt_pk_bf16_f32 v21, v26, v21
	global_store_dwordx4 v[28:29], v[18:21], off
	s_nop 0
	s_andn2_b64 vcc, exec, s[0:1]
	v_mov_b32_e32 v19, v6
	v_mov_b32_e32 v6, v15
	v_mov_b32_e32 v15, v8
	v_mov_b32_e32 v8, v17
	v_mov_b32_e32 v17, v2
	v_mov_b32_e32 v2, v11
	v_mov_b32_e32 v11, v4
	v_mov_b32_e32 v4, v13
	v_mov_b32_e32 v18, v14
	v_mov_b32_e32 v14, v16
	v_mov_b32_e32 v16, v10
	v_mov_b32_e32 v10, v12
	v_add_u32_e32 v12, 0xb0, v148
	v_mad_i64_i32 v[12:13], s[36:37], v12, s55, v[122:123]
	v_lshl_add_u64 v[12:13], v[12:13], 0, s[26:27]
	v_lshl_add_u64 v[12:13], v[12:13], 0, s[4:5]
	v_lshl_add_u64 v[12:13], v[12:13], 0, v[138:139]
	v_mov_b32_e32 v20, v191
	v_fmamk_f32 v20, v20, 0x3a800000, v157
	v_mul_f32_e32 v21, 0x4b800000, v20
	v_cmp_gt_f32_e64 s[0:1], s54, v20
	s_nop 1
	v_cndmask_b32_e64 v20, v20, v21, s[0:1]
	v_rsq_f32_e32 v20, v20
	s_nop 0
	v_mul_f32_e32 v21, 0x45800000, v20
	v_cndmask_b32_e64 v20, v20, v21, s[0:1]
	v_pk_mul_f32 v[4:5], v[4:5], v[20:21] op_sel_hi:[1,0]
	v_pk_mul_f32 v[18:19], v[18:19], v[20:21] op_sel_hi:[1,0]
	v_pk_mul_f32 v[6:7], v[6:7], v[20:21] op_sel_hi:[1,0]
	v_pk_mul_f32 v[14:15], v[14:15], v[20:21] op_sel_hi:[1,0]
	v_pk_mul_f32 v[8:9], v[8:9], v[20:21] op_sel_hi:[1,0]
	v_pk_mul_f32 v[16:17], v[16:17], v[20:21] op_sel_hi:[1,0]
	v_pk_mul_f32 v[2:3], v[2:3], v[20:21] op_sel_hi:[1,0]
	v_pk_mul_f32 v[10:11], v[10:11], v[20:21] op_sel_hi:[1,0]
	v_mul_f32_e32 v5, v4, v5
	v_mul_f32_e32 v4, 0xbfb8aa3b, v4
	v_mul_f32_e32 v19, v18, v19
	v_mul_f32_e32 v18, 0xbfb8aa3b, v18
	v_mul_f32_e32 v7, v6, v7
	v_mul_f32_e32 v6, 0xbfb8aa3b, v6
	v_mul_f32_e32 v15, v14, v15
	v_mul_f32_e32 v14, 0xbfb8aa3b, v14
	v_mul_f32_e32 v9, v8, v9
	v_mul_f32_e32 v8, 0xbfb8aa3b, v8
	v_mul_f32_e32 v17, v16, v17
	v_mul_f32_e32 v16, 0xbfb8aa3b, v16
	v_mul_f32_e32 v3, v2, v3
	v_mul_f32_e32 v2, 0xbfb8aa3b, v2
	v_mul_f32_e32 v11, v10, v11
	v_mul_f32_e32 v10, 0xbfb8aa3b, v10
	v_exp_f32_e32 v4, v4
	v_exp_f32_e32 v18, v18
	v_exp_f32_e32 v6, v6
	v_exp_f32_e32 v14, v14
	v_exp_f32_e32 v8, v8
	v_exp_f32_e32 v16, v16
	v_exp_f32_e32 v2, v2
	v_exp_f32_e32 v10, v10
	v_add_f32_e32 v4, 1.0, v4
	v_add_f32_e32 v18, 1.0, v18
	v_add_f32_e32 v6, 1.0, v6
	v_add_f32_e32 v14, 1.0, v14
	v_add_f32_e32 v8, 1.0, v8
	v_add_f32_e32 v16, 1.0, v16
	v_add_f32_e32 v2, 1.0, v2
	v_add_f32_e32 v10, 1.0, v10
	v_rcp_f32_e32 v4, v4
	v_rcp_f32_e32 v18, v18
	v_rcp_f32_e32 v6, v6
	v_rcp_f32_e32 v14, v14
	v_rcp_f32_e32 v8, v8
	v_rcp_f32_e32 v16, v16
	v_rcp_f32_e32 v2, v2
	v_rcp_f32_e32 v10, v10
	v_mul_f32_e32 v5, v5, v4
	s_mov_b64 s[0:1], -1
	v_mul_f32_e32 v18, v19, v18
	v_mul_f32_e32 v6, v7, v6
	v_mul_f32_e32 v7, v15, v14
	v_mul_f32_e32 v8, v9, v8
	v_mul_f32_e32 v9, v17, v16
	v_mul_f32_e32 v14, v3, v2
	v_mul_f32_e32 v10, v11, v10
	v_cvt_pk_bf16_f32 v2, v18, v6
	v_cvt_pk_bf16_f32 v3, v7, v8
	v_cvt_pk_bf16_f32 v4, v9, v14
	v_cvt_pk_bf16_f32 v5, v10, v5
	global_store_dwordx4 v[12:13], v[2:5], off
	s_cbranch_vccnz .LBB0_1931
	s_andn2_b64 vcc, exec, s[6:7]
	s_cbranch_vccnz .LBB0_1930
	s_barrier
	s_branch .LBB0_1930
